# v16 plus the two waits before each mainloop barrier merged into one s_waitcnt and the satisfied lgkmcnt wait after the barrier removed (40 sites)
# baseline (speedup 1.0000x reference)
.Lsp_skip0:
.LBB0_233:
	ds_read_b128 v[162:165], v155
	ds_read_b128 v[166:169], v155 offset:1024
	ds_read_b128 v[170:173], v155 offset:2048
	ds_read_b128 v[174:177], v155 offset:3072
	ds_read_b128 v[178:181], v158
	ds_read_b128 v[182:185], v158 offset:1024
	ds_read_b128 v[186:189], v158 offset:2048
	ds_read_b128 v[190:193], v158 offset:3072
	ds_read_b128 v[194:197], v159
	ds_read_b128 v[198:201], v159 offset:1024
	ds_read_b128 v[202:205], v159 offset:2048
	ds_read_b128 v[206:209], v159 offset:3072
	ds_read_b128 v[210:213], v159 offset:4096
	ds_read_b128 v[214:217], v159 offset:5120
	ds_read_b128 v[218:221], v159 offset:6144
	ds_read_b128 v[222:225], v159 offset:7168
	s_add_u32 s36, s34, 0xfff00080
	s_addc_u32 s37, s35, -1
	s_cmp_eq_u32 s68, 60
	s_cselect_b32 s39, s25, s37
	s_cselect_b32 s38, s64, s36
	s_cselect_b32 s37, s23, s67
	s_cselect_b32 s36, s65, s66
	v_lshl_add_u64 v[144:145], s[34:35], 0, v[138:139]
	s_add_i32 m0, s31, 0xc000
	s_nop 0
	global_load_lds_dwordx4 v[144:145], off
	v_lshl_add_u64 v[144:145], s[34:35], 0, v[136:137]
	s_add_i32 m0, s31, 0xe000
	s_nop 0
	global_load_lds_dwordx4 v[144:145], off
	s_waitcnt vmcnt(8) lgkmcnt(0)
	s_barrier
	v_mfma_f32_16x16x32_bf16 v[124:127], v[162:165], v[194:197], v[124:127]
	v_mfma_f32_16x16x32_bf16 v[120:123], v[170:173], v[194:197], v[120:123]
	v_mfma_f32_16x16x32_bf16 v[108:111], v[162:165], v[202:205], v[108:111]
	v_mfma_f32_16x16x32_bf16 v[104:107], v[170:173], v[202:205], v[104:107]
	v_mfma_f32_16x16x32_bf16 v[92:95], v[162:165], v[210:213], v[92:95]
	v_mfma_f32_16x16x32_bf16 v[88:91], v[170:173], v[210:213], v[88:91]
	v_mfma_f32_16x16x32_bf16 v[76:79], v[162:165], v[218:221], v[76:79]
	v_mfma_f32_16x16x32_bf16 v[72:75], v[170:173], v[218:221], v[72:75]
	v_mfma_f32_16x16x32_bf16 v[124:127], v[166:169], v[198:201], v[124:127]
	v_mfma_f32_16x16x32_bf16 v[120:123], v[174:177], v[198:201], v[120:123]
	v_mfma_f32_16x16x32_bf16 v[108:111], v[166:169], v[206:209], v[108:111]
	v_mfma_f32_16x16x32_bf16 v[104:107], v[174:177], v[206:209], v[104:107]
	v_mfma_f32_16x16x32_bf16 v[92:95], v[166:169], v[214:217], v[92:95]
	v_mfma_f32_16x16x32_bf16 v[88:91], v[174:177], v[214:217], v[88:91]
	v_mfma_f32_16x16x32_bf16 v[76:79], v[166:169], v[222:225], v[76:79]
	v_mfma_f32_16x16x32_bf16 v[72:75], v[174:177], v[222:225], v[72:75]
	v_mfma_f32_16x16x32_bf16 v[116:119], v[178:181], v[194:197], v[116:119]
	v_mfma_f32_16x16x32_bf16 v[112:115], v[186:189], v[194:197], v[112:115]
	v_mfma_f32_16x16x32_bf16 v[100:103], v[178:181], v[202:205], v[100:103]
	v_mfma_f32_16x16x32_bf16 v[96:99], v[186:189], v[202:205], v[96:99]
	v_mfma_f32_16x16x32_bf16 v[84:87], v[178:181], v[210:213], v[84:87]
	v_mfma_f32_16x16x32_bf16 v[80:83], v[186:189], v[210:213], v[80:83]
	v_mfma_f32_16x16x32_bf16 v[68:71], v[178:181], v[218:221], v[68:71]
	v_mfma_f32_16x16x32_bf16 v[64:67], v[186:189], v[218:221], v[64:67]
	v_mfma_f32_16x16x32_bf16 v[116:119], v[182:185], v[198:201], v[116:119]
	v_mfma_f32_16x16x32_bf16 v[112:115], v[190:193], v[198:201], v[112:115]
	v_mfma_f32_16x16x32_bf16 v[100:103], v[182:185], v[206:209], v[100:103]
	v_mfma_f32_16x16x32_bf16 v[96:99], v[190:193], v[206:209], v[96:99]
	v_mfma_f32_16x16x32_bf16 v[84:87], v[182:185], v[214:217], v[84:87]
	v_mfma_f32_16x16x32_bf16 v[80:83], v[190:193], v[214:217], v[80:83]
	v_mfma_f32_16x16x32_bf16 v[68:71], v[182:185], v[222:225], v[68:71]
	v_mfma_f32_16x16x32_bf16 v[64:67], v[190:193], v[222:225], v[64:67]
	s_barrier
	ds_read_b128 v[194:197], v159 offset:16384
	ds_read_b128 v[198:201], v159 offset:17408
	ds_read_b128 v[202:205], v159 offset:18432
	ds_read_b128 v[206:209], v159 offset:19456
	ds_read_b128 v[210:213], v159 offset:20480
	ds_read_b128 v[214:217], v159 offset:21504
	ds_read_b128 v[218:221], v159 offset:22528
	ds_read_b128 v[222:225], v159 offset:23552
	s_add_i32 s69, s57, s40
	v_lshl_add_u64 v[144:145], s[36:37], 0, v[130:131]
	s_mov_b32 m0, s69
	s_nop 0
	global_load_lds_dwordx4 v[144:145], off
	s_add_i32 m0, s69, 0x2000
	s_add_u32 s70, s36, 0x100000
	v_lshl_add_u64 v[150:151], s[36:37], 0, v[134:135]
	s_addc_u32 s71, s37, 0
	s_add_i32 s69, s58, s40
	global_load_lds_dwordx4 v[150:151], off
	v_lshl_add_u64 v[156:157], s[70:71], 0, v[130:131]
	s_mov_b32 m0, s69
	v_lshl_add_u64 v[226:227], s[38:39], 0, v[132:133]
	global_load_lds_dwordx4 v[156:157], off
	v_lshl_add_u64 v[156:157], s[70:71], 0, v[134:135]
	s_add_i32 m0, s69, 0x2000
	s_nop 0
	global_load_lds_dwordx4 v[156:157], off
	v_lshl_add_u64 v[156:157], s[38:39], 0, v[128:129]
	s_mov_b32 m0, s31
	s_nop 0
	global_load_lds_dwordx4 v[156:157], off
	s_mov_b32 m0, s50
	s_nop 0
	global_load_lds_dwordx4 v[226:227], off
	s_waitcnt vmcnt(8) lgkmcnt(0)
	s_barrier
	v_mfma_f32_16x16x32_bf16 v[60:63], v[162:165], v[194:197], v[60:63]
	v_mfma_f32_16x16x32_bf16 v[56:59], v[170:173], v[194:197], v[56:59]
	v_mfma_f32_16x16x32_bf16 v[48:51], v[162:165], v[202:205], v[48:51]
	v_mfma_f32_16x16x32_bf16 v[40:43], v[170:173], v[202:205], v[40:43]
	v_mfma_f32_16x16x32_bf16 v[32:35], v[162:165], v[210:213], v[32:35]
	v_mfma_f32_16x16x32_bf16 v[24:27], v[170:173], v[210:213], v[24:27]
	v_mfma_f32_16x16x32_bf16 v[16:19], v[162:165], v[218:221], v[16:19]
	v_mfma_f32_16x16x32_bf16 v[8:11], v[170:173], v[218:221], v[8:11]
	v_mfma_f32_16x16x32_bf16 v[60:63], v[166:169], v[198:201], v[60:63]
	v_mfma_f32_16x16x32_bf16 v[56:59], v[174:177], v[198:201], v[56:59]
	v_mfma_f32_16x16x32_bf16 v[48:51], v[166:169], v[206:209], v[48:51]
	v_mfma_f32_16x16x32_bf16 v[40:43], v[174:177], v[206:209], v[40:43]
	v_mfma_f32_16x16x32_bf16 v[32:35], v[166:169], v[214:217], v[32:35]
	v_mfma_f32_16x16x32_bf16 v[24:27], v[174:177], v[214:217], v[24:27]
	v_mfma_f32_16x16x32_bf16 v[16:19], v[166:169], v[222:225], v[16:19]
	v_mfma_f32_16x16x32_bf16 v[8:11], v[174:177], v[222:225], v[8:11]
	v_mfma_f32_16x16x32_bf16 v[52:55], v[178:181], v[194:197], v[52:55]
	v_mfma_f32_16x16x32_bf16 v[44:47], v[186:189], v[194:197], v[44:47]
	v_mfma_f32_16x16x32_bf16 v[36:39], v[178:181], v[202:205], v[36:39]
	v_mfma_f32_16x16x32_bf16 v[28:31], v[186:189], v[202:205], v[28:31]
	v_mfma_f32_16x16x32_bf16 v[20:23], v[178:181], v[210:213], v[20:23]
	v_mfma_f32_16x16x32_bf16 v[12:15], v[186:189], v[210:213], v[12:15]
	v_mfma_f32_16x16x32_bf16 v[4:7], v[178:181], v[218:221], v[4:7]
	v_mfma_f32_16x16x32_bf16 v[0:3], v[186:189], v[218:221], v[0:3]
	v_mfma_f32_16x16x32_bf16 v[52:55], v[182:185], v[198:201], v[52:55]
	v_mfma_f32_16x16x32_bf16 v[44:47], v[190:193], v[198:201], v[44:47]
	v_mfma_f32_16x16x32_bf16 v[36:39], v[182:185], v[206:209], v[36:39]
	v_mfma_f32_16x16x32_bf16 v[28:31], v[190:193], v[206:209], v[28:31]
	v_mfma_f32_16x16x32_bf16 v[20:23], v[182:185], v[214:217], v[20:23]
	v_mfma_f32_16x16x32_bf16 v[12:15], v[190:193], v[214:217], v[12:15]
	v_mfma_f32_16x16x32_bf16 v[4:7], v[182:185], v[222:225], v[4:7]
	v_mfma_f32_16x16x32_bf16 v[0:3], v[190:193], v[222:225], v[0:3]
	s_barrier
	ds_read_b128 v[194:197], v159 offset:32768
	ds_read_b128 v[198:201], v159 offset:33792
	ds_read_b128 v[202:205], v159 offset:34816
	ds_read_b128 v[206:209], v159 offset:35840
	ds_read_b128 v[210:213], v159 offset:36864
	ds_read_b128 v[214:217], v159 offset:37888
	ds_read_b128 v[218:221], v159 offset:38912
	ds_read_b128 v[222:225], v159 offset:39936
	s_add_i32 s69, 0, 0x18000
	v_add_u32_e32 v146, s69, v149
	s_add_i32 s70, 0, 0x1c000
	ds_read_b128 v[162:165], v146
	ds_read_b128 v[166:169], v146 offset:1024
	ds_read_b128 v[170:173], v146 offset:2048
	ds_read_b128 v[174:177], v146 offset:3072
	v_add_u32_e32 v146, s70, v149
	ds_read_b128 v[178:181], v146
	ds_read_b128 v[182:185], v146 offset:1024
	ds_read_b128 v[186:189], v146 offset:2048
	ds_read_b128 v[190:193], v146 offset:3072
	s_add_u32 s38, s38, 0x100000
	s_addc_u32 s39, s39, 0
	s_mov_b32 m0, s51
	v_lshl_add_u64 v[228:229], s[38:39], 0, v[128:129]
	global_load_lds_dwordx4 v[228:229], off
	v_lshl_add_u64 v[228:229], s[38:39], 0, v[132:133]
	s_mov_b32 m0, s52
	s_nop 0
	global_load_lds_dwordx4 v[228:229], off
	s_waitcnt vmcnt(8) lgkmcnt(0)
	s_barrier
	v_mfma_f32_16x16x32_bf16 v[124:127], v[162:165], v[194:197], v[124:127]
	v_mfma_f32_16x16x32_bf16 v[120:123], v[170:173], v[194:197], v[120:123]
	v_mfma_f32_16x16x32_bf16 v[108:111], v[162:165], v[202:205], v[108:111]
	v_mfma_f32_16x16x32_bf16 v[104:107], v[170:173], v[202:205], v[104:107]
	v_mfma_f32_16x16x32_bf16 v[92:95], v[162:165], v[210:213], v[92:95]
	v_mfma_f32_16x16x32_bf16 v[88:91], v[170:173], v[210:213], v[88:91]
	v_mfma_f32_16x16x32_bf16 v[76:79], v[162:165], v[218:221], v[76:79]
	v_mfma_f32_16x16x32_bf16 v[72:75], v[170:173], v[218:221], v[72:75]
	v_mfma_f32_16x16x32_bf16 v[124:127], v[166:169], v[198:201], v[124:127]
	v_mfma_f32_16x16x32_bf16 v[120:123], v[174:177], v[198:201], v[120:123]
	v_mfma_f32_16x16x32_bf16 v[108:111], v[166:169], v[206:209], v[108:111]
	v_mfma_f32_16x16x32_bf16 v[104:107], v[174:177], v[206:209], v[104:107]
	v_mfma_f32_16x16x32_bf16 v[92:95], v[166:169], v[214:217], v[92:95]
	v_mfma_f32_16x16x32_bf16 v[88:91], v[174:177], v[214:217], v[88:91]
	v_mfma_f32_16x16x32_bf16 v[76:79], v[166:169], v[222:225], v[76:79]
	v_mfma_f32_16x16x32_bf16 v[72:75], v[174:177], v[222:225], v[72:75]
	v_mfma_f32_16x16x32_bf16 v[116:119], v[178:181], v[194:197], v[116:119]
	v_mfma_f32_16x16x32_bf16 v[112:115], v[186:189], v[194:197], v[112:115]
	v_mfma_f32_16x16x32_bf16 v[100:103], v[178:181], v[202:205], v[100:103]
	v_mfma_f32_16x16x32_bf16 v[96:99], v[186:189], v[202:205], v[96:99]
	v_mfma_f32_16x16x32_bf16 v[84:87], v[178:181], v[210:213], v[84:87]
	v_mfma_f32_16x16x32_bf16 v[80:83], v[186:189], v[210:213], v[80:83]
	v_mfma_f32_16x16x32_bf16 v[68:71], v[178:181], v[218:221], v[68:71]
	v_mfma_f32_16x16x32_bf16 v[64:67], v[186:189], v[218:221], v[64:67]
	v_mfma_f32_16x16x32_bf16 v[116:119], v[182:185], v[198:201], v[116:119]
	v_mfma_f32_16x16x32_bf16 v[112:115], v[190:193], v[198:201], v[112:115]
	v_mfma_f32_16x16x32_bf16 v[100:103], v[182:185], v[206:209], v[100:103]
	v_mfma_f32_16x16x32_bf16 v[96:99], v[190:193], v[206:209], v[96:99]
	v_mfma_f32_16x16x32_bf16 v[84:87], v[182:185], v[214:217], v[84:87]
	v_mfma_f32_16x16x32_bf16 v[80:83], v[190:193], v[214:217], v[80:83]
	v_mfma_f32_16x16x32_bf16 v[68:71], v[182:185], v[222:225], v[68:71]
	v_mfma_f32_16x16x32_bf16 v[64:67], v[190:193], v[222:225], v[64:67]
	s_barrier
	ds_read_b128 v[194:197], v159 offset:49152
	ds_read_b128 v[198:201], v159 offset:50176
	ds_read_b128 v[202:205], v159 offset:51200
	ds_read_b128 v[206:209], v159 offset:52224
	ds_read_b128 v[210:213], v159 offset:53248
	ds_read_b128 v[214:217], v159 offset:54272
	ds_read_b128 v[218:221], v159 offset:55296
	ds_read_b128 v[222:225], v159 offset:56320
	s_add_i32 s38, s69, s40
	v_lshl_add_u64 v[144:145], v[144:145], 0, s[12:13]
	s_mov_b32 m0, s38
	s_nop 0
	global_load_lds_dwordx4 v[144:145], off
	s_add_i32 m0, s38, 0x2000
	s_add_u32 s36, s36, 0x100080
	v_lshl_add_u64 v[144:145], v[150:151], 0, s[12:13]
	s_addc_u32 s37, s37, 0
	s_add_i32 s38, s70, s40
	global_load_lds_dwordx4 v[144:145], off
	v_lshl_add_u64 v[144:145], s[36:37], 0, v[130:131]
	s_mov_b32 m0, s38
	s_nop 0
	global_load_lds_dwordx4 v[144:145], off
	v_lshl_add_u64 v[144:145], s[36:37], 0, v[134:135]
	s_add_i32 m0, s38, 0x2000
	s_nop 0
	global_load_lds_dwordx4 v[144:145], off
	v_lshl_add_u64 v[144:145], v[156:157], 0, s[12:13]
	s_mov_b32 m0, s54
	s_nop 0
	global_load_lds_dwordx4 v[144:145], off
	v_lshl_add_u64 v[144:145], v[226:227], 0, s[12:13]
	s_mov_b32 m0, s55
	s_nop 0
	global_load_lds_dwordx4 v[144:145], off
	s_waitcnt vmcnt(8) lgkmcnt(0)
	s_barrier
	v_mfma_f32_16x16x32_bf16 v[60:63], v[162:165], v[194:197], v[60:63]
	v_mfma_f32_16x16x32_bf16 v[56:59], v[170:173], v[194:197], v[56:59]
	v_mfma_f32_16x16x32_bf16 v[48:51], v[162:165], v[202:205], v[48:51]
	v_mfma_f32_16x16x32_bf16 v[40:43], v[170:173], v[202:205], v[40:43]
	v_mfma_f32_16x16x32_bf16 v[32:35], v[162:165], v[210:213], v[32:35]
	v_mfma_f32_16x16x32_bf16 v[24:27], v[170:173], v[210:213], v[24:27]
	v_mfma_f32_16x16x32_bf16 v[16:19], v[162:165], v[218:221], v[16:19]
	v_mfma_f32_16x16x32_bf16 v[8:11], v[170:173], v[218:221], v[8:11]
	v_mfma_f32_16x16x32_bf16 v[60:63], v[166:169], v[198:201], v[60:63]
	v_mfma_f32_16x16x32_bf16 v[56:59], v[174:177], v[198:201], v[56:59]
	v_mfma_f32_16x16x32_bf16 v[48:51], v[166:169], v[206:209], v[48:51]
	v_mfma_f32_16x16x32_bf16 v[40:43], v[174:177], v[206:209], v[40:43]
	v_mfma_f32_16x16x32_bf16 v[32:35], v[166:169], v[214:217], v[32:35]
	v_mfma_f32_16x16x32_bf16 v[24:27], v[174:177], v[214:217], v[24:27]
	v_mfma_f32_16x16x32_bf16 v[16:19], v[166:169], v[222:225], v[16:19]
	v_mfma_f32_16x16x32_bf16 v[8:11], v[174:177], v[222:225], v[8:11]
	v_mfma_f32_16x16x32_bf16 v[52:55], v[178:181], v[194:197], v[52:55]
	v_mfma_f32_16x16x32_bf16 v[44:47], v[186:189], v[194:197], v[44:47]
	v_mfma_f32_16x16x32_bf16 v[36:39], v[178:181], v[202:205], v[36:39]
	v_mfma_f32_16x16x32_bf16 v[28:31], v[186:189], v[202:205], v[28:31]
	v_mfma_f32_16x16x32_bf16 v[20:23], v[178:181], v[210:213], v[20:23]
	v_mfma_f32_16x16x32_bf16 v[12:15], v[186:189], v[210:213], v[12:15]
	v_mfma_f32_16x16x32_bf16 v[4:7], v[178:181], v[218:221], v[4:7]
	v_mfma_f32_16x16x32_bf16 v[0:3], v[186:189], v[218:221], v[0:3]
	v_mfma_f32_16x16x32_bf16 v[52:55], v[182:185], v[198:201], v[52:55]
	v_mfma_f32_16x16x32_bf16 v[44:47], v[190:193], v[198:201], v[44:47]
	v_mfma_f32_16x16x32_bf16 v[36:39], v[182:185], v[206:209], v[36:39]
	v_mfma_f32_16x16x32_bf16 v[28:31], v[190:193], v[206:209], v[28:31]
	v_mfma_f32_16x16x32_bf16 v[20:23], v[182:185], v[214:217], v[20:23]
	v_mfma_f32_16x16x32_bf16 v[12:15], v[190:193], v[214:217], v[12:15]
	v_mfma_f32_16x16x32_bf16 v[4:7], v[182:185], v[222:225], v[4:7]
	v_mfma_f32_16x16x32_bf16 v[0:3], v[190:193], v[222:225], v[0:3]
	s_barrier
	s_add_i32 s68, s68, 2
	s_add_u32 s66, s66, 0x100
	s_addc_u32 s67, s67, 0
	s_add_u32 s34, s34, 0x100
	s_addc_u32 s35, s35, 0
	s_cmp_gt_u32 s68, 61
	s_cbranch_scc0 .LBB0_233
	s_setprio 0
	s_and_b64 vcc, exec, s[14:15]
	s_cbranch_vccz .LBB0_236
	s_barrier

.Lsp_skip1:
.LBB0_254:
	ds_read_b128 v[152:155], v149
	ds_read_b128 v[156:159], v149 offset:1024
	ds_read_b128 v[160:163], v149 offset:2048
	ds_read_b128 v[164:167], v149 offset:3072
	ds_read_b128 v[168:171], v150
	ds_read_b128 v[172:175], v150 offset:1024
	ds_read_b128 v[176:179], v150 offset:2048
	ds_read_b128 v[180:183], v150 offset:3072
	ds_read_b128 v[184:187], v151
	ds_read_b128 v[188:191], v151 offset:1024
	ds_read_b128 v[192:195], v151 offset:2048
	ds_read_b128 v[196:199], v151 offset:3072
	ds_read_b128 v[200:203], v151 offset:4096
	ds_read_b128 v[204:207], v151 offset:5120
	ds_read_b128 v[208:211], v151 offset:6144
	ds_read_b128 v[212:215], v151 offset:7168
	s_add_u32 s26, s24, 0x100
	s_addc_u32 s27, s25, 0
	s_cmp_eq_u32 s67, 8
	s_cselect_b32 s31, s1, s27
	s_cselect_b32 s30, s0, s26
	s_cselect_b32 s29, s23, s66
	s_cselect_b32 s28, s22, s65
	v_lshl_add_u64 v[144:145], s[24:25], 0, v[138:139]
	s_add_i32 m0, s46, 0xc000
	s_nop 0
	global_load_lds_dwordx4 v[144:145], off
	v_lshl_add_u64 v[144:145], s[24:25], 0, v[136:137]
	s_add_i32 m0, s46, 0xe000
	s_nop 0
	global_load_lds_dwordx4 v[144:145], off
	s_waitcnt vmcnt(8) lgkmcnt(0)
	s_barrier
	v_mfma_f32_16x16x32_bf16 v[124:127], v[152:155], v[184:187], v[124:127]
	v_mfma_f32_16x16x32_bf16 v[120:123], v[160:163], v[184:187], v[120:123]
	v_mfma_f32_16x16x32_bf16 v[116:119], v[152:155], v[192:195], v[116:119]
	v_mfma_f32_16x16x32_bf16 v[108:111], v[160:163], v[192:195], v[108:111]
	v_mfma_f32_16x16x32_bf16 v[100:103], v[152:155], v[200:203], v[100:103]
	v_mfma_f32_16x16x32_bf16 v[92:95], v[160:163], v[200:203], v[92:95]
	v_mfma_f32_16x16x32_bf16 v[84:87], v[152:155], v[208:211], v[84:87]
	v_mfma_f32_16x16x32_bf16 v[76:79], v[160:163], v[208:211], v[76:79]
	v_mfma_f32_16x16x32_bf16 v[124:127], v[156:159], v[188:191], v[124:127]
	v_mfma_f32_16x16x32_bf16 v[120:123], v[164:167], v[188:191], v[120:123]
	v_mfma_f32_16x16x32_bf16 v[116:119], v[156:159], v[196:199], v[116:119]
	v_mfma_f32_16x16x32_bf16 v[108:111], v[164:167], v[196:199], v[108:111]
	v_mfma_f32_16x16x32_bf16 v[100:103], v[156:159], v[204:207], v[100:103]
	v_mfma_f32_16x16x32_bf16 v[92:95], v[164:167], v[204:207], v[92:95]
	v_mfma_f32_16x16x32_bf16 v[84:87], v[156:159], v[212:215], v[84:87]
	v_mfma_f32_16x16x32_bf16 v[76:79], v[164:167], v[212:215], v[76:79]
	v_mfma_f32_16x16x32_bf16 v[112:115], v[168:171], v[184:187], v[112:115]
	v_mfma_f32_16x16x32_bf16 v[104:107], v[176:179], v[184:187], v[104:107]
	v_mfma_f32_16x16x32_bf16 v[96:99], v[168:171], v[192:195], v[96:99]
	v_mfma_f32_16x16x32_bf16 v[88:91], v[176:179], v[192:195], v[88:91]
	v_mfma_f32_16x16x32_bf16 v[80:83], v[168:171], v[200:203], v[80:83]
	v_mfma_f32_16x16x32_bf16 v[72:75], v[176:179], v[200:203], v[72:75]
	v_mfma_f32_16x16x32_bf16 v[68:71], v[168:171], v[208:211], v[68:71]
	v_mfma_f32_16x16x32_bf16 v[64:67], v[176:179], v[208:211], v[64:67]
	v_mfma_f32_16x16x32_bf16 v[112:115], v[172:175], v[188:191], v[112:115]
	v_mfma_f32_16x16x32_bf16 v[104:107], v[180:183], v[188:191], v[104:107]
	v_mfma_f32_16x16x32_bf16 v[96:99], v[172:175], v[196:199], v[96:99]
	v_mfma_f32_16x16x32_bf16 v[88:91], v[180:183], v[196:199], v[88:91]
	v_mfma_f32_16x16x32_bf16 v[80:83], v[172:175], v[204:207], v[80:83]
	v_mfma_f32_16x16x32_bf16 v[72:75], v[180:183], v[204:207], v[72:75]
	v_mfma_f32_16x16x32_bf16 v[68:71], v[172:175], v[212:215], v[68:71]
	v_mfma_f32_16x16x32_bf16 v[64:67], v[180:183], v[212:215], v[64:67]
	s_barrier
	ds_read_b128 v[184:187], v151 offset:16384
	ds_read_b128 v[188:191], v151 offset:17408
	ds_read_b128 v[192:195], v151 offset:18432
	ds_read_b128 v[196:199], v151 offset:19456
	ds_read_b128 v[200:203], v151 offset:20480
	ds_read_b128 v[204:207], v151 offset:21504
	ds_read_b128 v[208:211], v151 offset:22528
	ds_read_b128 v[212:215], v151 offset:23552
	s_add_i32 s24, s55, s40
	v_lshl_add_u64 v[144:145], s[28:29], 0, v[132:133]
	s_mov_b32 m0, s24
	s_nop 0
	global_load_lds_dwordx4 v[144:145], off
	s_add_i32 m0, s24, 0x2000
	s_add_u32 s24, s28, 0x30000
	v_lshl_add_u64 v[216:217], s[28:29], 0, v[128:129]
	s_addc_u32 s25, s29, 0
	s_add_i32 s68, s56, s40
	global_load_lds_dwordx4 v[216:217], off
	v_lshl_add_u64 v[218:219], s[24:25], 0, v[132:133]
	s_mov_b32 m0, s68
	v_lshl_add_u64 v[220:221], s[30:31], 0, v[130:131]
	global_load_lds_dwordx4 v[218:219], off
	v_lshl_add_u64 v[218:219], s[24:25], 0, v[128:129]
	s_add_i32 m0, s68, 0x2000
	s_nop 0
	global_load_lds_dwordx4 v[218:219], off
	v_lshl_add_u64 v[218:219], s[30:31], 0, v[134:135]
	s_mov_b32 m0, s46
	s_nop 0
	global_load_lds_dwordx4 v[218:219], off
	s_mov_b32 m0, s47
	s_nop 0
	global_load_lds_dwordx4 v[220:221], off
	s_waitcnt vmcnt(8) lgkmcnt(0)
	s_barrier
	v_mfma_f32_16x16x32_bf16 v[60:63], v[152:155], v[184:187], v[60:63]
	v_mfma_f32_16x16x32_bf16 v[56:59], v[160:163], v[184:187], v[56:59]
	v_mfma_f32_16x16x32_bf16 v[52:55], v[152:155], v[192:195], v[52:55]
	v_mfma_f32_16x16x32_bf16 v[44:47], v[160:163], v[192:195], v[44:47]
	v_mfma_f32_16x16x32_bf16 v[36:39], v[152:155], v[200:203], v[36:39]
	v_mfma_f32_16x16x32_bf16 v[28:31], v[160:163], v[200:203], v[28:31]
	v_mfma_f32_16x16x32_bf16 v[20:23], v[152:155], v[208:211], v[20:23]
	v_mfma_f32_16x16x32_bf16 v[12:15], v[160:163], v[208:211], v[12:15]
	v_mfma_f32_16x16x32_bf16 v[60:63], v[156:159], v[188:191], v[60:63]
	v_mfma_f32_16x16x32_bf16 v[56:59], v[164:167], v[188:191], v[56:59]
	v_mfma_f32_16x16x32_bf16 v[52:55], v[156:159], v[196:199], v[52:55]
	v_mfma_f32_16x16x32_bf16 v[44:47], v[164:167], v[196:199], v[44:47]
	v_mfma_f32_16x16x32_bf16 v[36:39], v[156:159], v[204:207], v[36:39]
	v_mfma_f32_16x16x32_bf16 v[28:31], v[164:167], v[204:207], v[28:31]
	v_mfma_f32_16x16x32_bf16 v[20:23], v[156:159], v[212:215], v[20:23]
	v_mfma_f32_16x16x32_bf16 v[12:15], v[164:167], v[212:215], v[12:15]
	v_mfma_f32_16x16x32_bf16 v[48:51], v[168:171], v[184:187], v[48:51]
	v_mfma_f32_16x16x32_bf16 v[40:43], v[176:179], v[184:187], v[40:43]
	v_mfma_f32_16x16x32_bf16 v[32:35], v[168:171], v[192:195], v[32:35]
	v_mfma_f32_16x16x32_bf16 v[24:27], v[176:179], v[192:195], v[24:27]
	v_mfma_f32_16x16x32_bf16 v[16:19], v[168:171], v[200:203], v[16:19]
	v_mfma_f32_16x16x32_bf16 v[8:11], v[176:179], v[200:203], v[8:11]
	v_mfma_f32_16x16x32_bf16 v[4:7], v[168:171], v[208:211], v[4:7]
	v_mfma_f32_16x16x32_bf16 v[0:3], v[176:179], v[208:211], v[0:3]
	v_mfma_f32_16x16x32_bf16 v[48:51], v[172:175], v[188:191], v[48:51]
	v_mfma_f32_16x16x32_bf16 v[40:43], v[180:183], v[188:191], v[40:43]
	v_mfma_f32_16x16x32_bf16 v[32:35], v[172:175], v[196:199], v[32:35]
	v_mfma_f32_16x16x32_bf16 v[24:27], v[180:183], v[196:199], v[24:27]
	v_mfma_f32_16x16x32_bf16 v[16:19], v[172:175], v[204:207], v[16:19]
	v_mfma_f32_16x16x32_bf16 v[8:11], v[180:183], v[204:207], v[8:11]
	v_mfma_f32_16x16x32_bf16 v[4:7], v[172:175], v[212:215], v[4:7]
	v_mfma_f32_16x16x32_bf16 v[0:3], v[180:183], v[212:215], v[0:3]
	s_barrier
	ds_read_b128 v[184:187], v151 offset:32768
	ds_read_b128 v[188:191], v151 offset:33792
	ds_read_b128 v[192:195], v151 offset:34816
	ds_read_b128 v[196:199], v151 offset:35840
	ds_read_b128 v[200:203], v151 offset:36864
	ds_read_b128 v[204:207], v151 offset:37888
	ds_read_b128 v[208:211], v151 offset:38912
	ds_read_b128 v[212:215], v151 offset:39936
	s_add_i32 s68, 0, 0x18000
	s_add_i32 s69, 0, 0x1c000
	v_add_u32_e32 v164, s68, v147
	v_add_u32_e32 v180, s69, v147
	ds_read_b128 v[152:155], v164
	ds_read_b128 v[156:159], v164 offset:1024
	ds_read_b128 v[160:163], v164 offset:2048
	ds_read_b128 v[164:167], v164 offset:3072
	ds_read_b128 v[168:171], v180
	ds_read_b128 v[172:175], v180 offset:1024
	ds_read_b128 v[176:179], v180 offset:2048
	ds_read_b128 v[180:183], v180 offset:3072
	s_add_u32 s24, s30, 0xc0000
	s_addc_u32 s25, s31, 0
	s_mov_b32 m0, s48
	v_lshl_add_u64 v[222:223], s[24:25], 0, v[134:135]
	global_load_lds_dwordx4 v[222:223], off
	v_lshl_add_u64 v[222:223], s[24:25], 0, v[130:131]
	s_mov_b32 m0, s49
	s_nop 0
	global_load_lds_dwordx4 v[222:223], off
	s_waitcnt vmcnt(8) lgkmcnt(0)
	s_barrier
	v_mfma_f32_16x16x32_bf16 v[124:127], v[152:155], v[184:187], v[124:127]
	v_mfma_f32_16x16x32_bf16 v[120:123], v[160:163], v[184:187], v[120:123]
	v_mfma_f32_16x16x32_bf16 v[116:119], v[152:155], v[192:195], v[116:119]
	v_mfma_f32_16x16x32_bf16 v[108:111], v[160:163], v[192:195], v[108:111]
	v_mfma_f32_16x16x32_bf16 v[100:103], v[152:155], v[200:203], v[100:103]
	v_mfma_f32_16x16x32_bf16 v[92:95], v[160:163], v[200:203], v[92:95]
	v_mfma_f32_16x16x32_bf16 v[84:87], v[152:155], v[208:211], v[84:87]
	v_mfma_f32_16x16x32_bf16 v[76:79], v[160:163], v[208:211], v[76:79]
	v_mfma_f32_16x16x32_bf16 v[124:127], v[156:159], v[188:191], v[124:127]
	v_mfma_f32_16x16x32_bf16 v[120:123], v[164:167], v[188:191], v[120:123]
	v_mfma_f32_16x16x32_bf16 v[116:119], v[156:159], v[196:199], v[116:119]
	v_mfma_f32_16x16x32_bf16 v[108:111], v[164:167], v[196:199], v[108:111]
	v_mfma_f32_16x16x32_bf16 v[100:103], v[156:159], v[204:207], v[100:103]
	v_mfma_f32_16x16x32_bf16 v[92:95], v[164:167], v[204:207], v[92:95]
	v_mfma_f32_16x16x32_bf16 v[84:87], v[156:159], v[212:215], v[84:87]
	v_mfma_f32_16x16x32_bf16 v[76:79], v[164:167], v[212:215], v[76:79]
	v_mfma_f32_16x16x32_bf16 v[112:115], v[168:171], v[184:187], v[112:115]
	v_mfma_f32_16x16x32_bf16 v[104:107], v[176:179], v[184:187], v[104:107]
	v_mfma_f32_16x16x32_bf16 v[96:99], v[168:171], v[192:195], v[96:99]
	v_mfma_f32_16x16x32_bf16 v[88:91], v[176:179], v[192:195], v[88:91]
	v_mfma_f32_16x16x32_bf16 v[80:83], v[168:171], v[200:203], v[80:83]
	v_mfma_f32_16x16x32_bf16 v[72:75], v[176:179], v[200:203], v[72:75]
	v_mfma_f32_16x16x32_bf16 v[68:71], v[168:171], v[208:211], v[68:71]
	v_mfma_f32_16x16x32_bf16 v[64:67], v[176:179], v[208:211], v[64:67]
	v_mfma_f32_16x16x32_bf16 v[112:115], v[172:175], v[188:191], v[112:115]
	v_mfma_f32_16x16x32_bf16 v[104:107], v[180:183], v[188:191], v[104:107]
	v_mfma_f32_16x16x32_bf16 v[96:99], v[172:175], v[196:199], v[96:99]
	v_mfma_f32_16x16x32_bf16 v[88:91], v[180:183], v[196:199], v[88:91]
	v_mfma_f32_16x16x32_bf16 v[80:83], v[172:175], v[204:207], v[80:83]
	v_mfma_f32_16x16x32_bf16 v[72:75], v[180:183], v[204:207], v[72:75]
	v_mfma_f32_16x16x32_bf16 v[68:71], v[172:175], v[212:215], v[68:71]
	v_mfma_f32_16x16x32_bf16 v[64:67], v[180:183], v[212:215], v[64:67]
	s_barrier
	ds_read_b128 v[184:187], v151 offset:49152
	ds_read_b128 v[188:191], v151 offset:50176
	ds_read_b128 v[192:195], v151 offset:51200
	ds_read_b128 v[196:199], v151 offset:52224
	ds_read_b128 v[200:203], v151 offset:53248
	ds_read_b128 v[204:207], v151 offset:54272
	ds_read_b128 v[208:211], v151 offset:55296
	ds_read_b128 v[212:215], v151 offset:56320
	s_add_i32 s24, s68, s40
	v_lshl_add_u64 v[144:145], v[144:145], 0, s[10:11]
	s_mov_b32 m0, s24
	s_nop 0
	global_load_lds_dwordx4 v[144:145], off
	s_add_i32 m0, s24, 0x2000
	s_add_u32 s24, s28, 0x30080
	v_lshl_add_u64 v[144:145], v[216:217], 0, s[10:11]
	s_addc_u32 s25, s29, 0
	s_add_i32 s28, s69, s40
	global_load_lds_dwordx4 v[144:145], off
	v_lshl_add_u64 v[144:145], s[24:25], 0, v[132:133]
	s_mov_b32 m0, s28
	s_nop 0
	global_load_lds_dwordx4 v[144:145], off
	v_lshl_add_u64 v[144:145], s[24:25], 0, v[128:129]
	s_add_i32 m0, s28, 0x2000
	s_nop 0
	global_load_lds_dwordx4 v[144:145], off
	v_lshl_add_u64 v[144:145], v[218:219], 0, s[10:11]
	s_mov_b32 m0, s52
	s_nop 0
	global_load_lds_dwordx4 v[144:145], off
	v_lshl_add_u64 v[144:145], v[220:221], 0, s[10:11]
	s_mov_b32 m0, s53
	s_nop 0
	global_load_lds_dwordx4 v[144:145], off
	s_waitcnt vmcnt(8) lgkmcnt(0)
	s_barrier
	v_mfma_f32_16x16x32_bf16 v[60:63], v[152:155], v[184:187], v[60:63]
	v_mfma_f32_16x16x32_bf16 v[56:59], v[160:163], v[184:187], v[56:59]
	v_mfma_f32_16x16x32_bf16 v[52:55], v[152:155], v[192:195], v[52:55]
	v_mfma_f32_16x16x32_bf16 v[44:47], v[160:163], v[192:195], v[44:47]
	v_mfma_f32_16x16x32_bf16 v[36:39], v[152:155], v[200:203], v[36:39]
	v_mfma_f32_16x16x32_bf16 v[28:31], v[160:163], v[200:203], v[28:31]
	v_mfma_f32_16x16x32_bf16 v[20:23], v[152:155], v[208:211], v[20:23]
	v_mfma_f32_16x16x32_bf16 v[12:15], v[160:163], v[208:211], v[12:15]
	v_mfma_f32_16x16x32_bf16 v[60:63], v[156:159], v[188:191], v[60:63]
	v_mfma_f32_16x16x32_bf16 v[56:59], v[164:167], v[188:191], v[56:59]
	v_mfma_f32_16x16x32_bf16 v[52:55], v[156:159], v[196:199], v[52:55]
	v_mfma_f32_16x16x32_bf16 v[44:47], v[164:167], v[196:199], v[44:47]
	v_mfma_f32_16x16x32_bf16 v[36:39], v[156:159], v[204:207], v[36:39]
	v_mfma_f32_16x16x32_bf16 v[28:31], v[164:167], v[204:207], v[28:31]
	v_mfma_f32_16x16x32_bf16 v[20:23], v[156:159], v[212:215], v[20:23]
	v_mfma_f32_16x16x32_bf16 v[12:15], v[164:167], v[212:215], v[12:15]
	v_mfma_f32_16x16x32_bf16 v[48:51], v[168:171], v[184:187], v[48:51]
	v_mfma_f32_16x16x32_bf16 v[40:43], v[176:179], v[184:187], v[40:43]
	v_mfma_f32_16x16x32_bf16 v[32:35], v[168:171], v[192:195], v[32:35]
	v_mfma_f32_16x16x32_bf16 v[24:27], v[176:179], v[192:195], v[24:27]
	v_mfma_f32_16x16x32_bf16 v[16:19], v[168:171], v[200:203], v[16:19]
	v_mfma_f32_16x16x32_bf16 v[8:11], v[176:179], v[200:203], v[8:11]
	v_mfma_f32_16x16x32_bf16 v[4:7], v[168:171], v[208:211], v[4:7]
	v_mfma_f32_16x16x32_bf16 v[0:3], v[176:179], v[208:211], v[0:3]
	v_mfma_f32_16x16x32_bf16 v[48:51], v[172:175], v[188:191], v[48:51]
	v_mfma_f32_16x16x32_bf16 v[40:43], v[180:183], v[188:191], v[40:43]
	v_mfma_f32_16x16x32_bf16 v[32:35], v[172:175], v[196:199], v[32:35]
	v_mfma_f32_16x16x32_bf16 v[24:27], v[180:183], v[196:199], v[24:27]
	v_mfma_f32_16x16x32_bf16 v[16:19], v[172:175], v[204:207], v[16:19]
	v_mfma_f32_16x16x32_bf16 v[8:11], v[180:183], v[204:207], v[8:11]
	v_mfma_f32_16x16x32_bf16 v[4:7], v[172:175], v[212:215], v[4:7]
	v_mfma_f32_16x16x32_bf16 v[0:3], v[180:183], v[212:215], v[0:3]
	s_barrier
	s_add_i32 s67, s67, 2
	s_add_u32 s65, s65, 0x100
	s_addc_u32 s66, s66, 0
	s_cmp_gt_u32 s67, 9
	s_mov_b64 s[24:25], s[26:27]
	s_cbranch_scc0 .LBB0_254
	s_setprio 0
	s_and_b64 vcc, exec, s[12:13]
	s_cbranch_vccz .LBB0_257
	s_barrier

.Lsp_skip2:
.LBB0_281:
	ds_read_b128 v[144:147], v153
	ds_read_b128 v[156:159], v153 offset:1024
	ds_read_b128 v[160:163], v153 offset:2048
	ds_read_b128 v[164:167], v153 offset:3072
	ds_read_b128 v[168:171], v154
	ds_read_b128 v[172:175], v154 offset:1024
	ds_read_b128 v[176:179], v154 offset:2048
	ds_read_b128 v[180:183], v154 offset:3072
	ds_read_b128 v[184:187], v155
	ds_read_b128 v[188:191], v155 offset:1024
	ds_read_b128 v[192:195], v155 offset:2048
	ds_read_b128 v[196:199], v155 offset:3072
	ds_read_b128 v[200:203], v155 offset:4096
	ds_read_b128 v[204:207], v155 offset:5120
	ds_read_b128 v[208:211], v155 offset:6144
	ds_read_b128 v[212:215], v155 offset:7168
	s_add_u32 s34, s30, 0xfff80080
	s_addc_u32 s35, s31, -1
	s_cmp_eq_u32 s61, 28
	s_cselect_b32 s37, s23, s35
	s_cselect_b32 s36, s57, s34
	s_cselect_b32 s35, s21, s60
	s_cselect_b32 s34, s58, s59
	v_lshl_add_u64 v[148:149], s[30:31], 0, v[138:139]
	s_add_i32 m0, s29, 0xc000
	s_nop 0
	global_load_lds_dwordx4 v[148:149], off
	v_lshl_add_u64 v[148:149], s[30:31], 0, v[136:137]
	s_add_i32 m0, s29, 0xe000
	s_nop 0
	global_load_lds_dwordx4 v[148:149], off
	s_waitcnt vmcnt(8) lgkmcnt(0)
	s_barrier
	v_mfma_i32_16x16x64_i8 v[124:127], v[144:147], v[184:187], v[124:127]
	v_mfma_i32_16x16x64_i8 v[120:123], v[160:163], v[184:187], v[120:123]
	v_mfma_i32_16x16x64_i8 v[108:111], v[144:147], v[192:195], v[108:111]
	v_mfma_i32_16x16x64_i8 v[104:107], v[160:163], v[192:195], v[104:107]
	v_mfma_i32_16x16x64_i8 v[92:95], v[144:147], v[200:203], v[92:95]
	v_mfma_i32_16x16x64_i8 v[88:91], v[160:163], v[200:203], v[88:91]
	v_mfma_i32_16x16x64_i8 v[76:79], v[144:147], v[208:211], v[76:79]
	v_mfma_i32_16x16x64_i8 v[72:75], v[160:163], v[208:211], v[72:75]
	v_mfma_i32_16x16x64_i8 v[124:127], v[156:159], v[188:191], v[124:127]
	v_mfma_i32_16x16x64_i8 v[120:123], v[164:167], v[188:191], v[120:123]
	v_mfma_i32_16x16x64_i8 v[108:111], v[156:159], v[196:199], v[108:111]
	v_mfma_i32_16x16x64_i8 v[104:107], v[164:167], v[196:199], v[104:107]
	v_mfma_i32_16x16x64_i8 v[92:95], v[156:159], v[204:207], v[92:95]
	v_mfma_i32_16x16x64_i8 v[88:91], v[164:167], v[204:207], v[88:91]
	v_mfma_i32_16x16x64_i8 v[76:79], v[156:159], v[212:215], v[76:79]
	v_mfma_i32_16x16x64_i8 v[72:75], v[164:167], v[212:215], v[72:75]
	v_mfma_i32_16x16x64_i8 v[116:119], v[168:171], v[184:187], v[116:119]
	v_mfma_i32_16x16x64_i8 v[112:115], v[176:179], v[184:187], v[112:115]
	v_mfma_i32_16x16x64_i8 v[100:103], v[168:171], v[192:195], v[100:103]
	v_mfma_i32_16x16x64_i8 v[96:99], v[176:179], v[192:195], v[96:99]
	v_mfma_i32_16x16x64_i8 v[84:87], v[168:171], v[200:203], v[84:87]
	v_mfma_i32_16x16x64_i8 v[80:83], v[176:179], v[200:203], v[80:83]
	v_mfma_i32_16x16x64_i8 v[68:71], v[168:171], v[208:211], v[68:71]
	v_mfma_i32_16x16x64_i8 v[64:67], v[176:179], v[208:211], v[64:67]
	v_mfma_i32_16x16x64_i8 v[116:119], v[172:175], v[188:191], v[116:119]
	v_mfma_i32_16x16x64_i8 v[112:115], v[180:183], v[188:191], v[112:115]
	v_mfma_i32_16x16x64_i8 v[100:103], v[172:175], v[196:199], v[100:103]
	v_mfma_i32_16x16x64_i8 v[96:99], v[180:183], v[196:199], v[96:99]
	v_mfma_i32_16x16x64_i8 v[84:87], v[172:175], v[204:207], v[84:87]
	v_mfma_i32_16x16x64_i8 v[80:83], v[180:183], v[204:207], v[80:83]
	v_mfma_i32_16x16x64_i8 v[68:71], v[172:175], v[212:215], v[68:71]
	v_mfma_i32_16x16x64_i8 v[64:67], v[180:183], v[212:215], v[64:67]
	s_barrier
	ds_read_b128 v[184:187], v155 offset:16384
	ds_read_b128 v[188:191], v155 offset:17408
	ds_read_b128 v[192:195], v155 offset:18432
	ds_read_b128 v[196:199], v155 offset:19456
	ds_read_b128 v[200:203], v155 offset:20480
	ds_read_b128 v[204:207], v155 offset:21504
	ds_read_b128 v[208:211], v155 offset:22528
	ds_read_b128 v[212:215], v155 offset:23552
	s_add_i32 s62, s41, s40
	v_lshl_add_u64 v[148:149], s[34:35], 0, v[130:131]
	s_mov_b32 m0, s62
	s_nop 0
	global_load_lds_dwordx4 v[148:149], off
	s_add_i32 m0, s62, 0x2000
	s_add_u32 s62, s34, 0x80000
	v_lshl_add_u64 v[216:217], s[34:35], 0, v[134:135]
	s_addc_u32 s63, s35, 0
	s_add_i32 s64, s42, s40
	global_load_lds_dwordx4 v[216:217], off
	v_lshl_add_u64 v[218:219], s[62:63], 0, v[130:131]
	s_mov_b32 m0, s64
	v_lshl_add_u64 v[220:221], s[36:37], 0, v[132:133]
	global_load_lds_dwordx4 v[218:219], off
	v_lshl_add_u64 v[218:219], s[62:63], 0, v[134:135]
	s_add_i32 m0, s64, 0x2000
	s_nop 0
	global_load_lds_dwordx4 v[218:219], off
	v_lshl_add_u64 v[218:219], s[36:37], 0, v[128:129]
	s_mov_b32 m0, s29
	s_nop 0
	global_load_lds_dwordx4 v[218:219], off
	s_mov_b32 m0, s48
	s_nop 0
	global_load_lds_dwordx4 v[220:221], off
	s_waitcnt vmcnt(8) lgkmcnt(0)
	s_barrier
	v_mfma_i32_16x16x64_i8 v[60:63], v[144:147], v[184:187], v[60:63]
	v_mfma_i32_16x16x64_i8 v[56:59], v[160:163], v[184:187], v[56:59]
	v_mfma_i32_16x16x64_i8 v[44:47], v[144:147], v[192:195], v[44:47]
	v_mfma_i32_16x16x64_i8 v[40:43], v[160:163], v[192:195], v[40:43]
	v_mfma_i32_16x16x64_i8 v[28:31], v[144:147], v[200:203], v[28:31]
	v_mfma_i32_16x16x64_i8 v[24:27], v[160:163], v[200:203], v[24:27]
	v_mfma_i32_16x16x64_i8 v[12:15], v[144:147], v[208:211], v[12:15]
	v_mfma_i32_16x16x64_i8 v[8:11], v[160:163], v[208:211], v[8:11]
	v_mfma_i32_16x16x64_i8 v[60:63], v[156:159], v[188:191], v[60:63]
	v_mfma_i32_16x16x64_i8 v[56:59], v[164:167], v[188:191], v[56:59]
	v_mfma_i32_16x16x64_i8 v[44:47], v[156:159], v[196:199], v[44:47]
	v_mfma_i32_16x16x64_i8 v[40:43], v[164:167], v[196:199], v[40:43]
	v_mfma_i32_16x16x64_i8 v[28:31], v[156:159], v[204:207], v[28:31]
	v_mfma_i32_16x16x64_i8 v[24:27], v[164:167], v[204:207], v[24:27]
	v_mfma_i32_16x16x64_i8 v[12:15], v[156:159], v[212:215], v[12:15]
	v_mfma_i32_16x16x64_i8 v[8:11], v[164:167], v[212:215], v[8:11]
	v_mfma_i32_16x16x64_i8 v[52:55], v[168:171], v[184:187], v[52:55]
	v_mfma_i32_16x16x64_i8 v[48:51], v[176:179], v[184:187], v[48:51]
	v_mfma_i32_16x16x64_i8 v[36:39], v[168:171], v[192:195], v[36:39]
	v_mfma_i32_16x16x64_i8 v[32:35], v[176:179], v[192:195], v[32:35]
	v_mfma_i32_16x16x64_i8 v[20:23], v[168:171], v[200:203], v[20:23]
	v_mfma_i32_16x16x64_i8 v[16:19], v[176:179], v[200:203], v[16:19]
	v_mfma_i32_16x16x64_i8 v[4:7], v[168:171], v[208:211], v[4:7]
	v_mfma_i32_16x16x64_i8 v[0:3], v[176:179], v[208:211], v[0:3]
	v_mfma_i32_16x16x64_i8 v[52:55], v[172:175], v[188:191], v[52:55]
	v_mfma_i32_16x16x64_i8 v[48:51], v[180:183], v[188:191], v[48:51]
	v_mfma_i32_16x16x64_i8 v[36:39], v[172:175], v[196:199], v[36:39]
	v_mfma_i32_16x16x64_i8 v[32:35], v[180:183], v[196:199], v[32:35]
	v_mfma_i32_16x16x64_i8 v[20:23], v[172:175], v[204:207], v[20:23]
	v_mfma_i32_16x16x64_i8 v[16:19], v[180:183], v[204:207], v[16:19]
	v_mfma_i32_16x16x64_i8 v[4:7], v[172:175], v[212:215], v[4:7]
	v_mfma_i32_16x16x64_i8 v[0:3], v[180:183], v[212:215], v[0:3]
	s_barrier
	ds_read_b128 v[184:187], v155 offset:32768
	ds_read_b128 v[188:191], v155 offset:33792
	ds_read_b128 v[192:195], v155 offset:34816
	ds_read_b128 v[196:199], v155 offset:35840
	ds_read_b128 v[200:203], v155 offset:36864
	ds_read_b128 v[204:207], v155 offset:37888
	ds_read_b128 v[208:211], v155 offset:38912
	ds_read_b128 v[212:215], v155 offset:39936
	s_add_i32 s62, 0, 0x18000
	s_add_i32 s63, 0, 0x1c000
	v_add_u32_e32 v164, s62, v151
	v_add_u32_e32 v180, s63, v151
	ds_read_b128 v[144:147], v164
	ds_read_b128 v[156:159], v164 offset:1024
	ds_read_b128 v[160:163], v164 offset:2048
	ds_read_b128 v[164:167], v164 offset:3072
	ds_read_b128 v[168:171], v180
	ds_read_b128 v[172:175], v180 offset:1024
	ds_read_b128 v[176:179], v180 offset:2048
	ds_read_b128 v[180:183], v180 offset:3072
	s_add_u32 s36, s36, 0x80000
	s_addc_u32 s37, s37, 0
	s_mov_b32 m0, s49
	v_lshl_add_u64 v[222:223], s[36:37], 0, v[128:129]
	global_load_lds_dwordx4 v[222:223], off
	v_lshl_add_u64 v[222:223], s[36:37], 0, v[132:133]
	s_mov_b32 m0, s50
	s_nop 0
	global_load_lds_dwordx4 v[222:223], off
	s_waitcnt vmcnt(8) lgkmcnt(0)
	s_barrier
	v_mfma_i32_16x16x64_i8 v[124:127], v[144:147], v[184:187], v[124:127]
	v_mfma_i32_16x16x64_i8 v[120:123], v[160:163], v[184:187], v[120:123]
	v_mfma_i32_16x16x64_i8 v[108:111], v[144:147], v[192:195], v[108:111]
	v_mfma_i32_16x16x64_i8 v[104:107], v[160:163], v[192:195], v[104:107]
	v_mfma_i32_16x16x64_i8 v[92:95], v[144:147], v[200:203], v[92:95]
	v_mfma_i32_16x16x64_i8 v[88:91], v[160:163], v[200:203], v[88:91]
	v_mfma_i32_16x16x64_i8 v[76:79], v[144:147], v[208:211], v[76:79]
	v_mfma_i32_16x16x64_i8 v[72:75], v[160:163], v[208:211], v[72:75]
	v_mfma_i32_16x16x64_i8 v[124:127], v[156:159], v[188:191], v[124:127]
	v_mfma_i32_16x16x64_i8 v[120:123], v[164:167], v[188:191], v[120:123]
	v_mfma_i32_16x16x64_i8 v[108:111], v[156:159], v[196:199], v[108:111]
	v_mfma_i32_16x16x64_i8 v[104:107], v[164:167], v[196:199], v[104:107]
	v_mfma_i32_16x16x64_i8 v[92:95], v[156:159], v[204:207], v[92:95]
	v_mfma_i32_16x16x64_i8 v[88:91], v[164:167], v[204:207], v[88:91]
	v_mfma_i32_16x16x64_i8 v[76:79], v[156:159], v[212:215], v[76:79]
	v_mfma_i32_16x16x64_i8 v[72:75], v[164:167], v[212:215], v[72:75]
	v_mfma_i32_16x16x64_i8 v[116:119], v[168:171], v[184:187], v[116:119]
	v_mfma_i32_16x16x64_i8 v[112:115], v[176:179], v[184:187], v[112:115]
	v_mfma_i32_16x16x64_i8 v[100:103], v[168:171], v[192:195], v[100:103]
	v_mfma_i32_16x16x64_i8 v[96:99], v[176:179], v[192:195], v[96:99]
	v_mfma_i32_16x16x64_i8 v[84:87], v[168:171], v[200:203], v[84:87]
	v_mfma_i32_16x16x64_i8 v[80:83], v[176:179], v[200:203], v[80:83]
	v_mfma_i32_16x16x64_i8 v[68:71], v[168:171], v[208:211], v[68:71]
	v_mfma_i32_16x16x64_i8 v[64:67], v[176:179], v[208:211], v[64:67]
	v_mfma_i32_16x16x64_i8 v[116:119], v[172:175], v[188:191], v[116:119]
	v_mfma_i32_16x16x64_i8 v[112:115], v[180:183], v[188:191], v[112:115]
	v_mfma_i32_16x16x64_i8 v[100:103], v[172:175], v[196:199], v[100:103]
	v_mfma_i32_16x16x64_i8 v[96:99], v[180:183], v[196:199], v[96:99]
	v_mfma_i32_16x16x64_i8 v[84:87], v[172:175], v[204:207], v[84:87]
	v_mfma_i32_16x16x64_i8 v[80:83], v[180:183], v[204:207], v[80:83]
	v_mfma_i32_16x16x64_i8 v[68:71], v[172:175], v[212:215], v[68:71]
	v_mfma_i32_16x16x64_i8 v[64:67], v[180:183], v[212:215], v[64:67]
	s_barrier
	ds_read_b128 v[184:187], v155 offset:49152
	ds_read_b128 v[188:191], v155 offset:50176
	ds_read_b128 v[192:195], v155 offset:51200
	ds_read_b128 v[196:199], v155 offset:52224
	ds_read_b128 v[200:203], v155 offset:53248
	ds_read_b128 v[204:207], v155 offset:54272
	ds_read_b128 v[208:211], v155 offset:55296
	ds_read_b128 v[212:215], v155 offset:56320
	s_add_i32 s36, s62, s40
	v_lshl_add_u64 v[148:149], v[148:149], 0, s[6:7]
	s_mov_b32 m0, s36
	s_nop 0
	global_load_lds_dwordx4 v[148:149], off
	s_add_i32 m0, s36, 0x2000
	s_add_u32 s34, s34, 0x80080
	v_lshl_add_u64 v[148:149], v[216:217], 0, s[6:7]
	s_addc_u32 s35, s35, 0
	s_add_i32 s36, s63, s40
	global_load_lds_dwordx4 v[148:149], off
	v_lshl_add_u64 v[148:149], s[34:35], 0, v[130:131]
	s_mov_b32 m0, s36
	s_nop 0
	global_load_lds_dwordx4 v[148:149], off
	v_lshl_add_u64 v[148:149], s[34:35], 0, v[134:135]
	s_add_i32 m0, s36, 0x2000
	s_nop 0
	global_load_lds_dwordx4 v[148:149], off
	v_lshl_add_u64 v[148:149], v[218:219], 0, s[6:7]
	s_mov_b32 m0, s44
	s_nop 0
	global_load_lds_dwordx4 v[148:149], off
	v_lshl_add_u64 v[148:149], v[220:221], 0, s[6:7]
	s_mov_b32 m0, s52
	s_nop 0
	global_load_lds_dwordx4 v[148:149], off
	s_waitcnt vmcnt(8) lgkmcnt(0)
	s_barrier
	v_mfma_i32_16x16x64_i8 v[60:63], v[144:147], v[184:187], v[60:63]
	v_mfma_i32_16x16x64_i8 v[56:59], v[160:163], v[184:187], v[56:59]
	v_mfma_i32_16x16x64_i8 v[44:47], v[144:147], v[192:195], v[44:47]
	v_mfma_i32_16x16x64_i8 v[40:43], v[160:163], v[192:195], v[40:43]
	v_mfma_i32_16x16x64_i8 v[28:31], v[144:147], v[200:203], v[28:31]
	v_mfma_i32_16x16x64_i8 v[24:27], v[160:163], v[200:203], v[24:27]
	v_mfma_i32_16x16x64_i8 v[12:15], v[144:147], v[208:211], v[12:15]
	v_mfma_i32_16x16x64_i8 v[8:11], v[160:163], v[208:211], v[8:11]
	v_mfma_i32_16x16x64_i8 v[60:63], v[156:159], v[188:191], v[60:63]
	v_mfma_i32_16x16x64_i8 v[56:59], v[164:167], v[188:191], v[56:59]
	v_mfma_i32_16x16x64_i8 v[44:47], v[156:159], v[196:199], v[44:47]
	v_mfma_i32_16x16x64_i8 v[40:43], v[164:167], v[196:199], v[40:43]
	v_mfma_i32_16x16x64_i8 v[28:31], v[156:159], v[204:207], v[28:31]
	v_mfma_i32_16x16x64_i8 v[24:27], v[164:167], v[204:207], v[24:27]
	v_mfma_i32_16x16x64_i8 v[12:15], v[156:159], v[212:215], v[12:15]
	v_mfma_i32_16x16x64_i8 v[8:11], v[164:167], v[212:215], v[8:11]
	v_mfma_i32_16x16x64_i8 v[52:55], v[168:171], v[184:187], v[52:55]
	v_mfma_i32_16x16x64_i8 v[48:51], v[176:179], v[184:187], v[48:51]
	v_mfma_i32_16x16x64_i8 v[36:39], v[168:171], v[192:195], v[36:39]
	v_mfma_i32_16x16x64_i8 v[32:35], v[176:179], v[192:195], v[32:35]
	v_mfma_i32_16x16x64_i8 v[20:23], v[168:171], v[200:203], v[20:23]
	v_mfma_i32_16x16x64_i8 v[16:19], v[176:179], v[200:203], v[16:19]
	v_mfma_i32_16x16x64_i8 v[4:7], v[168:171], v[208:211], v[4:7]
	v_mfma_i32_16x16x64_i8 v[0:3], v[176:179], v[208:211], v[0:3]
	v_mfma_i32_16x16x64_i8 v[52:55], v[172:175], v[188:191], v[52:55]
	v_mfma_i32_16x16x64_i8 v[48:51], v[180:183], v[188:191], v[48:51]
	v_mfma_i32_16x16x64_i8 v[36:39], v[172:175], v[196:199], v[36:39]
	v_mfma_i32_16x16x64_i8 v[32:35], v[180:183], v[196:199], v[32:35]
	v_mfma_i32_16x16x64_i8 v[20:23], v[172:175], v[204:207], v[20:23]
	v_mfma_i32_16x16x64_i8 v[16:19], v[180:183], v[204:207], v[16:19]
	v_mfma_i32_16x16x64_i8 v[4:7], v[172:175], v[212:215], v[4:7]
	v_mfma_i32_16x16x64_i8 v[0:3], v[180:183], v[212:215], v[0:3]
	s_barrier
	s_add_i32 s61, s61, 2
	s_add_u32 s59, s59, 0x100
	s_addc_u32 s60, s60, 0
	s_add_u32 s30, s30, 0x100
	s_addc_u32 s31, s31, 0
	s_cmp_gt_u32 s61, 29
	s_cbranch_scc0 .LBB0_281
	s_setprio 0
	s_and_b64 vcc, exec, s[8:9]
	s_cbranch_vccz .LBB0_284
	s_barrier

.Lsp_skip3:
.LBB0_451:
	ds_read_b128 v[112:115], v193
	ds_read_b128 v[124:127], v193 offset:1024
	ds_read_b128 v[136:139], v193 offset:2048
	ds_read_b128 v[140:143], v193 offset:3072
	ds_read_b128 v[144:147], v194
	ds_read_b128 v[148:151], v194 offset:1024
	ds_read_b128 v[168:171], v194 offset:2048
	ds_read_b128 v[172:175], v194 offset:3072
	ds_read_b128 v[176:179], v195
	ds_read_b128 v[180:183], v195 offset:1024
	ds_read_b128 v[184:187], v195 offset:2048
	ds_read_b128 v[200:203], v195 offset:3072
	ds_read_b128 v[204:207], v195 offset:4096
	ds_read_b128 v[208:211], v195 offset:5120
	ds_read_b128 v[212:215], v195 offset:6144
	ds_read_b128 v[216:219], v195 offset:7168
	s_add_u32 s34, s30, 0xfff00080
	s_addc_u32 s35, s31, -1
	s_cmp_eq_u32 s58, 60
	s_cselect_b32 s37, s21, s35
	s_cselect_b32 s36, s27, s34
	s_cselect_b32 s35, s19, s57
	s_cselect_b32 s34, s55, s56
	v_lshl_add_u64 v[188:189], s[30:31], 0, v[162:163]
	s_add_i32 m0, s29, 0xc000
	s_nop 0
	global_load_lds_dwordx4 v[188:189], off
	v_lshl_add_u64 v[188:189], s[30:31], 0, v[160:161]
	s_add_i32 m0, s29, 0xe000
	s_nop 0
	global_load_lds_dwordx4 v[188:189], off
	s_waitcnt vmcnt(8) lgkmcnt(0)
	s_barrier
	v_mfma_f32_16x16x32_bf16 v[132:135], v[112:115], v[176:179], v[132:135]
	v_mfma_f32_16x16x32_bf16 v[128:131], v[136:139], v[176:179], v[128:131]
	v_mfma_f32_16x16x32_bf16 v[108:111], v[112:115], v[184:187], v[108:111]
	v_mfma_f32_16x16x32_bf16 v[104:107], v[136:139], v[184:187], v[104:107]
	v_mfma_f32_16x16x32_bf16 v[92:95], v[112:115], v[204:207], v[92:95]
	v_mfma_f32_16x16x32_bf16 v[88:91], v[136:139], v[204:207], v[88:91]
	v_mfma_f32_16x16x32_bf16 v[76:79], v[112:115], v[212:215], v[76:79]
	v_mfma_f32_16x16x32_bf16 v[72:75], v[136:139], v[212:215], v[72:75]
	v_mfma_f32_16x16x32_bf16 v[132:135], v[124:127], v[180:183], v[132:135]
	v_mfma_f32_16x16x32_bf16 v[128:131], v[140:143], v[180:183], v[128:131]
	v_mfma_f32_16x16x32_bf16 v[108:111], v[124:127], v[200:203], v[108:111]
	v_mfma_f32_16x16x32_bf16 v[104:107], v[140:143], v[200:203], v[104:107]
	v_mfma_f32_16x16x32_bf16 v[92:95], v[124:127], v[208:211], v[92:95]
	v_mfma_f32_16x16x32_bf16 v[88:91], v[140:143], v[208:211], v[88:91]
	v_mfma_f32_16x16x32_bf16 v[76:79], v[124:127], v[216:219], v[76:79]
	v_mfma_f32_16x16x32_bf16 v[72:75], v[140:143], v[216:219], v[72:75]
	v_mfma_f32_16x16x32_bf16 v[120:123], v[144:147], v[176:179], v[120:123]
	v_mfma_f32_16x16x32_bf16 v[116:119], v[168:171], v[176:179], v[116:119]
	v_mfma_f32_16x16x32_bf16 v[100:103], v[144:147], v[184:187], v[100:103]
	v_mfma_f32_16x16x32_bf16 v[96:99], v[168:171], v[184:187], v[96:99]
	v_mfma_f32_16x16x32_bf16 v[84:87], v[144:147], v[204:207], v[84:87]
	v_mfma_f32_16x16x32_bf16 v[80:83], v[168:171], v[204:207], v[80:83]
	v_mfma_f32_16x16x32_bf16 v[68:71], v[144:147], v[212:215], v[68:71]
	v_mfma_f32_16x16x32_bf16 v[64:67], v[168:171], v[212:215], v[64:67]
	v_mfma_f32_16x16x32_bf16 v[120:123], v[148:151], v[180:183], v[120:123]
	v_mfma_f32_16x16x32_bf16 v[116:119], v[172:175], v[180:183], v[116:119]
	v_mfma_f32_16x16x32_bf16 v[100:103], v[148:151], v[200:203], v[100:103]
	v_mfma_f32_16x16x32_bf16 v[96:99], v[172:175], v[200:203], v[96:99]
	v_mfma_f32_16x16x32_bf16 v[84:87], v[148:151], v[208:211], v[84:87]
	v_mfma_f32_16x16x32_bf16 v[80:83], v[172:175], v[208:211], v[80:83]
	v_mfma_f32_16x16x32_bf16 v[68:71], v[148:151], v[216:219], v[68:71]
	v_mfma_f32_16x16x32_bf16 v[64:67], v[172:175], v[216:219], v[64:67]
	s_barrier
	ds_read_b128 v[176:179], v195 offset:16384
	ds_read_b128 v[180:183], v195 offset:17408
	ds_read_b128 v[184:187], v195 offset:18432
	ds_read_b128 v[200:203], v195 offset:19456
	ds_read_b128 v[204:207], v195 offset:20480
	ds_read_b128 v[208:211], v195 offset:21504
	ds_read_b128 v[212:215], v195 offset:22528
	ds_read_b128 v[216:219], v195 offset:23552
	s_add_i32 s59, s50, s41
	v_lshl_add_u64 v[188:189], s[34:35], 0, v[154:155]
	s_mov_b32 m0, s59
	s_nop 0
	global_load_lds_dwordx4 v[188:189], off
	s_add_i32 m0, s59, 0x2000
	s_add_u32 s60, s34, 0x100000
	v_lshl_add_u64 v[220:221], s[34:35], 0, v[158:159]
	s_addc_u32 s61, s35, 0
	s_add_i32 s59, s51, s41
	global_load_lds_dwordx4 v[220:221], off
	v_lshl_add_u64 v[222:223], s[60:61], 0, v[154:155]
	s_mov_b32 m0, s59
	v_lshl_add_u64 v[224:225], s[36:37], 0, v[156:157]
	global_load_lds_dwordx4 v[222:223], off
	v_lshl_add_u64 v[222:223], s[60:61], 0, v[158:159]
	s_add_i32 m0, s59, 0x2000
	s_nop 0
	global_load_lds_dwordx4 v[222:223], off
	v_lshl_add_u64 v[222:223], s[36:37], 0, v[152:153]
	s_mov_b32 m0, s29
	s_nop 0
	global_load_lds_dwordx4 v[222:223], off
	s_mov_b32 m0, s42
	s_nop 0
	global_load_lds_dwordx4 v[224:225], off
	s_waitcnt vmcnt(8) lgkmcnt(0)
	s_barrier
	v_mfma_f32_16x16x32_bf16 v[60:63], v[112:115], v[176:179], v[60:63]
	v_mfma_f32_16x16x32_bf16 v[56:59], v[136:139], v[176:179], v[56:59]
	v_mfma_f32_16x16x32_bf16 v[44:47], v[112:115], v[184:187], v[44:47]
	v_mfma_f32_16x16x32_bf16 v[40:43], v[136:139], v[184:187], v[40:43]
	v_mfma_f32_16x16x32_bf16 v[28:31], v[112:115], v[204:207], v[28:31]
	v_mfma_f32_16x16x32_bf16 v[24:27], v[136:139], v[204:207], v[24:27]
	v_mfma_f32_16x16x32_bf16 v[12:15], v[112:115], v[212:215], v[12:15]
	v_mfma_f32_16x16x32_bf16 v[8:11], v[136:139], v[212:215], v[8:11]
	v_mfma_f32_16x16x32_bf16 v[60:63], v[124:127], v[180:183], v[60:63]
	v_mfma_f32_16x16x32_bf16 v[56:59], v[140:143], v[180:183], v[56:59]
	v_mfma_f32_16x16x32_bf16 v[44:47], v[124:127], v[200:203], v[44:47]
	v_mfma_f32_16x16x32_bf16 v[40:43], v[140:143], v[200:203], v[40:43]
	v_mfma_f32_16x16x32_bf16 v[28:31], v[124:127], v[208:211], v[28:31]
	v_mfma_f32_16x16x32_bf16 v[24:27], v[140:143], v[208:211], v[24:27]
	v_mfma_f32_16x16x32_bf16 v[12:15], v[124:127], v[216:219], v[12:15]
	v_mfma_f32_16x16x32_bf16 v[8:11], v[140:143], v[216:219], v[8:11]
	v_mfma_f32_16x16x32_bf16 v[52:55], v[144:147], v[176:179], v[52:55]
	v_mfma_f32_16x16x32_bf16 v[48:51], v[168:171], v[176:179], v[48:51]
	v_mfma_f32_16x16x32_bf16 v[36:39], v[144:147], v[184:187], v[36:39]
	v_mfma_f32_16x16x32_bf16 v[32:35], v[168:171], v[184:187], v[32:35]
	v_mfma_f32_16x16x32_bf16 v[20:23], v[144:147], v[204:207], v[20:23]
	v_mfma_f32_16x16x32_bf16 v[16:19], v[168:171], v[204:207], v[16:19]
	v_mfma_f32_16x16x32_bf16 v[4:7], v[144:147], v[212:215], v[4:7]
	v_mfma_f32_16x16x32_bf16 v[0:3], v[168:171], v[212:215], v[0:3]
	v_mfma_f32_16x16x32_bf16 v[52:55], v[148:151], v[180:183], v[52:55]
	v_mfma_f32_16x16x32_bf16 v[48:51], v[172:175], v[180:183], v[48:51]
	v_mfma_f32_16x16x32_bf16 v[36:39], v[148:151], v[200:203], v[36:39]
	v_mfma_f32_16x16x32_bf16 v[32:35], v[172:175], v[200:203], v[32:35]
	v_mfma_f32_16x16x32_bf16 v[20:23], v[148:151], v[208:211], v[20:23]
	v_mfma_f32_16x16x32_bf16 v[16:19], v[172:175], v[208:211], v[16:19]
	v_mfma_f32_16x16x32_bf16 v[4:7], v[148:151], v[216:219], v[4:7]
	v_mfma_f32_16x16x32_bf16 v[0:3], v[172:175], v[216:219], v[0:3]
	s_barrier
	ds_read_b128 v[176:179], v195 offset:32768
	ds_read_b128 v[180:183], v195 offset:33792
	ds_read_b128 v[184:187], v195 offset:34816
	ds_read_b128 v[200:203], v195 offset:35840
	ds_read_b128 v[204:207], v195 offset:36864
	ds_read_b128 v[208:211], v195 offset:37888
	ds_read_b128 v[212:215], v195 offset:38912
	ds_read_b128 v[216:219], v195 offset:39936
	s_add_i32 s59, 0, 0x18000
	s_add_i32 s60, 0, 0x1c000
	v_add_u32_e32 v140, s59, v191
	v_add_u32_e32 v172, s60, v191
	ds_read_b128 v[112:115], v140
	ds_read_b128 v[124:127], v140 offset:1024
	ds_read_b128 v[136:139], v140 offset:2048
	ds_read_b128 v[140:143], v140 offset:3072
	ds_read_b128 v[144:147], v172
	ds_read_b128 v[148:151], v172 offset:1024
	ds_read_b128 v[168:171], v172 offset:2048
	ds_read_b128 v[172:175], v172 offset:3072
	s_add_u32 s36, s36, 0x100000
	s_addc_u32 s37, s37, 0
	s_mov_b32 m0, s43
	v_lshl_add_u64 v[226:227], s[36:37], 0, v[152:153]
	global_load_lds_dwordx4 v[226:227], off
	v_lshl_add_u64 v[226:227], s[36:37], 0, v[156:157]
	s_mov_b32 m0, s44
	s_nop 0
	global_load_lds_dwordx4 v[226:227], off
	s_waitcnt vmcnt(8) lgkmcnt(0)
	s_barrier
	v_mfma_f32_16x16x32_bf16 v[132:135], v[112:115], v[176:179], v[132:135]
	v_mfma_f32_16x16x32_bf16 v[128:131], v[136:139], v[176:179], v[128:131]
	v_mfma_f32_16x16x32_bf16 v[108:111], v[112:115], v[184:187], v[108:111]
	v_mfma_f32_16x16x32_bf16 v[104:107], v[136:139], v[184:187], v[104:107]
	v_mfma_f32_16x16x32_bf16 v[92:95], v[112:115], v[204:207], v[92:95]
	v_mfma_f32_16x16x32_bf16 v[88:91], v[136:139], v[204:207], v[88:91]
	v_mfma_f32_16x16x32_bf16 v[76:79], v[112:115], v[212:215], v[76:79]
	v_mfma_f32_16x16x32_bf16 v[72:75], v[136:139], v[212:215], v[72:75]
	v_mfma_f32_16x16x32_bf16 v[132:135], v[124:127], v[180:183], v[132:135]
	v_mfma_f32_16x16x32_bf16 v[128:131], v[140:143], v[180:183], v[128:131]
	v_mfma_f32_16x16x32_bf16 v[108:111], v[124:127], v[200:203], v[108:111]
	v_mfma_f32_16x16x32_bf16 v[104:107], v[140:143], v[200:203], v[104:107]
	v_mfma_f32_16x16x32_bf16 v[92:95], v[124:127], v[208:211], v[92:95]
	v_mfma_f32_16x16x32_bf16 v[88:91], v[140:143], v[208:211], v[88:91]
	v_mfma_f32_16x16x32_bf16 v[76:79], v[124:127], v[216:219], v[76:79]
	v_mfma_f32_16x16x32_bf16 v[72:75], v[140:143], v[216:219], v[72:75]
	v_mfma_f32_16x16x32_bf16 v[120:123], v[144:147], v[176:179], v[120:123]
	v_mfma_f32_16x16x32_bf16 v[116:119], v[168:171], v[176:179], v[116:119]
	v_mfma_f32_16x16x32_bf16 v[100:103], v[144:147], v[184:187], v[100:103]
	v_mfma_f32_16x16x32_bf16 v[96:99], v[168:171], v[184:187], v[96:99]
	v_mfma_f32_16x16x32_bf16 v[84:87], v[144:147], v[204:207], v[84:87]
	v_mfma_f32_16x16x32_bf16 v[80:83], v[168:171], v[204:207], v[80:83]
	v_mfma_f32_16x16x32_bf16 v[68:71], v[144:147], v[212:215], v[68:71]
	v_mfma_f32_16x16x32_bf16 v[64:67], v[168:171], v[212:215], v[64:67]
	v_mfma_f32_16x16x32_bf16 v[120:123], v[148:151], v[180:183], v[120:123]
	v_mfma_f32_16x16x32_bf16 v[116:119], v[172:175], v[180:183], v[116:119]
	v_mfma_f32_16x16x32_bf16 v[100:103], v[148:151], v[200:203], v[100:103]
	v_mfma_f32_16x16x32_bf16 v[96:99], v[172:175], v[200:203], v[96:99]
	v_mfma_f32_16x16x32_bf16 v[84:87], v[148:151], v[208:211], v[84:87]
	v_mfma_f32_16x16x32_bf16 v[80:83], v[172:175], v[208:211], v[80:83]
	v_mfma_f32_16x16x32_bf16 v[68:71], v[148:151], v[216:219], v[68:71]
	v_mfma_f32_16x16x32_bf16 v[64:67], v[172:175], v[216:219], v[64:67]
	s_barrier
	ds_read_b128 v[176:179], v195 offset:49152
	ds_read_b128 v[180:183], v195 offset:50176
	ds_read_b128 v[184:187], v195 offset:51200
	ds_read_b128 v[200:203], v195 offset:52224
	ds_read_b128 v[204:207], v195 offset:53248
	ds_read_b128 v[208:211], v195 offset:54272
	ds_read_b128 v[212:215], v195 offset:55296
	ds_read_b128 v[216:219], v195 offset:56320
	s_add_i32 s36, s59, s41
	v_lshl_add_u64 v[188:189], v[188:189], 0, s[14:15]
	s_mov_b32 m0, s36
	s_nop 0
	global_load_lds_dwordx4 v[188:189], off
	s_add_i32 m0, s36, 0x2000
	s_add_u32 s34, s34, 0x100080
	v_lshl_add_u64 v[188:189], v[220:221], 0, s[14:15]
	s_addc_u32 s35, s35, 0
	s_add_i32 s36, s60, s41
	global_load_lds_dwordx4 v[188:189], off
	v_lshl_add_u64 v[188:189], s[34:35], 0, v[154:155]
	s_mov_b32 m0, s36
	s_nop 0
	global_load_lds_dwordx4 v[188:189], off
	v_lshl_add_u64 v[188:189], s[34:35], 0, v[158:159]
	s_add_i32 m0, s36, 0x2000
	s_nop 0
	global_load_lds_dwordx4 v[188:189], off
	v_lshl_add_u64 v[188:189], v[222:223], 0, s[14:15]
	s_mov_b32 m0, s46
	s_nop 0
	global_load_lds_dwordx4 v[188:189], off
	v_lshl_add_u64 v[188:189], v[224:225], 0, s[14:15]
	s_mov_b32 m0, s47
	s_nop 0
	global_load_lds_dwordx4 v[188:189], off
	s_waitcnt vmcnt(8) lgkmcnt(0)
	s_barrier
	v_mfma_f32_16x16x32_bf16 v[60:63], v[112:115], v[176:179], v[60:63]
	v_mfma_f32_16x16x32_bf16 v[56:59], v[136:139], v[176:179], v[56:59]
	v_mfma_f32_16x16x32_bf16 v[44:47], v[112:115], v[184:187], v[44:47]
	v_mfma_f32_16x16x32_bf16 v[40:43], v[136:139], v[184:187], v[40:43]
	v_mfma_f32_16x16x32_bf16 v[28:31], v[112:115], v[204:207], v[28:31]
	v_mfma_f32_16x16x32_bf16 v[24:27], v[136:139], v[204:207], v[24:27]
	v_mfma_f32_16x16x32_bf16 v[12:15], v[112:115], v[212:215], v[12:15]
	v_mfma_f32_16x16x32_bf16 v[8:11], v[136:139], v[212:215], v[8:11]
	v_mfma_f32_16x16x32_bf16 v[60:63], v[124:127], v[180:183], v[60:63]
	v_mfma_f32_16x16x32_bf16 v[56:59], v[140:143], v[180:183], v[56:59]
	v_mfma_f32_16x16x32_bf16 v[44:47], v[124:127], v[200:203], v[44:47]
	v_mfma_f32_16x16x32_bf16 v[40:43], v[140:143], v[200:203], v[40:43]
	v_mfma_f32_16x16x32_bf16 v[28:31], v[124:127], v[208:211], v[28:31]
	v_mfma_f32_16x16x32_bf16 v[24:27], v[140:143], v[208:211], v[24:27]
	v_mfma_f32_16x16x32_bf16 v[12:15], v[124:127], v[216:219], v[12:15]
	v_mfma_f32_16x16x32_bf16 v[8:11], v[140:143], v[216:219], v[8:11]
	v_mfma_f32_16x16x32_bf16 v[52:55], v[144:147], v[176:179], v[52:55]
	v_mfma_f32_16x16x32_bf16 v[48:51], v[168:171], v[176:179], v[48:51]
	v_mfma_f32_16x16x32_bf16 v[36:39], v[144:147], v[184:187], v[36:39]
	v_mfma_f32_16x16x32_bf16 v[32:35], v[168:171], v[184:187], v[32:35]
	v_mfma_f32_16x16x32_bf16 v[20:23], v[144:147], v[204:207], v[20:23]
	v_mfma_f32_16x16x32_bf16 v[16:19], v[168:171], v[204:207], v[16:19]
	v_mfma_f32_16x16x32_bf16 v[4:7], v[144:147], v[212:215], v[4:7]
	v_mfma_f32_16x16x32_bf16 v[0:3], v[168:171], v[212:215], v[0:3]
	v_mfma_f32_16x16x32_bf16 v[52:55], v[148:151], v[180:183], v[52:55]
	v_mfma_f32_16x16x32_bf16 v[48:51], v[172:175], v[180:183], v[48:51]
	v_mfma_f32_16x16x32_bf16 v[36:39], v[148:151], v[200:203], v[36:39]
	v_mfma_f32_16x16x32_bf16 v[32:35], v[172:175], v[200:203], v[32:35]
	v_mfma_f32_16x16x32_bf16 v[20:23], v[148:151], v[208:211], v[20:23]
	v_mfma_f32_16x16x32_bf16 v[16:19], v[172:175], v[208:211], v[16:19]
	v_mfma_f32_16x16x32_bf16 v[4:7], v[148:151], v[216:219], v[4:7]
	v_mfma_f32_16x16x32_bf16 v[0:3], v[172:175], v[216:219], v[0:3]
	s_barrier
	s_add_i32 s58, s58, 2
	s_add_u32 s56, s56, 0x100
	s_addc_u32 s57, s57, 0
	s_add_u32 s30, s30, 0x100
	s_addc_u32 s31, s31, 0
	s_cmp_gt_u32 s58, 61
	s_cbranch_scc0 .LBB0_451
	s_setprio 0
	s_and_b64 vcc, exec, s[16:17]
	s_cbranch_vccz .LBB0_454
	s_barrier

.Lsp_skip4:
.LBB0_550:
	ds_read_b128 v[144:147], v161
	ds_read_b128 v[148:151], v161 offset:1024
	ds_read_b128 v[170:173], v161 offset:2048
	ds_read_b128 v[174:177], v161 offset:3072
	ds_read_b128 v[178:181], v163
	ds_read_b128 v[182:185], v163 offset:1024
	ds_read_b128 v[186:189], v163 offset:2048
	ds_read_b128 v[190:193], v163 offset:3072
	ds_read_b128 v[194:197], v166
	ds_read_b128 v[198:201], v166 offset:1024
	ds_read_b128 v[202:205], v166 offset:2048
	ds_read_b128 v[206:209], v166 offset:3072
	ds_read_b128 v[210:213], v166 offset:4096
	ds_read_b128 v[214:217], v166 offset:5120
	ds_read_b128 v[218:221], v166 offset:6144
	ds_read_b128 v[222:225], v166 offset:7168
	s_add_u32 s6, s4, 0xfff80080
	s_addc_u32 s7, s5, -1
	s_cmp_eq_u32 s64, 28
	s_cselect_b32 s39, s1, s7
	s_cselect_b32 s38, s31, s6
	s_cselect_b32 s7, s29, s63
	s_cselect_b32 s6, s61, s62
	v_lshl_add_u64 v[152:153], s[4:5], 0, v[138:139]
	s_add_i32 m0, s45, 0xc000
	s_nop 0
	global_load_lds_dwordx4 v[152:153], off
	v_lshl_add_u64 v[152:153], s[4:5], 0, v[136:137]
	s_add_i32 m0, s45, 0xe000
	s_nop 0
	global_load_lds_dwordx4 v[152:153], off
	s_waitcnt vmcnt(8) lgkmcnt(0)
	s_barrier
	v_mfma_i32_16x16x64_i8 v[124:127], v[144:147], v[194:197], v[124:127]
	v_mfma_i32_16x16x64_i8 v[120:123], v[170:173], v[194:197], v[120:123]
	v_mfma_i32_16x16x64_i8 v[108:111], v[144:147], v[202:205], v[108:111]
	v_mfma_i32_16x16x64_i8 v[104:107], v[170:173], v[202:205], v[104:107]
	v_mfma_i32_16x16x64_i8 v[92:95], v[144:147], v[210:213], v[92:95]
	v_mfma_i32_16x16x64_i8 v[88:91], v[170:173], v[210:213], v[88:91]
	v_mfma_i32_16x16x64_i8 v[76:79], v[144:147], v[218:221], v[76:79]
	v_mfma_i32_16x16x64_i8 v[72:75], v[170:173], v[218:221], v[72:75]
	v_mfma_i32_16x16x64_i8 v[124:127], v[148:151], v[198:201], v[124:127]
	v_mfma_i32_16x16x64_i8 v[120:123], v[174:177], v[198:201], v[120:123]
	v_mfma_i32_16x16x64_i8 v[108:111], v[148:151], v[206:209], v[108:111]
	v_mfma_i32_16x16x64_i8 v[104:107], v[174:177], v[206:209], v[104:107]
	v_mfma_i32_16x16x64_i8 v[92:95], v[148:151], v[214:217], v[92:95]
	v_mfma_i32_16x16x64_i8 v[88:91], v[174:177], v[214:217], v[88:91]
	v_mfma_i32_16x16x64_i8 v[76:79], v[148:151], v[222:225], v[76:79]
	v_mfma_i32_16x16x64_i8 v[72:75], v[174:177], v[222:225], v[72:75]
	v_mfma_i32_16x16x64_i8 v[116:119], v[178:181], v[194:197], v[116:119]
	v_mfma_i32_16x16x64_i8 v[112:115], v[186:189], v[194:197], v[112:115]
	v_mfma_i32_16x16x64_i8 v[100:103], v[178:181], v[202:205], v[100:103]
	v_mfma_i32_16x16x64_i8 v[96:99], v[186:189], v[202:205], v[96:99]
	v_mfma_i32_16x16x64_i8 v[84:87], v[178:181], v[210:213], v[84:87]
	v_mfma_i32_16x16x64_i8 v[80:83], v[186:189], v[210:213], v[80:83]
	v_mfma_i32_16x16x64_i8 v[68:71], v[178:181], v[218:221], v[68:71]
	v_mfma_i32_16x16x64_i8 v[64:67], v[186:189], v[218:221], v[64:67]
	v_mfma_i32_16x16x64_i8 v[116:119], v[182:185], v[198:201], v[116:119]
	v_mfma_i32_16x16x64_i8 v[112:115], v[190:193], v[198:201], v[112:115]
	v_mfma_i32_16x16x64_i8 v[100:103], v[182:185], v[206:209], v[100:103]
	v_mfma_i32_16x16x64_i8 v[96:99], v[190:193], v[206:209], v[96:99]
	v_mfma_i32_16x16x64_i8 v[84:87], v[182:185], v[214:217], v[84:87]
	v_mfma_i32_16x16x64_i8 v[80:83], v[190:193], v[214:217], v[80:83]
	v_mfma_i32_16x16x64_i8 v[68:71], v[182:185], v[222:225], v[68:71]
	v_mfma_i32_16x16x64_i8 v[64:67], v[190:193], v[222:225], v[64:67]
	s_barrier
	ds_read_b128 v[194:197], v166 offset:16384
	ds_read_b128 v[198:201], v166 offset:17408
	ds_read_b128 v[202:205], v166 offset:18432
	ds_read_b128 v[206:209], v166 offset:19456
	ds_read_b128 v[210:213], v166 offset:20480
	ds_read_b128 v[214:217], v166 offset:21504
	ds_read_b128 v[218:221], v166 offset:22528
	ds_read_b128 v[222:225], v166 offset:23552
	s_add_i32 s65, s53, s44
	v_lshl_add_u64 v[152:153], s[6:7], 0, v[130:131]
	s_mov_b32 m0, s65
	s_nop 0
	global_load_lds_dwordx4 v[152:153], off
	s_add_i32 m0, s65, 0x2000
	s_add_u32 s66, s6, 0x80000
	v_lshl_add_u64 v[164:165], s[6:7], 0, v[134:135]
	s_addc_u32 s67, s7, 0
	s_add_i32 s65, s54, s44
	global_load_lds_dwordx4 v[164:165], off
	v_lshl_add_u64 v[226:227], s[66:67], 0, v[130:131]
	s_mov_b32 m0, s65
	v_lshl_add_u64 v[228:229], s[38:39], 0, v[132:133]
	global_load_lds_dwordx4 v[226:227], off
	v_lshl_add_u64 v[226:227], s[66:67], 0, v[134:135]
	s_add_i32 m0, s65, 0x2000
	s_nop 0
	global_load_lds_dwordx4 v[226:227], off
	v_lshl_add_u64 v[226:227], s[38:39], 0, v[128:129]
	s_mov_b32 m0, s45
	s_nop 0
	global_load_lds_dwordx4 v[226:227], off
	s_mov_b32 m0, s46
	s_nop 0
	global_load_lds_dwordx4 v[228:229], off
	s_waitcnt vmcnt(8) lgkmcnt(0)
	s_barrier
	v_mfma_i32_16x16x64_i8 v[60:63], v[144:147], v[194:197], v[60:63]
	v_mfma_i32_16x16x64_i8 v[56:59], v[170:173], v[194:197], v[56:59]
	v_mfma_i32_16x16x64_i8 v[44:47], v[144:147], v[202:205], v[44:47]
	v_mfma_i32_16x16x64_i8 v[40:43], v[170:173], v[202:205], v[40:43]
	v_mfma_i32_16x16x64_i8 v[28:31], v[144:147], v[210:213], v[28:31]
	v_mfma_i32_16x16x64_i8 v[24:27], v[170:173], v[210:213], v[24:27]
	v_mfma_i32_16x16x64_i8 v[12:15], v[144:147], v[218:221], v[12:15]
	v_mfma_i32_16x16x64_i8 v[8:11], v[170:173], v[218:221], v[8:11]
	v_mfma_i32_16x16x64_i8 v[60:63], v[148:151], v[198:201], v[60:63]
	v_mfma_i32_16x16x64_i8 v[56:59], v[174:177], v[198:201], v[56:59]
	v_mfma_i32_16x16x64_i8 v[44:47], v[148:151], v[206:209], v[44:47]
	v_mfma_i32_16x16x64_i8 v[40:43], v[174:177], v[206:209], v[40:43]
	v_mfma_i32_16x16x64_i8 v[28:31], v[148:151], v[214:217], v[28:31]
	v_mfma_i32_16x16x64_i8 v[24:27], v[174:177], v[214:217], v[24:27]
	v_mfma_i32_16x16x64_i8 v[12:15], v[148:151], v[222:225], v[12:15]
	v_mfma_i32_16x16x64_i8 v[8:11], v[174:177], v[222:225], v[8:11]
	v_mfma_i32_16x16x64_i8 v[52:55], v[178:181], v[194:197], v[52:55]
	v_mfma_i32_16x16x64_i8 v[48:51], v[186:189], v[194:197], v[48:51]
	v_mfma_i32_16x16x64_i8 v[36:39], v[178:181], v[202:205], v[36:39]
	v_mfma_i32_16x16x64_i8 v[32:35], v[186:189], v[202:205], v[32:35]
	v_mfma_i32_16x16x64_i8 v[20:23], v[178:181], v[210:213], v[20:23]
	v_mfma_i32_16x16x64_i8 v[16:19], v[186:189], v[210:213], v[16:19]
	v_mfma_i32_16x16x64_i8 v[4:7], v[178:181], v[218:221], v[4:7]
	v_mfma_i32_16x16x64_i8 v[0:3], v[186:189], v[218:221], v[0:3]
	v_mfma_i32_16x16x64_i8 v[52:55], v[182:185], v[198:201], v[52:55]
	v_mfma_i32_16x16x64_i8 v[48:51], v[190:193], v[198:201], v[48:51]
	v_mfma_i32_16x16x64_i8 v[36:39], v[182:185], v[206:209], v[36:39]
	v_mfma_i32_16x16x64_i8 v[32:35], v[190:193], v[206:209], v[32:35]
	v_mfma_i32_16x16x64_i8 v[20:23], v[182:185], v[214:217], v[20:23]
	v_mfma_i32_16x16x64_i8 v[16:19], v[190:193], v[214:217], v[16:19]
	v_mfma_i32_16x16x64_i8 v[4:7], v[182:185], v[222:225], v[4:7]
	v_mfma_i32_16x16x64_i8 v[0:3], v[190:193], v[222:225], v[0:3]
	s_barrier
	ds_read_b128 v[194:197], v166 offset:32768
	ds_read_b128 v[198:201], v166 offset:33792
	ds_read_b128 v[202:205], v166 offset:34816
	ds_read_b128 v[206:209], v166 offset:35840
	ds_read_b128 v[210:213], v166 offset:36864
	ds_read_b128 v[214:217], v166 offset:37888
	ds_read_b128 v[218:221], v166 offset:38912
	ds_read_b128 v[222:225], v166 offset:39936
	s_add_i32 s65, 0, 0x18000
	v_add_u32_e32 v154, s65, v157
	s_add_i32 s66, 0, 0x1c000
	ds_read_b128 v[144:147], v154
	ds_read_b128 v[148:151], v154 offset:1024
	ds_read_b128 v[170:173], v154 offset:2048
	ds_read_b128 v[174:177], v154 offset:3072
	v_add_u32_e32 v154, s66, v157
	ds_read_b128 v[178:181], v154
	ds_read_b128 v[182:185], v154 offset:1024
	ds_read_b128 v[186:189], v154 offset:2048
	ds_read_b128 v[190:193], v154 offset:3072
	s_add_u32 s38, s38, 0x80000
	s_addc_u32 s39, s39, 0
	s_mov_b32 m0, s47
	v_lshl_add_u64 v[230:231], s[38:39], 0, v[128:129]
	global_load_lds_dwordx4 v[230:231], off
	v_lshl_add_u64 v[230:231], s[38:39], 0, v[132:133]
	s_mov_b32 m0, s48
	s_nop 0
	global_load_lds_dwordx4 v[230:231], off
	s_waitcnt vmcnt(8) lgkmcnt(0)
	s_barrier
	v_mfma_i32_16x16x64_i8 v[124:127], v[144:147], v[194:197], v[124:127]
	v_mfma_i32_16x16x64_i8 v[120:123], v[170:173], v[194:197], v[120:123]
	v_mfma_i32_16x16x64_i8 v[108:111], v[144:147], v[202:205], v[108:111]
	v_mfma_i32_16x16x64_i8 v[104:107], v[170:173], v[202:205], v[104:107]
	v_mfma_i32_16x16x64_i8 v[92:95], v[144:147], v[210:213], v[92:95]
	v_mfma_i32_16x16x64_i8 v[88:91], v[170:173], v[210:213], v[88:91]
	v_mfma_i32_16x16x64_i8 v[76:79], v[144:147], v[218:221], v[76:79]
	v_mfma_i32_16x16x64_i8 v[72:75], v[170:173], v[218:221], v[72:75]
	v_mfma_i32_16x16x64_i8 v[124:127], v[148:151], v[198:201], v[124:127]
	v_mfma_i32_16x16x64_i8 v[120:123], v[174:177], v[198:201], v[120:123]
	v_mfma_i32_16x16x64_i8 v[108:111], v[148:151], v[206:209], v[108:111]
	v_mfma_i32_16x16x64_i8 v[104:107], v[174:177], v[206:209], v[104:107]
	v_mfma_i32_16x16x64_i8 v[92:95], v[148:151], v[214:217], v[92:95]
	v_mfma_i32_16x16x64_i8 v[88:91], v[174:177], v[214:217], v[88:91]
	v_mfma_i32_16x16x64_i8 v[76:79], v[148:151], v[222:225], v[76:79]
	v_mfma_i32_16x16x64_i8 v[72:75], v[174:177], v[222:225], v[72:75]
	v_mfma_i32_16x16x64_i8 v[116:119], v[178:181], v[194:197], v[116:119]
	v_mfma_i32_16x16x64_i8 v[112:115], v[186:189], v[194:197], v[112:115]
	v_mfma_i32_16x16x64_i8 v[100:103], v[178:181], v[202:205], v[100:103]
	v_mfma_i32_16x16x64_i8 v[96:99], v[186:189], v[202:205], v[96:99]
	v_mfma_i32_16x16x64_i8 v[84:87], v[178:181], v[210:213], v[84:87]
	v_mfma_i32_16x16x64_i8 v[80:83], v[186:189], v[210:213], v[80:83]
	v_mfma_i32_16x16x64_i8 v[68:71], v[178:181], v[218:221], v[68:71]
	v_mfma_i32_16x16x64_i8 v[64:67], v[186:189], v[218:221], v[64:67]
	v_mfma_i32_16x16x64_i8 v[116:119], v[182:185], v[198:201], v[116:119]
	v_mfma_i32_16x16x64_i8 v[112:115], v[190:193], v[198:201], v[112:115]
	v_mfma_i32_16x16x64_i8 v[100:103], v[182:185], v[206:209], v[100:103]
	v_mfma_i32_16x16x64_i8 v[96:99], v[190:193], v[206:209], v[96:99]
	v_mfma_i32_16x16x64_i8 v[84:87], v[182:185], v[214:217], v[84:87]
	v_mfma_i32_16x16x64_i8 v[80:83], v[190:193], v[214:217], v[80:83]
	v_mfma_i32_16x16x64_i8 v[68:71], v[182:185], v[222:225], v[68:71]
	v_mfma_i32_16x16x64_i8 v[64:67], v[190:193], v[222:225], v[64:67]
	s_barrier
	ds_read_b128 v[194:197], v166 offset:49152
	ds_read_b128 v[198:201], v166 offset:50176
	ds_read_b128 v[202:205], v166 offset:51200
	ds_read_b128 v[206:209], v166 offset:52224
	ds_read_b128 v[210:213], v166 offset:53248
	ds_read_b128 v[214:217], v166 offset:54272
	ds_read_b128 v[218:221], v166 offset:55296
	ds_read_b128 v[222:225], v166 offset:56320
	s_add_i32 s38, s65, s44
	v_lshl_add_u64 v[152:153], v[152:153], 0, s[16:17]
	s_mov_b32 m0, s38
	s_nop 0
	global_load_lds_dwordx4 v[152:153], off
	s_add_i32 m0, s38, 0x2000
	s_add_u32 s6, s6, 0x80080
	v_lshl_add_u64 v[152:153], v[164:165], 0, s[16:17]
	s_addc_u32 s7, s7, 0
	s_add_i32 s38, s66, s44
	global_load_lds_dwordx4 v[152:153], off
	v_lshl_add_u64 v[152:153], s[6:7], 0, v[130:131]
	s_mov_b32 m0, s38
	s_nop 0
	global_load_lds_dwordx4 v[152:153], off
	v_lshl_add_u64 v[152:153], s[6:7], 0, v[134:135]
	s_add_i32 m0, s38, 0x2000
	s_nop 0
	global_load_lds_dwordx4 v[152:153], off
	v_lshl_add_u64 v[152:153], v[226:227], 0, s[16:17]
	s_mov_b32 m0, s50
	s_nop 0
	global_load_lds_dwordx4 v[152:153], off
	v_lshl_add_u64 v[152:153], v[228:229], 0, s[16:17]
	s_mov_b32 m0, s51
	s_nop 0
	global_load_lds_dwordx4 v[152:153], off
	s_waitcnt vmcnt(8) lgkmcnt(0)
	s_barrier
	v_mfma_i32_16x16x64_i8 v[60:63], v[144:147], v[194:197], v[60:63]
	v_mfma_i32_16x16x64_i8 v[56:59], v[170:173], v[194:197], v[56:59]
	v_mfma_i32_16x16x64_i8 v[44:47], v[144:147], v[202:205], v[44:47]
	v_mfma_i32_16x16x64_i8 v[40:43], v[170:173], v[202:205], v[40:43]
	v_mfma_i32_16x16x64_i8 v[28:31], v[144:147], v[210:213], v[28:31]
	v_mfma_i32_16x16x64_i8 v[24:27], v[170:173], v[210:213], v[24:27]
	v_mfma_i32_16x16x64_i8 v[12:15], v[144:147], v[218:221], v[12:15]
	v_mfma_i32_16x16x64_i8 v[8:11], v[170:173], v[218:221], v[8:11]
	v_mfma_i32_16x16x64_i8 v[60:63], v[148:151], v[198:201], v[60:63]
	v_mfma_i32_16x16x64_i8 v[56:59], v[174:177], v[198:201], v[56:59]
	v_mfma_i32_16x16x64_i8 v[44:47], v[148:151], v[206:209], v[44:47]
	v_mfma_i32_16x16x64_i8 v[40:43], v[174:177], v[206:209], v[40:43]
	v_mfma_i32_16x16x64_i8 v[28:31], v[148:151], v[214:217], v[28:31]
	v_mfma_i32_16x16x64_i8 v[24:27], v[174:177], v[214:217], v[24:27]
	v_mfma_i32_16x16x64_i8 v[12:15], v[148:151], v[222:225], v[12:15]
	v_mfma_i32_16x16x64_i8 v[8:11], v[174:177], v[222:225], v[8:11]
	v_mfma_i32_16x16x64_i8 v[52:55], v[178:181], v[194:197], v[52:55]
	v_mfma_i32_16x16x64_i8 v[48:51], v[186:189], v[194:197], v[48:51]
	v_mfma_i32_16x16x64_i8 v[36:39], v[178:181], v[202:205], v[36:39]
	v_mfma_i32_16x16x64_i8 v[32:35], v[186:189], v[202:205], v[32:35]
	v_mfma_i32_16x16x64_i8 v[20:23], v[178:181], v[210:213], v[20:23]
	v_mfma_i32_16x16x64_i8 v[16:19], v[186:189], v[210:213], v[16:19]
	v_mfma_i32_16x16x64_i8 v[4:7], v[178:181], v[218:221], v[4:7]
	v_mfma_i32_16x16x64_i8 v[0:3], v[186:189], v[218:221], v[0:3]
	v_mfma_i32_16x16x64_i8 v[52:55], v[182:185], v[198:201], v[52:55]
	v_mfma_i32_16x16x64_i8 v[48:51], v[190:193], v[198:201], v[48:51]
	v_mfma_i32_16x16x64_i8 v[36:39], v[182:185], v[206:209], v[36:39]
	v_mfma_i32_16x16x64_i8 v[32:35], v[190:193], v[206:209], v[32:35]
	v_mfma_i32_16x16x64_i8 v[20:23], v[182:185], v[214:217], v[20:23]
	v_mfma_i32_16x16x64_i8 v[16:19], v[190:193], v[214:217], v[16:19]
	v_mfma_i32_16x16x64_i8 v[4:7], v[182:185], v[222:225], v[4:7]
	v_mfma_i32_16x16x64_i8 v[0:3], v[190:193], v[222:225], v[0:3]
	s_barrier
	s_add_i32 s64, s64, 2
	s_add_u32 s62, s62, 0x100
	s_addc_u32 s63, s63, 0
	s_add_u32 s4, s4, 0x100
	s_addc_u32 s5, s5, 0
	s_cmp_gt_u32 s64, 29
	s_cbranch_scc0 .LBB0_550
	s_setprio 0
	s_and_b64 vcc, exec, s[18:19]
	s_cbranch_vccz .LBB0_553
	s_barrier

.Lsp_skip5:
.LBB0_635:
	ds_read_b128 v[112:115], v193
	ds_read_b128 v[124:127], v193 offset:1024
	ds_read_b128 v[136:139], v193 offset:2048
	ds_read_b128 v[140:143], v193 offset:3072
	ds_read_b128 v[144:147], v194
	ds_read_b128 v[148:151], v194 offset:1024
	ds_read_b128 v[168:171], v194 offset:2048
	ds_read_b128 v[172:175], v194 offset:3072
	ds_read_b128 v[176:179], v195
	ds_read_b128 v[180:183], v195 offset:1024
	ds_read_b128 v[184:187], v195 offset:2048
	ds_read_b128 v[200:203], v195 offset:3072
	ds_read_b128 v[204:207], v195 offset:4096
	ds_read_b128 v[208:211], v195 offset:5120
	ds_read_b128 v[212:215], v195 offset:6144
	ds_read_b128 v[216:219], v195 offset:7168
	s_add_u32 s34, s30, 0xffbf8080
	s_addc_u32 s35, s31, -1
	s_cmpk_eq_i32 s58, 0xfc
	s_cselect_b32 s37, s21, s35
	s_cselect_b32 s36, s27, s34
	s_cselect_b32 s35, s19, s57
	s_cselect_b32 s34, s55, s56
	v_lshl_add_u64 v[188:189], s[30:31], 0, v[162:163]
	s_add_i32 m0, s29, 0xc000
	s_nop 0
	global_load_lds_dwordx4 v[188:189], off
	v_lshl_add_u64 v[188:189], s[30:31], 0, v[160:161]
	s_add_i32 m0, s29, 0xe000
	s_nop 0
	global_load_lds_dwordx4 v[188:189], off
	s_waitcnt vmcnt(8) lgkmcnt(0)
	s_barrier
	v_mfma_f32_16x16x32_bf16 v[132:135], v[112:115], v[176:179], v[132:135]
	v_mfma_f32_16x16x32_bf16 v[128:131], v[136:139], v[176:179], v[128:131]
	v_mfma_f32_16x16x32_bf16 v[108:111], v[112:115], v[184:187], v[108:111]
	v_mfma_f32_16x16x32_bf16 v[104:107], v[136:139], v[184:187], v[104:107]
	v_mfma_f32_16x16x32_bf16 v[92:95], v[112:115], v[204:207], v[92:95]
	v_mfma_f32_16x16x32_bf16 v[88:91], v[136:139], v[204:207], v[88:91]
	v_mfma_f32_16x16x32_bf16 v[76:79], v[112:115], v[212:215], v[76:79]
	v_mfma_f32_16x16x32_bf16 v[72:75], v[136:139], v[212:215], v[72:75]
	v_mfma_f32_16x16x32_bf16 v[132:135], v[124:127], v[180:183], v[132:135]
	v_mfma_f32_16x16x32_bf16 v[128:131], v[140:143], v[180:183], v[128:131]
	v_mfma_f32_16x16x32_bf16 v[108:111], v[124:127], v[200:203], v[108:111]
	v_mfma_f32_16x16x32_bf16 v[104:107], v[140:143], v[200:203], v[104:107]
	v_mfma_f32_16x16x32_bf16 v[92:95], v[124:127], v[208:211], v[92:95]
	v_mfma_f32_16x16x32_bf16 v[88:91], v[140:143], v[208:211], v[88:91]
	v_mfma_f32_16x16x32_bf16 v[76:79], v[124:127], v[216:219], v[76:79]
	v_mfma_f32_16x16x32_bf16 v[72:75], v[140:143], v[216:219], v[72:75]
	v_mfma_f32_16x16x32_bf16 v[120:123], v[144:147], v[176:179], v[120:123]
	v_mfma_f32_16x16x32_bf16 v[116:119], v[168:171], v[176:179], v[116:119]
	v_mfma_f32_16x16x32_bf16 v[100:103], v[144:147], v[184:187], v[100:103]
	v_mfma_f32_16x16x32_bf16 v[96:99], v[168:171], v[184:187], v[96:99]
	v_mfma_f32_16x16x32_bf16 v[84:87], v[144:147], v[204:207], v[84:87]
	v_mfma_f32_16x16x32_bf16 v[80:83], v[168:171], v[204:207], v[80:83]
	v_mfma_f32_16x16x32_bf16 v[68:71], v[144:147], v[212:215], v[68:71]
	v_mfma_f32_16x16x32_bf16 v[64:67], v[168:171], v[212:215], v[64:67]
	v_mfma_f32_16x16x32_bf16 v[120:123], v[148:151], v[180:183], v[120:123]
	v_mfma_f32_16x16x32_bf16 v[116:119], v[172:175], v[180:183], v[116:119]
	v_mfma_f32_16x16x32_bf16 v[100:103], v[148:151], v[200:203], v[100:103]
	v_mfma_f32_16x16x32_bf16 v[96:99], v[172:175], v[200:203], v[96:99]
	v_mfma_f32_16x16x32_bf16 v[84:87], v[148:151], v[208:211], v[84:87]
	v_mfma_f32_16x16x32_bf16 v[80:83], v[172:175], v[208:211], v[80:83]
	v_mfma_f32_16x16x32_bf16 v[68:71], v[148:151], v[216:219], v[68:71]
	v_mfma_f32_16x16x32_bf16 v[64:67], v[172:175], v[216:219], v[64:67]
	s_barrier
	ds_read_b128 v[176:179], v195 offset:16384
	ds_read_b128 v[180:183], v195 offset:17408
	ds_read_b128 v[184:187], v195 offset:18432
	ds_read_b128 v[200:203], v195 offset:19456
	ds_read_b128 v[204:207], v195 offset:20480
	ds_read_b128 v[208:211], v195 offset:21504
	ds_read_b128 v[212:215], v195 offset:22528
	ds_read_b128 v[216:219], v195 offset:23552
	s_add_i32 s59, s50, s41
	v_lshl_add_u64 v[188:189], s[34:35], 0, v[154:155]
	s_mov_b32 m0, s59
	s_nop 0
	global_load_lds_dwordx4 v[188:189], off
	s_add_i32 m0, s59, 0x2000
	s_add_u32 s60, s34, 0x400000
	v_lshl_add_u64 v[220:221], s[34:35], 0, v[158:159]
	s_addc_u32 s61, s35, 0
	s_add_i32 s59, s51, s41
	global_load_lds_dwordx4 v[220:221], off
	v_lshl_add_u64 v[222:223], s[60:61], 0, v[154:155]
	s_mov_b32 m0, s59
	v_lshl_add_u64 v[224:225], s[36:37], 0, v[156:157]
	global_load_lds_dwordx4 v[222:223], off
	v_lshl_add_u64 v[222:223], s[60:61], 0, v[158:159]
	s_add_i32 m0, s59, 0x2000
	s_nop 0
	global_load_lds_dwordx4 v[222:223], off
	v_lshl_add_u64 v[222:223], s[36:37], 0, v[152:153]
	s_mov_b32 m0, s29
	s_nop 0
	global_load_lds_dwordx4 v[222:223], off
	s_mov_b32 m0, s42
	s_nop 0
	global_load_lds_dwordx4 v[224:225], off
	s_waitcnt vmcnt(8) lgkmcnt(0)
	s_barrier
	v_mfma_f32_16x16x32_bf16 v[60:63], v[112:115], v[176:179], v[60:63]
	v_mfma_f32_16x16x32_bf16 v[56:59], v[136:139], v[176:179], v[56:59]
	v_mfma_f32_16x16x32_bf16 v[44:47], v[112:115], v[184:187], v[44:47]
	v_mfma_f32_16x16x32_bf16 v[40:43], v[136:139], v[184:187], v[40:43]
	v_mfma_f32_16x16x32_bf16 v[28:31], v[112:115], v[204:207], v[28:31]
	v_mfma_f32_16x16x32_bf16 v[24:27], v[136:139], v[204:207], v[24:27]
	v_mfma_f32_16x16x32_bf16 v[12:15], v[112:115], v[212:215], v[12:15]
	v_mfma_f32_16x16x32_bf16 v[8:11], v[136:139], v[212:215], v[8:11]
	v_mfma_f32_16x16x32_bf16 v[60:63], v[124:127], v[180:183], v[60:63]
	v_mfma_f32_16x16x32_bf16 v[56:59], v[140:143], v[180:183], v[56:59]
	v_mfma_f32_16x16x32_bf16 v[44:47], v[124:127], v[200:203], v[44:47]
	v_mfma_f32_16x16x32_bf16 v[40:43], v[140:143], v[200:203], v[40:43]
	v_mfma_f32_16x16x32_bf16 v[28:31], v[124:127], v[208:211], v[28:31]
	v_mfma_f32_16x16x32_bf16 v[24:27], v[140:143], v[208:211], v[24:27]
	v_mfma_f32_16x16x32_bf16 v[12:15], v[124:127], v[216:219], v[12:15]
	v_mfma_f32_16x16x32_bf16 v[8:11], v[140:143], v[216:219], v[8:11]
	v_mfma_f32_16x16x32_bf16 v[52:55], v[144:147], v[176:179], v[52:55]
	v_mfma_f32_16x16x32_bf16 v[48:51], v[168:171], v[176:179], v[48:51]
	v_mfma_f32_16x16x32_bf16 v[36:39], v[144:147], v[184:187], v[36:39]
	v_mfma_f32_16x16x32_bf16 v[32:35], v[168:171], v[184:187], v[32:35]
	v_mfma_f32_16x16x32_bf16 v[20:23], v[144:147], v[204:207], v[20:23]
	v_mfma_f32_16x16x32_bf16 v[16:19], v[168:171], v[204:207], v[16:19]
	v_mfma_f32_16x16x32_bf16 v[4:7], v[144:147], v[212:215], v[4:7]
	v_mfma_f32_16x16x32_bf16 v[0:3], v[168:171], v[212:215], v[0:3]
	v_mfma_f32_16x16x32_bf16 v[52:55], v[148:151], v[180:183], v[52:55]
	v_mfma_f32_16x16x32_bf16 v[48:51], v[172:175], v[180:183], v[48:51]
	v_mfma_f32_16x16x32_bf16 v[36:39], v[148:151], v[200:203], v[36:39]
	v_mfma_f32_16x16x32_bf16 v[32:35], v[172:175], v[200:203], v[32:35]
	v_mfma_f32_16x16x32_bf16 v[20:23], v[148:151], v[208:211], v[20:23]
	v_mfma_f32_16x16x32_bf16 v[16:19], v[172:175], v[208:211], v[16:19]
	v_mfma_f32_16x16x32_bf16 v[4:7], v[148:151], v[216:219], v[4:7]
	v_mfma_f32_16x16x32_bf16 v[0:3], v[172:175], v[216:219], v[0:3]
	s_barrier
	ds_read_b128 v[176:179], v195 offset:32768
	ds_read_b128 v[180:183], v195 offset:33792
	ds_read_b128 v[184:187], v195 offset:34816
	ds_read_b128 v[200:203], v195 offset:35840
	ds_read_b128 v[204:207], v195 offset:36864
	ds_read_b128 v[208:211], v195 offset:37888
	ds_read_b128 v[212:215], v195 offset:38912
	ds_read_b128 v[216:219], v195 offset:39936
	s_add_i32 s59, 0, 0x18000
	s_add_i32 s60, 0, 0x1c000
	v_add_u32_e32 v140, s59, v191
	v_add_u32_e32 v172, s60, v191
	ds_read_b128 v[112:115], v140
	ds_read_b128 v[124:127], v140 offset:1024
	ds_read_b128 v[136:139], v140 offset:2048
	ds_read_b128 v[140:143], v140 offset:3072
	ds_read_b128 v[144:147], v172
	ds_read_b128 v[148:151], v172 offset:1024
	ds_read_b128 v[168:171], v172 offset:2048
	ds_read_b128 v[172:175], v172 offset:3072
	s_add_u32 s36, s36, 0x408000
	s_addc_u32 s37, s37, 0
	s_mov_b32 m0, s43
	v_lshl_add_u64 v[226:227], s[36:37], 0, v[152:153]
	global_load_lds_dwordx4 v[226:227], off
	v_lshl_add_u64 v[226:227], s[36:37], 0, v[156:157]
	s_mov_b32 m0, s44
	s_nop 0
	global_load_lds_dwordx4 v[226:227], off
	s_waitcnt vmcnt(8) lgkmcnt(0)
	s_barrier
	v_mfma_f32_16x16x32_bf16 v[132:135], v[112:115], v[176:179], v[132:135]
	v_mfma_f32_16x16x32_bf16 v[128:131], v[136:139], v[176:179], v[128:131]
	v_mfma_f32_16x16x32_bf16 v[108:111], v[112:115], v[184:187], v[108:111]
	v_mfma_f32_16x16x32_bf16 v[104:107], v[136:139], v[184:187], v[104:107]
	v_mfma_f32_16x16x32_bf16 v[92:95], v[112:115], v[204:207], v[92:95]
	v_mfma_f32_16x16x32_bf16 v[88:91], v[136:139], v[204:207], v[88:91]
	v_mfma_f32_16x16x32_bf16 v[76:79], v[112:115], v[212:215], v[76:79]
	v_mfma_f32_16x16x32_bf16 v[72:75], v[136:139], v[212:215], v[72:75]
	v_mfma_f32_16x16x32_bf16 v[132:135], v[124:127], v[180:183], v[132:135]
	v_mfma_f32_16x16x32_bf16 v[128:131], v[140:143], v[180:183], v[128:131]
	v_mfma_f32_16x16x32_bf16 v[108:111], v[124:127], v[200:203], v[108:111]
	v_mfma_f32_16x16x32_bf16 v[104:107], v[140:143], v[200:203], v[104:107]
	v_mfma_f32_16x16x32_bf16 v[92:95], v[124:127], v[208:211], v[92:95]
	v_mfma_f32_16x16x32_bf16 v[88:91], v[140:143], v[208:211], v[88:91]
	v_mfma_f32_16x16x32_bf16 v[76:79], v[124:127], v[216:219], v[76:79]
	v_mfma_f32_16x16x32_bf16 v[72:75], v[140:143], v[216:219], v[72:75]
	v_mfma_f32_16x16x32_bf16 v[120:123], v[144:147], v[176:179], v[120:123]
	v_mfma_f32_16x16x32_bf16 v[116:119], v[168:171], v[176:179], v[116:119]
	v_mfma_f32_16x16x32_bf16 v[100:103], v[144:147], v[184:187], v[100:103]
	v_mfma_f32_16x16x32_bf16 v[96:99], v[168:171], v[184:187], v[96:99]
	v_mfma_f32_16x16x32_bf16 v[84:87], v[144:147], v[204:207], v[84:87]
	v_mfma_f32_16x16x32_bf16 v[80:83], v[168:171], v[204:207], v[80:83]
	v_mfma_f32_16x16x32_bf16 v[68:71], v[144:147], v[212:215], v[68:71]
	v_mfma_f32_16x16x32_bf16 v[64:67], v[168:171], v[212:215], v[64:67]
	v_mfma_f32_16x16x32_bf16 v[120:123], v[148:151], v[180:183], v[120:123]
	v_mfma_f32_16x16x32_bf16 v[116:119], v[172:175], v[180:183], v[116:119]
	v_mfma_f32_16x16x32_bf16 v[100:103], v[148:151], v[200:203], v[100:103]
	v_mfma_f32_16x16x32_bf16 v[96:99], v[172:175], v[200:203], v[96:99]
	v_mfma_f32_16x16x32_bf16 v[84:87], v[148:151], v[208:211], v[84:87]
	v_mfma_f32_16x16x32_bf16 v[80:83], v[172:175], v[208:211], v[80:83]
	v_mfma_f32_16x16x32_bf16 v[68:71], v[148:151], v[216:219], v[68:71]
	v_mfma_f32_16x16x32_bf16 v[64:67], v[172:175], v[216:219], v[64:67]
	s_barrier
	ds_read_b128 v[176:179], v195 offset:49152
	ds_read_b128 v[180:183], v195 offset:50176
	ds_read_b128 v[184:187], v195 offset:51200
	ds_read_b128 v[200:203], v195 offset:52224
	ds_read_b128 v[204:207], v195 offset:53248
	ds_read_b128 v[208:211], v195 offset:54272
	ds_read_b128 v[212:215], v195 offset:55296
	ds_read_b128 v[216:219], v195 offset:56320
	s_add_i32 s36, s59, s41
	v_lshl_add_u64 v[188:189], v[188:189], 0, s[14:15]
	s_mov_b32 m0, s36
	s_nop 0
	global_load_lds_dwordx4 v[188:189], off
	s_add_i32 m0, s36, 0x2000
	s_add_u32 s34, s34, 0x400080
	v_lshl_add_u64 v[188:189], v[220:221], 0, s[14:15]
	s_addc_u32 s35, s35, 0
	s_add_i32 s36, s60, s41
	global_load_lds_dwordx4 v[188:189], off
	v_lshl_add_u64 v[188:189], s[34:35], 0, v[154:155]
	s_mov_b32 m0, s36
	s_nop 0
	global_load_lds_dwordx4 v[188:189], off
	v_lshl_add_u64 v[188:189], s[34:35], 0, v[158:159]
	s_add_i32 m0, s36, 0x2000
	s_nop 0
	global_load_lds_dwordx4 v[188:189], off
	v_lshl_add_u64 v[188:189], v[222:223], 0, s[14:15]
	s_mov_b32 m0, s46
	s_nop 0
	global_load_lds_dwordx4 v[188:189], off
	v_lshl_add_u64 v[188:189], v[224:225], 0, s[14:15]
	s_mov_b32 m0, s47
	s_nop 0
	global_load_lds_dwordx4 v[188:189], off
	s_waitcnt vmcnt(8) lgkmcnt(0)
	s_barrier
	v_mfma_f32_16x16x32_bf16 v[60:63], v[112:115], v[176:179], v[60:63]
	v_mfma_f32_16x16x32_bf16 v[56:59], v[136:139], v[176:179], v[56:59]
	v_mfma_f32_16x16x32_bf16 v[44:47], v[112:115], v[184:187], v[44:47]
	v_mfma_f32_16x16x32_bf16 v[40:43], v[136:139], v[184:187], v[40:43]
	v_mfma_f32_16x16x32_bf16 v[28:31], v[112:115], v[204:207], v[28:31]
	v_mfma_f32_16x16x32_bf16 v[24:27], v[136:139], v[204:207], v[24:27]
	v_mfma_f32_16x16x32_bf16 v[12:15], v[112:115], v[212:215], v[12:15]
	v_mfma_f32_16x16x32_bf16 v[8:11], v[136:139], v[212:215], v[8:11]
	v_mfma_f32_16x16x32_bf16 v[60:63], v[124:127], v[180:183], v[60:63]
	v_mfma_f32_16x16x32_bf16 v[56:59], v[140:143], v[180:183], v[56:59]
	v_mfma_f32_16x16x32_bf16 v[44:47], v[124:127], v[200:203], v[44:47]
	v_mfma_f32_16x16x32_bf16 v[40:43], v[140:143], v[200:203], v[40:43]
	v_mfma_f32_16x16x32_bf16 v[28:31], v[124:127], v[208:211], v[28:31]
	v_mfma_f32_16x16x32_bf16 v[24:27], v[140:143], v[208:211], v[24:27]
	v_mfma_f32_16x16x32_bf16 v[12:15], v[124:127], v[216:219], v[12:15]
	v_mfma_f32_16x16x32_bf16 v[8:11], v[140:143], v[216:219], v[8:11]
	v_mfma_f32_16x16x32_bf16 v[52:55], v[144:147], v[176:179], v[52:55]
	v_mfma_f32_16x16x32_bf16 v[48:51], v[168:171], v[176:179], v[48:51]
	v_mfma_f32_16x16x32_bf16 v[36:39], v[144:147], v[184:187], v[36:39]
	v_mfma_f32_16x16x32_bf16 v[32:35], v[168:171], v[184:187], v[32:35]
	v_mfma_f32_16x16x32_bf16 v[20:23], v[144:147], v[204:207], v[20:23]
	v_mfma_f32_16x16x32_bf16 v[16:19], v[168:171], v[204:207], v[16:19]
	v_mfma_f32_16x16x32_bf16 v[4:7], v[144:147], v[212:215], v[4:7]
	v_mfma_f32_16x16x32_bf16 v[0:3], v[168:171], v[212:215], v[0:3]
	v_mfma_f32_16x16x32_bf16 v[52:55], v[148:151], v[180:183], v[52:55]
	v_mfma_f32_16x16x32_bf16 v[48:51], v[172:175], v[180:183], v[48:51]
	v_mfma_f32_16x16x32_bf16 v[36:39], v[148:151], v[200:203], v[36:39]
	v_mfma_f32_16x16x32_bf16 v[32:35], v[172:175], v[200:203], v[32:35]
	v_mfma_f32_16x16x32_bf16 v[20:23], v[148:151], v[208:211], v[20:23]
	v_mfma_f32_16x16x32_bf16 v[16:19], v[172:175], v[208:211], v[16:19]
	v_mfma_f32_16x16x32_bf16 v[4:7], v[148:151], v[216:219], v[4:7]
	v_mfma_f32_16x16x32_bf16 v[0:3], v[172:175], v[216:219], v[0:3]
	s_barrier
	s_add_i32 s58, s58, 2
	s_add_u32 s56, s56, 0x100
	s_addc_u32 s57, s57, 0
	s_add_u32 s30, s30, 0x100
	s_addc_u32 s31, s31, 0
	s_cmpk_gt_u32 s58, 0xfd
	s_cbranch_scc0 .LBB0_635
	s_setprio 0
	s_and_b64 vcc, exec, s[16:17]
	s_cbranch_vccz .LBB0_638
	s_barrier

.Lsp_skip6:
.LBB0_726:
	ds_read_b128 v[144:147], v161
	ds_read_b128 v[148:151], v161 offset:1024
	ds_read_b128 v[168:171], v161 offset:2048
	ds_read_b128 v[172:175], v161 offset:3072
	ds_read_b128 v[176:179], v163
	ds_read_b128 v[180:183], v163 offset:1024
	ds_read_b128 v[184:187], v163 offset:2048
	ds_read_b128 v[188:191], v163 offset:3072
	ds_read_b128 v[192:195], v165
	ds_read_b128 v[196:199], v165 offset:1024
	ds_read_b128 v[200:203], v165 offset:2048
	ds_read_b128 v[204:207], v165 offset:3072
	ds_read_b128 v[208:211], v165 offset:4096
	ds_read_b128 v[212:215], v165 offset:5120
	ds_read_b128 v[216:219], v165 offset:6144
	ds_read_b128 v[220:223], v165 offset:7168
	s_add_u32 s6, s4, 0xfff80080
	s_addc_u32 s7, s5, -1
	s_cmp_eq_u32 s54, 28
	s_cselect_b32 s29, s1, s7
	s_cselect_b32 s28, s23, s6
	s_cselect_b32 s7, s21, s53
	s_cselect_b32 s6, s51, s52
	v_lshl_add_u64 v[152:153], s[4:5], 0, v[138:139]
	s_add_i32 m0, s38, 0xc000
	s_nop 0
	global_load_lds_dwordx4 v[152:153], off
	v_lshl_add_u64 v[152:153], s[4:5], 0, v[136:137]
	s_add_i32 m0, s38, 0xe000
	s_nop 0
	global_load_lds_dwordx4 v[152:153], off
	s_waitcnt vmcnt(8) lgkmcnt(0)
	s_barrier
	v_mfma_i32_16x16x64_i8 v[124:127], v[144:147], v[192:195], v[124:127]
	v_mfma_i32_16x16x64_i8 v[120:123], v[168:171], v[192:195], v[120:123]
	v_mfma_i32_16x16x64_i8 v[108:111], v[144:147], v[200:203], v[108:111]
	v_mfma_i32_16x16x64_i8 v[104:107], v[168:171], v[200:203], v[104:107]
	v_mfma_i32_16x16x64_i8 v[92:95], v[144:147], v[208:211], v[92:95]
	v_mfma_i32_16x16x64_i8 v[88:91], v[168:171], v[208:211], v[88:91]
	v_mfma_i32_16x16x64_i8 v[76:79], v[144:147], v[216:219], v[76:79]
	v_mfma_i32_16x16x64_i8 v[72:75], v[168:171], v[216:219], v[72:75]
	v_mfma_i32_16x16x64_i8 v[124:127], v[148:151], v[196:199], v[124:127]
	v_mfma_i32_16x16x64_i8 v[120:123], v[172:175], v[196:199], v[120:123]
	v_mfma_i32_16x16x64_i8 v[108:111], v[148:151], v[204:207], v[108:111]
	v_mfma_i32_16x16x64_i8 v[104:107], v[172:175], v[204:207], v[104:107]
	v_mfma_i32_16x16x64_i8 v[92:95], v[148:151], v[212:215], v[92:95]
	v_mfma_i32_16x16x64_i8 v[88:91], v[172:175], v[212:215], v[88:91]
	v_mfma_i32_16x16x64_i8 v[76:79], v[148:151], v[220:223], v[76:79]
	v_mfma_i32_16x16x64_i8 v[72:75], v[172:175], v[220:223], v[72:75]
	v_mfma_i32_16x16x64_i8 v[116:119], v[176:179], v[192:195], v[116:119]
	v_mfma_i32_16x16x64_i8 v[112:115], v[184:187], v[192:195], v[112:115]
	v_mfma_i32_16x16x64_i8 v[100:103], v[176:179], v[200:203], v[100:103]
	v_mfma_i32_16x16x64_i8 v[96:99], v[184:187], v[200:203], v[96:99]
	v_mfma_i32_16x16x64_i8 v[84:87], v[176:179], v[208:211], v[84:87]
	v_mfma_i32_16x16x64_i8 v[80:83], v[184:187], v[208:211], v[80:83]
	v_mfma_i32_16x16x64_i8 v[68:71], v[176:179], v[216:219], v[68:71]
	v_mfma_i32_16x16x64_i8 v[64:67], v[184:187], v[216:219], v[64:67]
	v_mfma_i32_16x16x64_i8 v[116:119], v[180:183], v[196:199], v[116:119]
	v_mfma_i32_16x16x64_i8 v[112:115], v[188:191], v[196:199], v[112:115]
	v_mfma_i32_16x16x64_i8 v[100:103], v[180:183], v[204:207], v[100:103]
	v_mfma_i32_16x16x64_i8 v[96:99], v[188:191], v[204:207], v[96:99]
	v_mfma_i32_16x16x64_i8 v[84:87], v[180:183], v[212:215], v[84:87]
	v_mfma_i32_16x16x64_i8 v[80:83], v[188:191], v[212:215], v[80:83]
	v_mfma_i32_16x16x64_i8 v[68:71], v[180:183], v[220:223], v[68:71]
	v_mfma_i32_16x16x64_i8 v[64:67], v[188:191], v[220:223], v[64:67]
	s_barrier
	ds_read_b128 v[192:195], v165 offset:16384
	ds_read_b128 v[196:199], v165 offset:17408
	ds_read_b128 v[200:203], v165 offset:18432
	ds_read_b128 v[204:207], v165 offset:19456
	ds_read_b128 v[208:211], v165 offset:20480
	ds_read_b128 v[212:215], v165 offset:21504
	ds_read_b128 v[216:219], v165 offset:22528
	ds_read_b128 v[220:223], v165 offset:23552
	s_add_i32 s55, s46, s35
	v_lshl_add_u64 v[152:153], s[6:7], 0, v[132:133]
	s_mov_b32 m0, s55
	s_nop 0
	global_load_lds_dwordx4 v[152:153], off
	s_add_i32 m0, s55, 0x2000
	s_add_u32 s56, s6, 0x80000
	v_lshl_add_u64 v[224:225], s[6:7], 0, v[128:129]
	s_addc_u32 s57, s7, 0
	s_add_i32 s55, s47, s35
	global_load_lds_dwordx4 v[224:225], off
	v_lshl_add_u64 v[226:227], s[56:57], 0, v[132:133]
	s_mov_b32 m0, s55
	v_lshl_add_u64 v[228:229], s[28:29], 0, v[130:131]
	global_load_lds_dwordx4 v[226:227], off
	v_lshl_add_u64 v[226:227], s[56:57], 0, v[128:129]
	s_add_i32 m0, s55, 0x2000
	s_nop 0
	global_load_lds_dwordx4 v[226:227], off
	v_lshl_add_u64 v[226:227], s[28:29], 0, v[134:135]
	s_mov_b32 m0, s38
	s_nop 0
	global_load_lds_dwordx4 v[226:227], off
	s_mov_b32 m0, s39
	s_nop 0
	global_load_lds_dwordx4 v[228:229], off
	s_waitcnt vmcnt(8) lgkmcnt(0)
	s_barrier
	v_mfma_i32_16x16x64_i8 v[60:63], v[144:147], v[192:195], v[60:63]
	v_mfma_i32_16x16x64_i8 v[56:59], v[168:171], v[192:195], v[56:59]
	v_mfma_i32_16x16x64_i8 v[44:47], v[144:147], v[200:203], v[44:47]
	v_mfma_i32_16x16x64_i8 v[40:43], v[168:171], v[200:203], v[40:43]
	v_mfma_i32_16x16x64_i8 v[28:31], v[144:147], v[208:211], v[28:31]
	v_mfma_i32_16x16x64_i8 v[24:27], v[168:171], v[208:211], v[24:27]
	v_mfma_i32_16x16x64_i8 v[12:15], v[144:147], v[216:219], v[12:15]
	v_mfma_i32_16x16x64_i8 v[8:11], v[168:171], v[216:219], v[8:11]
	v_mfma_i32_16x16x64_i8 v[60:63], v[148:151], v[196:199], v[60:63]
	v_mfma_i32_16x16x64_i8 v[56:59], v[172:175], v[196:199], v[56:59]
	v_mfma_i32_16x16x64_i8 v[44:47], v[148:151], v[204:207], v[44:47]
	v_mfma_i32_16x16x64_i8 v[40:43], v[172:175], v[204:207], v[40:43]
	v_mfma_i32_16x16x64_i8 v[28:31], v[148:151], v[212:215], v[28:31]
	v_mfma_i32_16x16x64_i8 v[24:27], v[172:175], v[212:215], v[24:27]
	v_mfma_i32_16x16x64_i8 v[12:15], v[148:151], v[220:223], v[12:15]
	v_mfma_i32_16x16x64_i8 v[8:11], v[172:175], v[220:223], v[8:11]
	v_mfma_i32_16x16x64_i8 v[52:55], v[176:179], v[192:195], v[52:55]
	v_mfma_i32_16x16x64_i8 v[48:51], v[184:187], v[192:195], v[48:51]
	v_mfma_i32_16x16x64_i8 v[36:39], v[176:179], v[200:203], v[36:39]
	v_mfma_i32_16x16x64_i8 v[32:35], v[184:187], v[200:203], v[32:35]
	v_mfma_i32_16x16x64_i8 v[20:23], v[176:179], v[208:211], v[20:23]
	v_mfma_i32_16x16x64_i8 v[16:19], v[184:187], v[208:211], v[16:19]
	v_mfma_i32_16x16x64_i8 v[4:7], v[176:179], v[216:219], v[4:7]
	v_mfma_i32_16x16x64_i8 v[0:3], v[184:187], v[216:219], v[0:3]
	v_mfma_i32_16x16x64_i8 v[52:55], v[180:183], v[196:199], v[52:55]
	v_mfma_i32_16x16x64_i8 v[48:51], v[188:191], v[196:199], v[48:51]
	v_mfma_i32_16x16x64_i8 v[36:39], v[180:183], v[204:207], v[36:39]
	v_mfma_i32_16x16x64_i8 v[32:35], v[188:191], v[204:207], v[32:35]
	v_mfma_i32_16x16x64_i8 v[20:23], v[180:183], v[212:215], v[20:23]
	v_mfma_i32_16x16x64_i8 v[16:19], v[188:191], v[212:215], v[16:19]
	v_mfma_i32_16x16x64_i8 v[4:7], v[180:183], v[220:223], v[4:7]
	v_mfma_i32_16x16x64_i8 v[0:3], v[188:191], v[220:223], v[0:3]
	s_barrier
	ds_read_b128 v[192:195], v165 offset:32768
	ds_read_b128 v[196:199], v165 offset:33792
	ds_read_b128 v[200:203], v165 offset:34816
	ds_read_b128 v[204:207], v165 offset:35840
	ds_read_b128 v[208:211], v165 offset:36864
	ds_read_b128 v[212:215], v165 offset:37888
	ds_read_b128 v[216:219], v165 offset:38912
	ds_read_b128 v[220:223], v165 offset:39936
	s_add_i32 s55, 0, 0x18000
	v_add_u32_e32 v154, s55, v157
	s_add_i32 s56, 0, 0x1c000
	ds_read_b128 v[144:147], v154
	ds_read_b128 v[148:151], v154 offset:1024
	ds_read_b128 v[168:171], v154 offset:2048
	ds_read_b128 v[172:175], v154 offset:3072
	v_add_u32_e32 v154, s56, v157
	ds_read_b128 v[176:179], v154
	ds_read_b128 v[180:183], v154 offset:1024
	ds_read_b128 v[184:187], v154 offset:2048
	ds_read_b128 v[188:191], v154 offset:3072
	s_add_u32 s28, s28, 0x80000
	s_addc_u32 s29, s29, 0
	s_mov_b32 m0, s40
	v_lshl_add_u64 v[230:231], s[28:29], 0, v[134:135]
	global_load_lds_dwordx4 v[230:231], off
	v_lshl_add_u64 v[230:231], s[28:29], 0, v[130:131]
	s_mov_b32 m0, s41
	s_nop 0
	global_load_lds_dwordx4 v[230:231], off
	s_waitcnt vmcnt(8) lgkmcnt(0)
	s_barrier
	v_mfma_i32_16x16x64_i8 v[124:127], v[144:147], v[192:195], v[124:127]
	v_mfma_i32_16x16x64_i8 v[120:123], v[168:171], v[192:195], v[120:123]
	v_mfma_i32_16x16x64_i8 v[108:111], v[144:147], v[200:203], v[108:111]
	v_mfma_i32_16x16x64_i8 v[104:107], v[168:171], v[200:203], v[104:107]
	v_mfma_i32_16x16x64_i8 v[92:95], v[144:147], v[208:211], v[92:95]
	v_mfma_i32_16x16x64_i8 v[88:91], v[168:171], v[208:211], v[88:91]
	v_mfma_i32_16x16x64_i8 v[76:79], v[144:147], v[216:219], v[76:79]
	v_mfma_i32_16x16x64_i8 v[72:75], v[168:171], v[216:219], v[72:75]
	v_mfma_i32_16x16x64_i8 v[124:127], v[148:151], v[196:199], v[124:127]
	v_mfma_i32_16x16x64_i8 v[120:123], v[172:175], v[196:199], v[120:123]
	v_mfma_i32_16x16x64_i8 v[108:111], v[148:151], v[204:207], v[108:111]
	v_mfma_i32_16x16x64_i8 v[104:107], v[172:175], v[204:207], v[104:107]
	v_mfma_i32_16x16x64_i8 v[92:95], v[148:151], v[212:215], v[92:95]
	v_mfma_i32_16x16x64_i8 v[88:91], v[172:175], v[212:215], v[88:91]
	v_mfma_i32_16x16x64_i8 v[76:79], v[148:151], v[220:223], v[76:79]
	v_mfma_i32_16x16x64_i8 v[72:75], v[172:175], v[220:223], v[72:75]
	v_mfma_i32_16x16x64_i8 v[116:119], v[176:179], v[192:195], v[116:119]
	v_mfma_i32_16x16x64_i8 v[112:115], v[184:187], v[192:195], v[112:115]
	v_mfma_i32_16x16x64_i8 v[100:103], v[176:179], v[200:203], v[100:103]
	v_mfma_i32_16x16x64_i8 v[96:99], v[184:187], v[200:203], v[96:99]
	v_mfma_i32_16x16x64_i8 v[84:87], v[176:179], v[208:211], v[84:87]
	v_mfma_i32_16x16x64_i8 v[80:83], v[184:187], v[208:211], v[80:83]
	v_mfma_i32_16x16x64_i8 v[68:71], v[176:179], v[216:219], v[68:71]
	v_mfma_i32_16x16x64_i8 v[64:67], v[184:187], v[216:219], v[64:67]
	v_mfma_i32_16x16x64_i8 v[116:119], v[180:183], v[196:199], v[116:119]
	v_mfma_i32_16x16x64_i8 v[112:115], v[188:191], v[196:199], v[112:115]
	v_mfma_i32_16x16x64_i8 v[100:103], v[180:183], v[204:207], v[100:103]
	v_mfma_i32_16x16x64_i8 v[96:99], v[188:191], v[204:207], v[96:99]
	v_mfma_i32_16x16x64_i8 v[84:87], v[180:183], v[212:215], v[84:87]
	v_mfma_i32_16x16x64_i8 v[80:83], v[188:191], v[212:215], v[80:83]
	v_mfma_i32_16x16x64_i8 v[68:71], v[180:183], v[220:223], v[68:71]
	v_mfma_i32_16x16x64_i8 v[64:67], v[188:191], v[220:223], v[64:67]
	s_barrier
	ds_read_b128 v[192:195], v165 offset:49152
	ds_read_b128 v[196:199], v165 offset:50176
	ds_read_b128 v[200:203], v165 offset:51200
	ds_read_b128 v[204:207], v165 offset:52224
	ds_read_b128 v[208:211], v165 offset:53248
	ds_read_b128 v[212:215], v165 offset:54272
	ds_read_b128 v[216:219], v165 offset:55296
	ds_read_b128 v[220:223], v165 offset:56320
	s_add_i32 s28, s55, s35
	v_lshl_add_u64 v[152:153], v[152:153], 0, s[16:17]
	s_mov_b32 m0, s28
	s_nop 0
	global_load_lds_dwordx4 v[152:153], off
	s_add_i32 m0, s28, 0x2000
	s_add_u32 s6, s6, 0x80080
	v_lshl_add_u64 v[152:153], v[224:225], 0, s[16:17]
	s_addc_u32 s7, s7, 0
	s_add_i32 s28, s56, s35
	global_load_lds_dwordx4 v[152:153], off
	v_lshl_add_u64 v[152:153], s[6:7], 0, v[132:133]
	s_mov_b32 m0, s28
	s_nop 0
	global_load_lds_dwordx4 v[152:153], off
	v_lshl_add_u64 v[152:153], s[6:7], 0, v[128:129]
	s_add_i32 m0, s28, 0x2000
	s_nop 0
	global_load_lds_dwordx4 v[152:153], off
	v_lshl_add_u64 v[152:153], v[226:227], 0, s[16:17]
	s_mov_b32 m0, s43
	s_nop 0
	global_load_lds_dwordx4 v[152:153], off
	v_lshl_add_u64 v[152:153], v[228:229], 0, s[16:17]
	s_mov_b32 m0, s44
	s_nop 0
	global_load_lds_dwordx4 v[152:153], off
	s_waitcnt vmcnt(8) lgkmcnt(0)
	s_barrier
	v_mfma_i32_16x16x64_i8 v[60:63], v[144:147], v[192:195], v[60:63]
	v_mfma_i32_16x16x64_i8 v[56:59], v[168:171], v[192:195], v[56:59]
	v_mfma_i32_16x16x64_i8 v[44:47], v[144:147], v[200:203], v[44:47]
	v_mfma_i32_16x16x64_i8 v[40:43], v[168:171], v[200:203], v[40:43]
	v_mfma_i32_16x16x64_i8 v[28:31], v[144:147], v[208:211], v[28:31]
	v_mfma_i32_16x16x64_i8 v[24:27], v[168:171], v[208:211], v[24:27]
	v_mfma_i32_16x16x64_i8 v[12:15], v[144:147], v[216:219], v[12:15]
	v_mfma_i32_16x16x64_i8 v[8:11], v[168:171], v[216:219], v[8:11]
	v_mfma_i32_16x16x64_i8 v[60:63], v[148:151], v[196:199], v[60:63]
	v_mfma_i32_16x16x64_i8 v[56:59], v[172:175], v[196:199], v[56:59]
	v_mfma_i32_16x16x64_i8 v[44:47], v[148:151], v[204:207], v[44:47]
	v_mfma_i32_16x16x64_i8 v[40:43], v[172:175], v[204:207], v[40:43]
	v_mfma_i32_16x16x64_i8 v[28:31], v[148:151], v[212:215], v[28:31]
	v_mfma_i32_16x16x64_i8 v[24:27], v[172:175], v[212:215], v[24:27]
	v_mfma_i32_16x16x64_i8 v[12:15], v[148:151], v[220:223], v[12:15]
	v_mfma_i32_16x16x64_i8 v[8:11], v[172:175], v[220:223], v[8:11]
	v_mfma_i32_16x16x64_i8 v[52:55], v[176:179], v[192:195], v[52:55]
	v_mfma_i32_16x16x64_i8 v[48:51], v[184:187], v[192:195], v[48:51]
	v_mfma_i32_16x16x64_i8 v[36:39], v[176:179], v[200:203], v[36:39]
	v_mfma_i32_16x16x64_i8 v[32:35], v[184:187], v[200:203], v[32:35]
	v_mfma_i32_16x16x64_i8 v[20:23], v[176:179], v[208:211], v[20:23]
	v_mfma_i32_16x16x64_i8 v[16:19], v[184:187], v[208:211], v[16:19]
	v_mfma_i32_16x16x64_i8 v[4:7], v[176:179], v[216:219], v[4:7]
	v_mfma_i32_16x16x64_i8 v[0:3], v[184:187], v[216:219], v[0:3]
	v_mfma_i32_16x16x64_i8 v[52:55], v[180:183], v[196:199], v[52:55]
	v_mfma_i32_16x16x64_i8 v[48:51], v[188:191], v[196:199], v[48:51]
	v_mfma_i32_16x16x64_i8 v[36:39], v[180:183], v[204:207], v[36:39]
	v_mfma_i32_16x16x64_i8 v[32:35], v[188:191], v[204:207], v[32:35]
	v_mfma_i32_16x16x64_i8 v[20:23], v[180:183], v[212:215], v[20:23]
	v_mfma_i32_16x16x64_i8 v[16:19], v[188:191], v[212:215], v[16:19]
	v_mfma_i32_16x16x64_i8 v[4:7], v[180:183], v[220:223], v[4:7]
	v_mfma_i32_16x16x64_i8 v[0:3], v[188:191], v[220:223], v[0:3]
	s_barrier
	s_add_i32 s54, s54, 2
	s_add_u32 s52, s52, 0x100
	s_addc_u32 s53, s53, 0
	s_add_u32 s4, s4, 0x100
	s_addc_u32 s5, s5, 0
	s_cmp_gt_u32 s54, 29
	s_cbranch_scc0 .LBB0_726
	s_setprio 0
	s_and_b64 vcc, exec, s[18:19]
	s_cbranch_vccz .LBB0_729
	s_barrier

.Lsp_skip7:
.LBB0_1255:
	ds_read_b128 v[16:19], v193
	ds_read_b128 v[20:23], v193 offset:1024
	ds_read_b128 v[24:27], v193 offset:2048
	ds_read_b128 v[28:31], v193 offset:3072
	ds_read_b128 v[0:3], v194
	ds_read_b128 v[4:7], v194 offset:1024
	ds_read_b128 v[8:11], v194 offset:2048
	ds_read_b128 v[12:15], v194 offset:3072
	ds_read_b128 v[176:179], v195
	ds_read_b128 v[180:183], v195 offset:1024
	ds_read_b128 v[200:203], v195 offset:2048
	ds_read_b128 v[204:207], v195 offset:3072
	ds_read_b128 v[208:211], v195 offset:4096
	ds_read_b128 v[212:215], v195 offset:5120
	ds_read_b128 v[216:219], v195 offset:6144
	ds_read_b128 v[220:223], v195 offset:7168
	s_waitcnt lgkmcnt(0)
	s_add_u32 s36, s34, 0xfffc0080
	s_addc_u32 s37, s35, -1
	s_cmp_eq_u32 s59, 12
	s_cselect_b32 s39, s23, s37
	s_cselect_b32 s38, s29, s36
	s_cselect_b32 s37, s21, s58
	s_cselect_b32 s36, s56, s57
	v_lshl_add_u64 v[184:185], s[34:35], 0, v[170:171]
	s_add_i32 m0, s31, 0xc000
	s_nop 0
	global_load_lds_dwordx4 v[184:185], off
	v_lshl_add_u64 v[184:185], s[34:35], 0, v[168:169]
	s_add_i32 m0, s31, 0xe000
	s_nop 0
	global_load_lds_dwordx4 v[184:185], off
	s_waitcnt vmcnt(8) lgkmcnt(0)
	s_barrier
	v_mfma_scale_f32_16x16x128_f8f6f4 v[156:159], v[16:23], v[176:183], v[156:159], v196, v196 op_sel_hi:[0,0,0]
	v_mfma_scale_f32_16x16x128_f8f6f4 v[152:155], v[24:31], v[176:183], v[152:155], v196, v196 op_sel_hi:[0,0,0]
	v_mfma_scale_f32_16x16x128_f8f6f4 v[140:143], v[16:23], v[200:207], v[140:143], v196, v196 op_sel_hi:[0,0,0]
	v_mfma_scale_f32_16x16x128_f8f6f4 v[136:139], v[24:31], v[200:207], v[136:139], v196, v196 op_sel_hi:[0,0,0]
	v_mfma_scale_f32_16x16x128_f8f6f4 v[124:127], v[16:23], v[208:215], v[124:127], v196, v196 op_sel_hi:[0,0,0]
	v_mfma_scale_f32_16x16x128_f8f6f4 v[120:123], v[24:31], v[208:215], v[120:123], v196, v196 op_sel_hi:[0,0,0]
	v_mfma_scale_f32_16x16x128_f8f6f4 v[108:111], v[16:23], v[216:223], v[108:111], v196, v196 op_sel_hi:[0,0,0]
	v_mfma_scale_f32_16x16x128_f8f6f4 v[104:107], v[24:31], v[216:223], v[104:107], v196, v196 op_sel_hi:[0,0,0]
	v_mfma_scale_f32_16x16x128_f8f6f4 v[148:151], v[0:7], v[176:183], v[148:151], v196, v196 op_sel_hi:[0,0,0]
	v_mfma_scale_f32_16x16x128_f8f6f4 v[144:147], v[8:15], v[176:183], v[144:147], v196, v196 op_sel_hi:[0,0,0]
	v_mfma_scale_f32_16x16x128_f8f6f4 v[132:135], v[0:7], v[200:207], v[132:135], v196, v196 op_sel_hi:[0,0,0]
	v_mfma_scale_f32_16x16x128_f8f6f4 v[128:131], v[8:15], v[200:207], v[128:131], v196, v196 op_sel_hi:[0,0,0]
	v_mfma_scale_f32_16x16x128_f8f6f4 v[116:119], v[0:7], v[208:215], v[116:119], v196, v196 op_sel_hi:[0,0,0]
	v_mfma_scale_f32_16x16x128_f8f6f4 v[112:115], v[8:15], v[208:215], v[112:115], v196, v196 op_sel_hi:[0,0,0]
	v_mfma_scale_f32_16x16x128_f8f6f4 v[100:103], v[0:7], v[216:223], v[100:103], v196, v196 op_sel_hi:[0,0,0]
	v_mfma_scale_f32_16x16x128_f8f6f4 v[96:99], v[8:15], v[216:223], v[96:99], v196, v196 op_sel_hi:[0,0,0]
	s_barrier
	ds_read_b128 v[200:203], v195 offset:16384
	ds_read_b128 v[204:207], v195 offset:17408
	ds_read_b128 v[208:211], v195 offset:18432
	ds_read_b128 v[212:215], v195 offset:19456
	ds_read_b128 v[216:219], v195 offset:20480
	ds_read_b128 v[220:223], v195 offset:21504
	ds_read_b128 v[224:227], v195 offset:22528
	ds_read_b128 v[228:231], v195 offset:23552
	s_add_i32 s60, s51, s42
	v_lshl_add_u64 v[176:177], s[36:37], 0, v[162:163]
	s_mov_b32 m0, s60
	s_nop 0
	global_load_lds_dwordx4 v[176:177], off
	s_add_i32 m0, s60, 0x2000
	s_add_u32 s60, s36, 0x40000
	v_lshl_add_u64 v[178:179], s[36:37], 0, v[166:167]
	s_addc_u32 s61, s37, 0
	s_add_i32 s62, s52, s42
	global_load_lds_dwordx4 v[178:179], off
	v_lshl_add_u64 v[180:181], s[60:61], 0, v[162:163]
	s_mov_b32 m0, s62
	v_lshl_add_u64 v[182:183], s[38:39], 0, v[164:165]
	global_load_lds_dwordx4 v[180:181], off
	v_lshl_add_u64 v[180:181], s[60:61], 0, v[166:167]
	s_add_i32 m0, s62, 0x2000
	s_nop 0
	global_load_lds_dwordx4 v[180:181], off
	v_lshl_add_u64 v[180:181], s[38:39], 0, v[160:161]
	s_mov_b32 m0, s31
	s_nop 0
	global_load_lds_dwordx4 v[180:181], off
	s_mov_b32 m0, s43
	s_nop 0
	global_load_lds_dwordx4 v[182:183], off
	s_waitcnt vmcnt(8) lgkmcnt(0)
	s_barrier
	v_mfma_scale_f32_16x16x128_f8f6f4 v[92:95], v[16:23], v[200:207], v[92:95], v196, v196 op_sel_hi:[0,0,0]
	v_mfma_scale_f32_16x16x128_f8f6f4 v[88:91], v[24:31], v[200:207], v[88:91], v196, v196 op_sel_hi:[0,0,0]
	v_mfma_scale_f32_16x16x128_f8f6f4 v[76:79], v[16:23], v[208:215], v[76:79], v196, v196 op_sel_hi:[0,0,0]
	v_mfma_scale_f32_16x16x128_f8f6f4 v[72:75], v[24:31], v[208:215], v[72:75], v196, v196 op_sel_hi:[0,0,0]
	v_mfma_scale_f32_16x16x128_f8f6f4 v[60:63], v[16:23], v[216:223], v[60:63], v196, v196 op_sel_hi:[0,0,0]
	v_mfma_scale_f32_16x16x128_f8f6f4 v[56:59], v[24:31], v[216:223], v[56:59], v196, v196 op_sel_hi:[0,0,0]
	v_mfma_scale_f32_16x16x128_f8f6f4 v[44:47], v[16:23], v[224:231], v[44:47], v196, v196 op_sel_hi:[0,0,0]
	v_mfma_scale_f32_16x16x128_f8f6f4 v[40:43], v[24:31], v[224:231], v[40:43], v196, v196 op_sel_hi:[0,0,0]
	v_mfma_scale_f32_16x16x128_f8f6f4 v[84:87], v[0:7], v[200:207], v[84:87], v196, v196 op_sel_hi:[0,0,0]
	v_mfma_scale_f32_16x16x128_f8f6f4 v[80:83], v[8:15], v[200:207], v[80:83], v196, v196 op_sel_hi:[0,0,0]
	v_mfma_scale_f32_16x16x128_f8f6f4 v[68:71], v[0:7], v[208:215], v[68:71], v196, v196 op_sel_hi:[0,0,0]
	v_mfma_scale_f32_16x16x128_f8f6f4 v[64:67], v[8:15], v[208:215], v[64:67], v196, v196 op_sel_hi:[0,0,0]
	v_mfma_scale_f32_16x16x128_f8f6f4 v[52:55], v[0:7], v[216:223], v[52:55], v196, v196 op_sel_hi:[0,0,0]
	v_mfma_scale_f32_16x16x128_f8f6f4 v[48:51], v[8:15], v[216:223], v[48:51], v196, v196 op_sel_hi:[0,0,0]
	v_mfma_scale_f32_16x16x128_f8f6f4 v[36:39], v[0:7], v[224:231], v[36:39], v196, v196 op_sel_hi:[0,0,0]
	v_mfma_scale_f32_16x16x128_f8f6f4 v[32:35], v[8:15], v[224:231], v[32:35], v196, v196 op_sel_hi:[0,0,0]
	s_barrier
	ds_read_b128 v[200:203], v195 offset:32768
	ds_read_b128 v[204:207], v195 offset:33792
	ds_read_b128 v[208:211], v195 offset:34816
	ds_read_b128 v[212:215], v195 offset:35840
	ds_read_b128 v[216:219], v195 offset:36864
	ds_read_b128 v[220:223], v195 offset:37888
	ds_read_b128 v[224:227], v195 offset:38912
	ds_read_b128 v[228:231], v195 offset:39936
	s_add_i32 s60, 0, 0x18000
	s_add_i32 s61, 0, 0x1c000
	v_add_u32_e32 v12, s60, v191
	v_add_u32_e32 v28, s61, v191
	ds_read_b128 v[0:3], v12
	ds_read_b128 v[4:7], v12 offset:1024
	ds_read_b128 v[8:11], v12 offset:2048
	ds_read_b128 v[12:15], v12 offset:3072
	ds_read_b128 v[16:19], v28
	ds_read_b128 v[20:23], v28 offset:1024
	ds_read_b128 v[24:27], v28 offset:2048
	ds_read_b128 v[28:31], v28 offset:3072
	s_add_u32 s38, s38, 0x40000
	s_addc_u32 s39, s39, 0
	s_mov_b32 m0, s44
	v_lshl_add_u64 v[184:185], s[38:39], 0, v[160:161]
	global_load_lds_dwordx4 v[184:185], off
	v_lshl_add_u64 v[184:185], s[38:39], 0, v[164:165]
	s_mov_b32 m0, s45
	s_nop 0
	global_load_lds_dwordx4 v[184:185], off
	s_waitcnt vmcnt(8) lgkmcnt(0)
	s_barrier
	v_mfma_scale_f32_16x16x128_f8f6f4 v[156:159], v[0:7], v[200:207], v[156:159], v196, v196 op_sel_hi:[0,0,0]
	v_mfma_scale_f32_16x16x128_f8f6f4 v[152:155], v[8:15], v[200:207], v[152:155], v196, v196 op_sel_hi:[0,0,0]
	v_mfma_scale_f32_16x16x128_f8f6f4 v[140:143], v[0:7], v[208:215], v[140:143], v196, v196 op_sel_hi:[0,0,0]
	v_mfma_scale_f32_16x16x128_f8f6f4 v[136:139], v[8:15], v[208:215], v[136:139], v196, v196 op_sel_hi:[0,0,0]
	v_mfma_scale_f32_16x16x128_f8f6f4 v[124:127], v[0:7], v[216:223], v[124:127], v196, v196 op_sel_hi:[0,0,0]
	v_mfma_scale_f32_16x16x128_f8f6f4 v[120:123], v[8:15], v[216:223], v[120:123], v196, v196 op_sel_hi:[0,0,0]
	v_mfma_scale_f32_16x16x128_f8f6f4 v[108:111], v[0:7], v[224:231], v[108:111], v196, v196 op_sel_hi:[0,0,0]
	v_mfma_scale_f32_16x16x128_f8f6f4 v[104:107], v[8:15], v[224:231], v[104:107], v196, v196 op_sel_hi:[0,0,0]
	v_mfma_scale_f32_16x16x128_f8f6f4 v[148:151], v[16:23], v[200:207], v[148:151], v196, v196 op_sel_hi:[0,0,0]
	v_mfma_scale_f32_16x16x128_f8f6f4 v[144:147], v[24:31], v[200:207], v[144:147], v196, v196 op_sel_hi:[0,0,0]
	v_mfma_scale_f32_16x16x128_f8f6f4 v[132:135], v[16:23], v[208:215], v[132:135], v196, v196 op_sel_hi:[0,0,0]
	v_mfma_scale_f32_16x16x128_f8f6f4 v[128:131], v[24:31], v[208:215], v[128:131], v196, v196 op_sel_hi:[0,0,0]
	v_mfma_scale_f32_16x16x128_f8f6f4 v[116:119], v[16:23], v[216:223], v[116:119], v196, v196 op_sel_hi:[0,0,0]
	v_mfma_scale_f32_16x16x128_f8f6f4 v[112:115], v[24:31], v[216:223], v[112:115], v196, v196 op_sel_hi:[0,0,0]
	v_mfma_scale_f32_16x16x128_f8f6f4 v[100:103], v[16:23], v[224:231], v[100:103], v196, v196 op_sel_hi:[0,0,0]
	v_mfma_scale_f32_16x16x128_f8f6f4 v[96:99], v[24:31], v[224:231], v[96:99], v196, v196 op_sel_hi:[0,0,0]
	s_barrier
	ds_read_b128 v[200:203], v195 offset:49152
	ds_read_b128 v[204:207], v195 offset:50176
	ds_read_b128 v[208:211], v195 offset:51200
	ds_read_b128 v[212:215], v195 offset:52224
	ds_read_b128 v[216:219], v195 offset:53248
	ds_read_b128 v[220:223], v195 offset:54272
	ds_read_b128 v[224:227], v195 offset:55296
	ds_read_b128 v[228:231], v195 offset:56320
	s_add_i32 s38, s60, s42
	v_lshl_add_u64 v[176:177], v[176:177], 0, s[14:15]
	s_mov_b32 m0, s38
	s_nop 0
	global_load_lds_dwordx4 v[176:177], off
	s_add_i32 m0, s38, 0x2000
	s_add_u32 s36, s36, 0x40080
	v_lshl_add_u64 v[176:177], v[178:179], 0, s[14:15]
	s_addc_u32 s37, s37, 0
	s_add_i32 s38, s61, s42
	global_load_lds_dwordx4 v[176:177], off
	v_lshl_add_u64 v[176:177], s[36:37], 0, v[162:163]
	s_mov_b32 m0, s38
	s_nop 0
	global_load_lds_dwordx4 v[176:177], off
	v_lshl_add_u64 v[176:177], s[36:37], 0, v[166:167]
	s_add_i32 m0, s38, 0x2000
	s_nop 0
	global_load_lds_dwordx4 v[176:177], off
	v_lshl_add_u64 v[176:177], v[180:181], 0, s[14:15]
	s_mov_b32 m0, s47
	s_nop 0
	global_load_lds_dwordx4 v[176:177], off
	v_lshl_add_u64 v[176:177], v[182:183], 0, s[14:15]
	s_mov_b32 m0, s48
	s_nop 0
	global_load_lds_dwordx4 v[176:177], off
	s_waitcnt vmcnt(8) lgkmcnt(0)
	s_barrier
	v_mfma_scale_f32_16x16x128_f8f6f4 v[92:95], v[0:7], v[200:207], v[92:95], v196, v196 op_sel_hi:[0,0,0]
	v_mfma_scale_f32_16x16x128_f8f6f4 v[88:91], v[8:15], v[200:207], v[88:91], v196, v196 op_sel_hi:[0,0,0]
	v_mfma_scale_f32_16x16x128_f8f6f4 v[76:79], v[0:7], v[208:215], v[76:79], v196, v196 op_sel_hi:[0,0,0]
	v_mfma_scale_f32_16x16x128_f8f6f4 v[72:75], v[8:15], v[208:215], v[72:75], v196, v196 op_sel_hi:[0,0,0]
	v_mfma_scale_f32_16x16x128_f8f6f4 v[60:63], v[0:7], v[216:223], v[60:63], v196, v196 op_sel_hi:[0,0,0]
	v_mfma_scale_f32_16x16x128_f8f6f4 v[56:59], v[8:15], v[216:223], v[56:59], v196, v196 op_sel_hi:[0,0,0]
	v_mfma_scale_f32_16x16x128_f8f6f4 v[44:47], v[0:7], v[224:231], v[44:47], v196, v196 op_sel_hi:[0,0,0]
	v_mfma_scale_f32_16x16x128_f8f6f4 v[40:43], v[8:15], v[224:231], v[40:43], v196, v196 op_sel_hi:[0,0,0]
	v_mfma_scale_f32_16x16x128_f8f6f4 v[84:87], v[16:23], v[200:207], v[84:87], v196, v196 op_sel_hi:[0,0,0]
	v_mfma_scale_f32_16x16x128_f8f6f4 v[80:83], v[24:31], v[200:207], v[80:83], v196, v196 op_sel_hi:[0,0,0]
	v_mfma_scale_f32_16x16x128_f8f6f4 v[68:71], v[16:23], v[208:215], v[68:71], v196, v196 op_sel_hi:[0,0,0]
	v_mfma_scale_f32_16x16x128_f8f6f4 v[64:67], v[24:31], v[208:215], v[64:67], v196, v196 op_sel_hi:[0,0,0]
	v_mfma_scale_f32_16x16x128_f8f6f4 v[52:55], v[16:23], v[216:223], v[52:55], v196, v196 op_sel_hi:[0,0,0]
	v_mfma_scale_f32_16x16x128_f8f6f4 v[48:51], v[24:31], v[216:223], v[48:51], v196, v196 op_sel_hi:[0,0,0]
	v_mfma_scale_f32_16x16x128_f8f6f4 v[36:39], v[16:23], v[224:231], v[36:39], v196, v196 op_sel_hi:[0,0,0]
	v_mfma_scale_f32_16x16x128_f8f6f4 v[32:35], v[24:31], v[224:231], v[32:35], v196, v196 op_sel_hi:[0,0,0]
	s_barrier
	s_add_i32 s59, s59, 2
	s_add_u32 s57, s57, 0x100
	s_addc_u32 s58, s58, 0
	s_add_u32 s34, s34, 0x100
	s_addc_u32 s35, s35, 0
	s_cmp_gt_u32 s59, 13
	s_cbranch_scc0 .LBB0_1255
	s_setprio 0
	s_and_b64 vcc, exec, s[16:17]
	s_cbranch_vccz .LBB0_1258
	s_barrier

.Lsp_skip8:
.LBB0_1356:
	ds_read_b128 v[144:147], v180
	ds_read_b128 v[148:151], v180 offset:1024
	ds_read_b128 v[152:155], v180 offset:2048
	ds_read_b128 v[156:159], v180 offset:3072
	ds_read_b128 v[160:163], v181
	ds_read_b128 v[164:167], v181 offset:1024
	ds_read_b128 v[168:171], v181 offset:2048
	ds_read_b128 v[172:175], v181 offset:3072
	ds_read_b128 v[186:189], v182
	ds_read_b128 v[190:193], v182 offset:1024
	ds_read_b128 v[194:197], v182 offset:2048
	ds_read_b128 v[198:201], v182 offset:3072
	ds_read_b128 v[202:205], v182 offset:4096
	ds_read_b128 v[206:209], v182 offset:5120
	ds_read_b128 v[210:213], v182 offset:6144
	ds_read_b128 v[214:217], v182 offset:7168
	s_add_u32 s34, s30, 0xfff80080
	s_addc_u32 s35, s31, -1
	s_cmp_eq_u32 s58, 28
	s_cselect_b32 s37, s1, s35
	s_cselect_b32 s36, s23, s34
	s_cselect_b32 s35, s21, s57
	s_cselect_b32 s34, s29, s33
	v_lshl_add_u64 v[218:219], s[30:31], 0, v[138:139]
	s_add_i32 m0, s43, 0xc000
	s_nop 0
	global_load_lds_dwordx4 v[218:219], off
	v_lshl_add_u64 v[218:219], s[30:31], 0, v[136:137]
	s_add_i32 m0, s43, 0xe000
	s_nop 0
	global_load_lds_dwordx4 v[218:219], off
	s_waitcnt vmcnt(8) lgkmcnt(0)
	s_barrier
	v_mfma_i32_16x16x64_i8 v[124:127], v[144:147], v[186:189], v[124:127]
	v_mfma_i32_16x16x64_i8 v[120:123], v[152:155], v[186:189], v[120:123]
	v_mfma_i32_16x16x64_i8 v[108:111], v[144:147], v[194:197], v[108:111]
	v_mfma_i32_16x16x64_i8 v[104:107], v[152:155], v[194:197], v[104:107]
	v_mfma_i32_16x16x64_i8 v[92:95], v[144:147], v[202:205], v[92:95]
	v_mfma_i32_16x16x64_i8 v[88:91], v[152:155], v[202:205], v[88:91]
	v_mfma_i32_16x16x64_i8 v[76:79], v[144:147], v[210:213], v[76:79]
	v_mfma_i32_16x16x64_i8 v[72:75], v[152:155], v[210:213], v[72:75]
	v_mfma_i32_16x16x64_i8 v[124:127], v[148:151], v[190:193], v[124:127]
	v_mfma_i32_16x16x64_i8 v[120:123], v[156:159], v[190:193], v[120:123]
	v_mfma_i32_16x16x64_i8 v[108:111], v[148:151], v[198:201], v[108:111]
	v_mfma_i32_16x16x64_i8 v[104:107], v[156:159], v[198:201], v[104:107]
	v_mfma_i32_16x16x64_i8 v[92:95], v[148:151], v[206:209], v[92:95]
	v_mfma_i32_16x16x64_i8 v[88:91], v[156:159], v[206:209], v[88:91]
	v_mfma_i32_16x16x64_i8 v[76:79], v[148:151], v[214:217], v[76:79]
	v_mfma_i32_16x16x64_i8 v[72:75], v[156:159], v[214:217], v[72:75]
	v_mfma_i32_16x16x64_i8 v[116:119], v[160:163], v[186:189], v[116:119]
	v_mfma_i32_16x16x64_i8 v[112:115], v[168:171], v[186:189], v[112:115]
	v_mfma_i32_16x16x64_i8 v[100:103], v[160:163], v[194:197], v[100:103]
	v_mfma_i32_16x16x64_i8 v[96:99], v[168:171], v[194:197], v[96:99]
	v_mfma_i32_16x16x64_i8 v[84:87], v[160:163], v[202:205], v[84:87]
	v_mfma_i32_16x16x64_i8 v[80:83], v[168:171], v[202:205], v[80:83]
	v_mfma_i32_16x16x64_i8 v[68:71], v[160:163], v[210:213], v[68:71]
	v_mfma_i32_16x16x64_i8 v[64:67], v[168:171], v[210:213], v[64:67]
	v_mfma_i32_16x16x64_i8 v[116:119], v[164:167], v[190:193], v[116:119]
	v_mfma_i32_16x16x64_i8 v[112:115], v[172:175], v[190:193], v[112:115]
	v_mfma_i32_16x16x64_i8 v[100:103], v[164:167], v[198:201], v[100:103]
	v_mfma_i32_16x16x64_i8 v[96:99], v[172:175], v[198:201], v[96:99]
	v_mfma_i32_16x16x64_i8 v[84:87], v[164:167], v[206:209], v[84:87]
	v_mfma_i32_16x16x64_i8 v[80:83], v[172:175], v[206:209], v[80:83]
	v_mfma_i32_16x16x64_i8 v[68:71], v[164:167], v[214:217], v[68:71]
	v_mfma_i32_16x16x64_i8 v[64:67], v[172:175], v[214:217], v[64:67]
	s_barrier
	ds_read_b128 v[186:189], v182 offset:16384
	ds_read_b128 v[190:193], v182 offset:17408
	ds_read_b128 v[194:197], v182 offset:18432
	ds_read_b128 v[198:201], v182 offset:19456
	ds_read_b128 v[202:205], v182 offset:20480
	ds_read_b128 v[206:209], v182 offset:21504
	ds_read_b128 v[210:213], v182 offset:22528
	ds_read_b128 v[214:217], v182 offset:23552
	s_add_i32 s59, s52, s42
	v_lshl_add_u64 v[218:219], s[34:35], 0, v[130:131]
	s_mov_b32 m0, s59
	s_nop 0
	global_load_lds_dwordx4 v[218:219], off
	s_add_i32 m0, s59, 0x2000
	s_add_u32 s60, s34, 0x80000
	v_lshl_add_u64 v[220:221], s[34:35], 0, v[134:135]
	s_addc_u32 s61, s35, 0
	s_add_i32 s59, s53, s42
	global_load_lds_dwordx4 v[220:221], off
	v_lshl_add_u64 v[222:223], s[60:61], 0, v[130:131]
	s_mov_b32 m0, s59
	v_lshl_add_u64 v[224:225], s[36:37], 0, v[132:133]
	global_load_lds_dwordx4 v[222:223], off
	v_lshl_add_u64 v[222:223], s[60:61], 0, v[134:135]
	s_add_i32 m0, s59, 0x2000
	s_nop 0
	global_load_lds_dwordx4 v[222:223], off
	v_lshl_add_u64 v[222:223], s[36:37], 0, v[128:129]
	s_mov_b32 m0, s43
	s_nop 0
	global_load_lds_dwordx4 v[222:223], off
	s_mov_b32 m0, s44
	s_nop 0
	global_load_lds_dwordx4 v[224:225], off
	s_waitcnt vmcnt(8) lgkmcnt(0)
	s_barrier
	v_mfma_i32_16x16x64_i8 v[60:63], v[144:147], v[186:189], v[60:63]
	v_mfma_i32_16x16x64_i8 v[56:59], v[152:155], v[186:189], v[56:59]
	v_mfma_i32_16x16x64_i8 v[44:47], v[144:147], v[194:197], v[44:47]
	v_mfma_i32_16x16x64_i8 v[40:43], v[152:155], v[194:197], v[40:43]
	v_mfma_i32_16x16x64_i8 v[28:31], v[144:147], v[202:205], v[28:31]
	v_mfma_i32_16x16x64_i8 v[24:27], v[152:155], v[202:205], v[24:27]
	v_mfma_i32_16x16x64_i8 v[12:15], v[144:147], v[210:213], v[12:15]
	v_mfma_i32_16x16x64_i8 v[8:11], v[152:155], v[210:213], v[8:11]
	v_mfma_i32_16x16x64_i8 v[60:63], v[148:151], v[190:193], v[60:63]
	v_mfma_i32_16x16x64_i8 v[56:59], v[156:159], v[190:193], v[56:59]
	v_mfma_i32_16x16x64_i8 v[44:47], v[148:151], v[198:201], v[44:47]
	v_mfma_i32_16x16x64_i8 v[40:43], v[156:159], v[198:201], v[40:43]
	v_mfma_i32_16x16x64_i8 v[28:31], v[148:151], v[206:209], v[28:31]
	v_mfma_i32_16x16x64_i8 v[24:27], v[156:159], v[206:209], v[24:27]
	v_mfma_i32_16x16x64_i8 v[12:15], v[148:151], v[214:217], v[12:15]
	v_mfma_i32_16x16x64_i8 v[8:11], v[156:159], v[214:217], v[8:11]
	v_mfma_i32_16x16x64_i8 v[52:55], v[160:163], v[186:189], v[52:55]
	v_mfma_i32_16x16x64_i8 v[48:51], v[168:171], v[186:189], v[48:51]
	v_mfma_i32_16x16x64_i8 v[36:39], v[160:163], v[194:197], v[36:39]
	v_mfma_i32_16x16x64_i8 v[32:35], v[168:171], v[194:197], v[32:35]
	v_mfma_i32_16x16x64_i8 v[20:23], v[160:163], v[202:205], v[20:23]
	v_mfma_i32_16x16x64_i8 v[16:19], v[168:171], v[202:205], v[16:19]
	v_mfma_i32_16x16x64_i8 v[4:7], v[160:163], v[210:213], v[4:7]
	v_mfma_i32_16x16x64_i8 v[0:3], v[168:171], v[210:213], v[0:3]
	v_mfma_i32_16x16x64_i8 v[52:55], v[164:167], v[190:193], v[52:55]
	v_mfma_i32_16x16x64_i8 v[48:51], v[172:175], v[190:193], v[48:51]
	v_mfma_i32_16x16x64_i8 v[36:39], v[164:167], v[198:201], v[36:39]
	v_mfma_i32_16x16x64_i8 v[32:35], v[172:175], v[198:201], v[32:35]
	v_mfma_i32_16x16x64_i8 v[20:23], v[164:167], v[206:209], v[20:23]
	v_mfma_i32_16x16x64_i8 v[16:19], v[172:175], v[206:209], v[16:19]
	v_mfma_i32_16x16x64_i8 v[4:7], v[164:167], v[214:217], v[4:7]
	v_mfma_i32_16x16x64_i8 v[0:3], v[172:175], v[214:217], v[0:3]
	s_barrier
	ds_read_b128 v[186:189], v182 offset:32768
	ds_read_b128 v[190:193], v182 offset:33792
	ds_read_b128 v[194:197], v182 offset:34816
	ds_read_b128 v[198:201], v182 offset:35840
	ds_read_b128 v[202:205], v182 offset:36864
	ds_read_b128 v[206:209], v182 offset:37888
	ds_read_b128 v[210:213], v182 offset:38912
	ds_read_b128 v[214:217], v182 offset:39936
	s_add_i32 s59, 0, 0x18000
	s_add_i32 s60, 0, 0x1c000
	v_add_u32_e32 v156, s59, v178
	v_add_u32_e32 v172, s60, v178
	ds_read_b128 v[144:147], v156
	ds_read_b128 v[148:151], v156 offset:1024
	ds_read_b128 v[152:155], v156 offset:2048
	ds_read_b128 v[156:159], v156 offset:3072
	ds_read_b128 v[160:163], v172
	ds_read_b128 v[164:167], v172 offset:1024
	ds_read_b128 v[168:171], v172 offset:2048
	ds_read_b128 v[172:175], v172 offset:3072
	s_add_u32 s36, s36, 0x80000
	s_addc_u32 s37, s37, 0
	s_mov_b32 m0, s45
	v_lshl_add_u64 v[226:227], s[36:37], 0, v[128:129]
	global_load_lds_dwordx4 v[226:227], off
	v_lshl_add_u64 v[226:227], s[36:37], 0, v[132:133]
	s_mov_b32 m0, s46
	s_nop 0
	global_load_lds_dwordx4 v[226:227], off
	s_waitcnt vmcnt(8) lgkmcnt(0)
	s_barrier
	v_mfma_i32_16x16x64_i8 v[124:127], v[144:147], v[186:189], v[124:127]
	v_mfma_i32_16x16x64_i8 v[120:123], v[152:155], v[186:189], v[120:123]
	v_mfma_i32_16x16x64_i8 v[108:111], v[144:147], v[194:197], v[108:111]
	v_mfma_i32_16x16x64_i8 v[104:107], v[152:155], v[194:197], v[104:107]
	v_mfma_i32_16x16x64_i8 v[92:95], v[144:147], v[202:205], v[92:95]
	v_mfma_i32_16x16x64_i8 v[88:91], v[152:155], v[202:205], v[88:91]
	v_mfma_i32_16x16x64_i8 v[76:79], v[144:147], v[210:213], v[76:79]
	v_mfma_i32_16x16x64_i8 v[72:75], v[152:155], v[210:213], v[72:75]
	v_mfma_i32_16x16x64_i8 v[124:127], v[148:151], v[190:193], v[124:127]
	v_mfma_i32_16x16x64_i8 v[120:123], v[156:159], v[190:193], v[120:123]
	v_mfma_i32_16x16x64_i8 v[108:111], v[148:151], v[198:201], v[108:111]
	v_mfma_i32_16x16x64_i8 v[104:107], v[156:159], v[198:201], v[104:107]
	v_mfma_i32_16x16x64_i8 v[92:95], v[148:151], v[206:209], v[92:95]
	v_mfma_i32_16x16x64_i8 v[88:91], v[156:159], v[206:209], v[88:91]
	v_mfma_i32_16x16x64_i8 v[76:79], v[148:151], v[214:217], v[76:79]
	v_mfma_i32_16x16x64_i8 v[72:75], v[156:159], v[214:217], v[72:75]
	v_mfma_i32_16x16x64_i8 v[116:119], v[160:163], v[186:189], v[116:119]
	v_mfma_i32_16x16x64_i8 v[112:115], v[168:171], v[186:189], v[112:115]
	v_mfma_i32_16x16x64_i8 v[100:103], v[160:163], v[194:197], v[100:103]
	v_mfma_i32_16x16x64_i8 v[96:99], v[168:171], v[194:197], v[96:99]
	v_mfma_i32_16x16x64_i8 v[84:87], v[160:163], v[202:205], v[84:87]
	v_mfma_i32_16x16x64_i8 v[80:83], v[168:171], v[202:205], v[80:83]
	v_mfma_i32_16x16x64_i8 v[68:71], v[160:163], v[210:213], v[68:71]
	v_mfma_i32_16x16x64_i8 v[64:67], v[168:171], v[210:213], v[64:67]
	v_mfma_i32_16x16x64_i8 v[116:119], v[164:167], v[190:193], v[116:119]
	v_mfma_i32_16x16x64_i8 v[112:115], v[172:175], v[190:193], v[112:115]
	v_mfma_i32_16x16x64_i8 v[100:103], v[164:167], v[198:201], v[100:103]
	v_mfma_i32_16x16x64_i8 v[96:99], v[172:175], v[198:201], v[96:99]
	v_mfma_i32_16x16x64_i8 v[84:87], v[164:167], v[206:209], v[84:87]
	v_mfma_i32_16x16x64_i8 v[80:83], v[172:175], v[206:209], v[80:83]
	v_mfma_i32_16x16x64_i8 v[68:71], v[164:167], v[214:217], v[68:71]
	v_mfma_i32_16x16x64_i8 v[64:67], v[172:175], v[214:217], v[64:67]
	s_barrier
	ds_read_b128 v[186:189], v182 offset:49152
	ds_read_b128 v[190:193], v182 offset:50176
	ds_read_b128 v[194:197], v182 offset:51200
	ds_read_b128 v[198:201], v182 offset:52224
	ds_read_b128 v[202:205], v182 offset:53248
	ds_read_b128 v[206:209], v182 offset:54272
	ds_read_b128 v[210:213], v182 offset:55296
	ds_read_b128 v[214:217], v182 offset:56320
	s_add_i32 s36, s59, s42
	v_lshl_add_u64 v[218:219], v[218:219], 0, s[16:17]
	s_mov_b32 m0, s36
	s_nop 0
	global_load_lds_dwordx4 v[218:219], off
	s_add_i32 m0, s36, 0x2000
	s_add_u32 s34, s34, 0x80080
	v_lshl_add_u64 v[218:219], v[220:221], 0, s[16:17]
	s_addc_u32 s35, s35, 0
	s_add_i32 s36, s60, s42
	global_load_lds_dwordx4 v[218:219], off
	v_lshl_add_u64 v[218:219], s[34:35], 0, v[130:131]
	s_mov_b32 m0, s36
	s_nop 0
	global_load_lds_dwordx4 v[218:219], off
	v_lshl_add_u64 v[218:219], s[34:35], 0, v[134:135]
	s_add_i32 m0, s36, 0x2000
	s_nop 0
	global_load_lds_dwordx4 v[218:219], off
	v_lshl_add_u64 v[218:219], v[222:223], 0, s[16:17]
	s_mov_b32 m0, s48
	s_nop 0
	global_load_lds_dwordx4 v[218:219], off
	v_lshl_add_u64 v[218:219], v[224:225], 0, s[16:17]
	s_mov_b32 m0, s49
	s_nop 0
	global_load_lds_dwordx4 v[218:219], off
	s_waitcnt vmcnt(8) lgkmcnt(0)
	s_barrier
	v_mfma_i32_16x16x64_i8 v[60:63], v[144:147], v[186:189], v[60:63]
	v_mfma_i32_16x16x64_i8 v[56:59], v[152:155], v[186:189], v[56:59]
	v_mfma_i32_16x16x64_i8 v[44:47], v[144:147], v[194:197], v[44:47]
	v_mfma_i32_16x16x64_i8 v[40:43], v[152:155], v[194:197], v[40:43]
	v_mfma_i32_16x16x64_i8 v[28:31], v[144:147], v[202:205], v[28:31]
	v_mfma_i32_16x16x64_i8 v[24:27], v[152:155], v[202:205], v[24:27]
	v_mfma_i32_16x16x64_i8 v[12:15], v[144:147], v[210:213], v[12:15]
	v_mfma_i32_16x16x64_i8 v[8:11], v[152:155], v[210:213], v[8:11]
	v_mfma_i32_16x16x64_i8 v[60:63], v[148:151], v[190:193], v[60:63]
	v_mfma_i32_16x16x64_i8 v[56:59], v[156:159], v[190:193], v[56:59]
	v_mfma_i32_16x16x64_i8 v[44:47], v[148:151], v[198:201], v[44:47]
	v_mfma_i32_16x16x64_i8 v[40:43], v[156:159], v[198:201], v[40:43]
	v_mfma_i32_16x16x64_i8 v[28:31], v[148:151], v[206:209], v[28:31]
	v_mfma_i32_16x16x64_i8 v[24:27], v[156:159], v[206:209], v[24:27]
	v_mfma_i32_16x16x64_i8 v[12:15], v[148:151], v[214:217], v[12:15]
	v_mfma_i32_16x16x64_i8 v[8:11], v[156:159], v[214:217], v[8:11]
	v_mfma_i32_16x16x64_i8 v[52:55], v[160:163], v[186:189], v[52:55]
	v_mfma_i32_16x16x64_i8 v[48:51], v[168:171], v[186:189], v[48:51]
	v_mfma_i32_16x16x64_i8 v[36:39], v[160:163], v[194:197], v[36:39]
	v_mfma_i32_16x16x64_i8 v[32:35], v[168:171], v[194:197], v[32:35]
	v_mfma_i32_16x16x64_i8 v[20:23], v[160:163], v[202:205], v[20:23]
	v_mfma_i32_16x16x64_i8 v[16:19], v[168:171], v[202:205], v[16:19]
	v_mfma_i32_16x16x64_i8 v[4:7], v[160:163], v[210:213], v[4:7]
	v_mfma_i32_16x16x64_i8 v[0:3], v[168:171], v[210:213], v[0:3]
	v_mfma_i32_16x16x64_i8 v[52:55], v[164:167], v[190:193], v[52:55]
	v_mfma_i32_16x16x64_i8 v[48:51], v[172:175], v[190:193], v[48:51]
	v_mfma_i32_16x16x64_i8 v[36:39], v[164:167], v[198:201], v[36:39]
	v_mfma_i32_16x16x64_i8 v[32:35], v[172:175], v[198:201], v[32:35]
	v_mfma_i32_16x16x64_i8 v[20:23], v[164:167], v[206:209], v[20:23]
	v_mfma_i32_16x16x64_i8 v[16:19], v[172:175], v[206:209], v[16:19]
	v_mfma_i32_16x16x64_i8 v[4:7], v[164:167], v[214:217], v[4:7]
	v_mfma_i32_16x16x64_i8 v[0:3], v[172:175], v[214:217], v[0:3]
	s_barrier
	s_add_i32 s58, s58, 2
	s_add_u32 s33, s33, 0x100
	s_addc_u32 s57, s57, 0
	s_add_u32 s30, s30, 0x100
	s_addc_u32 s31, s31, 0
	s_cmp_gt_u32 s58, 29
	s_cbranch_scc0 .LBB0_1356
	s_setprio 0
	s_and_b64 vcc, exec, s[18:19]
	s_cbranch_vccz .LBB0_1359
	s_barrier

.Lsp_skip9:
.LBB0_1841:
	ds_read_b128 v[186:189], v183
	ds_read_b128 v[190:193], v183 offset:1024
	ds_read_b128 v[194:197], v183 offset:2048
	ds_read_b128 v[198:201], v183 offset:3072
	ds_read_b128 v[202:205], v183 offset:4096
	ds_read_b128 v[206:209], v183 offset:5120
	ds_read_b128 v[210:213], v183 offset:6144
	ds_read_b128 v[214:217], v183 offset:7168
	v_add_u32_e32 v140, s47, v181
	v_add_u32_e32 v174, s48, v181
	ds_read_b128 v[124:127], v140
	ds_read_b128 v[132:135], v140 offset:1024
	ds_read_b128 v[136:139], v140 offset:2048
	ds_read_b128 v[140:143], v140 offset:3072
	ds_read_b128 v[162:165], v174
	ds_read_b128 v[166:169], v174 offset:1024
	ds_read_b128 v[170:173], v174 offset:2048
	ds_read_b128 v[174:177], v174 offset:3072
	s_add_u32 s30, s28, 0xffe00080
	s_addc_u32 s31, s29, -1
	s_cmpk_eq_i32 s53, 0x7c
	s_cselect_b32 s35, s19, s31
	s_cselect_b32 s34, s25, s30
	s_cselect_b32 s31, s17, s52
	s_cselect_b32 s30, s50, s51
	v_lshl_add_u64 v[178:179], s[28:29], 0, v[156:157]
	s_add_i32 m0, s27, 0xc000
	s_nop 0
	global_load_lds_dwordx4 v[178:179], off
	v_lshl_add_u64 v[178:179], s[28:29], 0, v[154:155]
	s_add_i32 m0, s27, 0xe000
	s_nop 0
	global_load_lds_dwordx4 v[178:179], off
	s_waitcnt vmcnt(8) lgkmcnt(0)
	s_barrier
	v_mfma_i32_16x16x64_i8 v[116:119], v[124:127], v[186:189], v[116:119]
	v_mfma_i32_16x16x64_i8 v[104:107], v[136:139], v[186:189], v[104:107]
	v_mfma_i32_16x16x64_i8 v[112:115], v[124:127], v[194:197], v[112:115]
	v_mfma_i32_16x16x64_i8 v[108:111], v[136:139], v[194:197], v[108:111]
	v_mfma_i32_16x16x64_i8 v[92:95], v[124:127], v[202:205], v[92:95]
	v_mfma_i32_16x16x64_i8 v[88:91], v[136:139], v[202:205], v[88:91]
	v_mfma_i32_16x16x64_i8 v[76:79], v[124:127], v[210:213], v[76:79]
	v_mfma_i32_16x16x64_i8 v[72:75], v[136:139], v[210:213], v[72:75]
	v_mfma_i32_16x16x64_i8 v[116:119], v[132:135], v[190:193], v[116:119]
	v_mfma_i32_16x16x64_i8 v[104:107], v[140:143], v[190:193], v[104:107]
	v_mfma_i32_16x16x64_i8 v[112:115], v[132:135], v[198:201], v[112:115]
	v_mfma_i32_16x16x64_i8 v[108:111], v[140:143], v[198:201], v[108:111]
	v_mfma_i32_16x16x64_i8 v[92:95], v[132:135], v[206:209], v[92:95]
	v_mfma_i32_16x16x64_i8 v[88:91], v[140:143], v[206:209], v[88:91]
	v_mfma_i32_16x16x64_i8 v[76:79], v[132:135], v[214:217], v[76:79]
	v_mfma_i32_16x16x64_i8 v[72:75], v[140:143], v[214:217], v[72:75]
	v_mfma_i32_16x16x64_i8 v[128:131], v[162:165], v[186:189], v[128:131]
	v_mfma_i32_16x16x64_i8 v[120:123], v[170:173], v[186:189], v[120:123]
	v_mfma_i32_16x16x64_i8 v[100:103], v[162:165], v[194:197], v[100:103]
	v_mfma_i32_16x16x64_i8 v[96:99], v[170:173], v[194:197], v[96:99]
	v_mfma_i32_16x16x64_i8 v[84:87], v[162:165], v[202:205], v[84:87]
	v_mfma_i32_16x16x64_i8 v[80:83], v[170:173], v[202:205], v[80:83]
	v_mfma_i32_16x16x64_i8 v[68:71], v[162:165], v[210:213], v[68:71]
	v_mfma_i32_16x16x64_i8 v[64:67], v[170:173], v[210:213], v[64:67]
	v_mfma_i32_16x16x64_i8 v[128:131], v[166:169], v[190:193], v[128:131]
	v_mfma_i32_16x16x64_i8 v[120:123], v[174:177], v[190:193], v[120:123]
	v_mfma_i32_16x16x64_i8 v[100:103], v[166:169], v[198:201], v[100:103]
	v_mfma_i32_16x16x64_i8 v[96:99], v[174:177], v[198:201], v[96:99]
	v_mfma_i32_16x16x64_i8 v[84:87], v[166:169], v[206:209], v[84:87]
	v_mfma_i32_16x16x64_i8 v[80:83], v[174:177], v[206:209], v[80:83]
	v_mfma_i32_16x16x64_i8 v[68:71], v[166:169], v[214:217], v[68:71]
	v_mfma_i32_16x16x64_i8 v[64:67], v[174:177], v[214:217], v[64:67]
	s_barrier
	ds_read_b128 v[186:189], v183 offset:16384
	ds_read_b128 v[190:193], v183 offset:17408
	ds_read_b128 v[194:197], v183 offset:18432
	ds_read_b128 v[198:201], v183 offset:19456
	ds_read_b128 v[202:205], v183 offset:20480
	ds_read_b128 v[206:209], v183 offset:21504
	ds_read_b128 v[210:213], v183 offset:22528
	ds_read_b128 v[214:217], v183 offset:23552
	s_add_i32 s54, s47, s38
	v_lshl_add_u64 v[178:179], s[30:31], 0, v[146:147]
	s_mov_b32 m0, s54
	s_nop 0
	global_load_lds_dwordx4 v[178:179], off
	s_add_i32 m0, s54, 0x2000
	s_add_u32 s54, s30, 0x200000
	v_lshl_add_u64 v[218:219], s[30:31], 0, v[150:151]
	s_addc_u32 s55, s31, 0
	s_add_i32 s56, s48, s38
	global_load_lds_dwordx4 v[218:219], off
	v_lshl_add_u64 v[220:221], s[54:55], 0, v[146:147]
	s_mov_b32 m0, s56
	v_lshl_add_u64 v[222:223], s[34:35], 0, v[148:149]
	global_load_lds_dwordx4 v[220:221], off
	v_lshl_add_u64 v[220:221], s[54:55], 0, v[150:151]
	s_add_i32 m0, s56, 0x2000
	s_nop 0
	global_load_lds_dwordx4 v[220:221], off
	v_lshl_add_u64 v[220:221], s[34:35], 0, v[144:145]
	s_mov_b32 m0, s27
	s_nop 0
	global_load_lds_dwordx4 v[220:221], off
	s_mov_b32 m0, s39
	s_nop 0
	global_load_lds_dwordx4 v[222:223], off
	s_waitcnt vmcnt(8) lgkmcnt(0)
	s_barrier
	v_mfma_i32_16x16x64_i8 v[60:63], v[124:127], v[186:189], v[60:63]
	v_mfma_i32_16x16x64_i8 v[56:59], v[136:139], v[186:189], v[56:59]
	v_mfma_i32_16x16x64_i8 v[44:47], v[124:127], v[194:197], v[44:47]
	v_mfma_i32_16x16x64_i8 v[40:43], v[136:139], v[194:197], v[40:43]
	v_mfma_i32_16x16x64_i8 v[28:31], v[124:127], v[202:205], v[28:31]
	v_mfma_i32_16x16x64_i8 v[24:27], v[136:139], v[202:205], v[24:27]
	v_mfma_i32_16x16x64_i8 v[12:15], v[124:127], v[210:213], v[12:15]
	v_mfma_i32_16x16x64_i8 v[8:11], v[136:139], v[210:213], v[8:11]
	v_mfma_i32_16x16x64_i8 v[60:63], v[132:135], v[190:193], v[60:63]
	v_mfma_i32_16x16x64_i8 v[56:59], v[140:143], v[190:193], v[56:59]
	v_mfma_i32_16x16x64_i8 v[44:47], v[132:135], v[198:201], v[44:47]
	v_mfma_i32_16x16x64_i8 v[40:43], v[140:143], v[198:201], v[40:43]
	v_mfma_i32_16x16x64_i8 v[28:31], v[132:135], v[206:209], v[28:31]
	v_mfma_i32_16x16x64_i8 v[24:27], v[140:143], v[206:209], v[24:27]
	v_mfma_i32_16x16x64_i8 v[12:15], v[132:135], v[214:217], v[12:15]
	v_mfma_i32_16x16x64_i8 v[8:11], v[140:143], v[214:217], v[8:11]
	v_mfma_i32_16x16x64_i8 v[52:55], v[162:165], v[186:189], v[52:55]
	v_mfma_i32_16x16x64_i8 v[48:51], v[170:173], v[186:189], v[48:51]
	v_mfma_i32_16x16x64_i8 v[36:39], v[162:165], v[194:197], v[36:39]
	v_mfma_i32_16x16x64_i8 v[32:35], v[170:173], v[194:197], v[32:35]
	v_mfma_i32_16x16x64_i8 v[20:23], v[162:165], v[202:205], v[20:23]
	v_mfma_i32_16x16x64_i8 v[16:19], v[170:173], v[202:205], v[16:19]
	v_mfma_i32_16x16x64_i8 v[4:7], v[162:165], v[210:213], v[4:7]
	v_mfma_i32_16x16x64_i8 v[0:3], v[170:173], v[210:213], v[0:3]
	v_mfma_i32_16x16x64_i8 v[52:55], v[166:169], v[190:193], v[52:55]
	v_mfma_i32_16x16x64_i8 v[48:51], v[174:177], v[190:193], v[48:51]
	v_mfma_i32_16x16x64_i8 v[36:39], v[166:169], v[198:201], v[36:39]
	v_mfma_i32_16x16x64_i8 v[32:35], v[174:177], v[198:201], v[32:35]
	v_mfma_i32_16x16x64_i8 v[20:23], v[166:169], v[206:209], v[20:23]
	v_mfma_i32_16x16x64_i8 v[16:19], v[174:177], v[206:209], v[16:19]
	v_mfma_i32_16x16x64_i8 v[4:7], v[166:169], v[214:217], v[4:7]
	v_mfma_i32_16x16x64_i8 v[0:3], v[174:177], v[214:217], v[0:3]
	s_barrier
	ds_read_b128 v[186:189], v183 offset:32768
	ds_read_b128 v[190:193], v183 offset:33792
	ds_read_b128 v[194:197], v183 offset:34816
	ds_read_b128 v[198:201], v183 offset:35840
	ds_read_b128 v[202:205], v183 offset:36864
	ds_read_b128 v[206:209], v183 offset:37888
	ds_read_b128 v[210:213], v183 offset:38912
	ds_read_b128 v[214:217], v183 offset:39936
	s_add_i32 s54, 0, 0x18000
	s_add_i32 s55, 0, 0x1c000
	v_add_u32_e32 v140, s54, v181
	v_add_u32_e32 v174, s55, v181
	ds_read_b128 v[124:127], v140
	ds_read_b128 v[132:135], v140 offset:1024
	ds_read_b128 v[136:139], v140 offset:2048
	ds_read_b128 v[140:143], v140 offset:3072
	ds_read_b128 v[162:165], v174
	ds_read_b128 v[166:169], v174 offset:1024
	ds_read_b128 v[170:173], v174 offset:2048
	ds_read_b128 v[174:177], v174 offset:3072
	s_add_u32 s34, s34, 0x200000
	s_addc_u32 s35, s35, 0
	s_mov_b32 m0, s40
	v_lshl_add_u64 v[224:225], s[34:35], 0, v[144:145]
	global_load_lds_dwordx4 v[224:225], off
	v_lshl_add_u64 v[224:225], s[34:35], 0, v[148:149]
	s_mov_b32 m0, s41
	s_nop 0
	global_load_lds_dwordx4 v[224:225], off
	s_waitcnt vmcnt(8) lgkmcnt(0)
	s_barrier
	v_mfma_i32_16x16x64_i8 v[116:119], v[124:127], v[186:189], v[116:119]
	v_mfma_i32_16x16x64_i8 v[104:107], v[136:139], v[186:189], v[104:107]
	v_mfma_i32_16x16x64_i8 v[112:115], v[124:127], v[194:197], v[112:115]
	v_mfma_i32_16x16x64_i8 v[108:111], v[136:139], v[194:197], v[108:111]
	v_mfma_i32_16x16x64_i8 v[92:95], v[124:127], v[202:205], v[92:95]
	v_mfma_i32_16x16x64_i8 v[88:91], v[136:139], v[202:205], v[88:91]
	v_mfma_i32_16x16x64_i8 v[76:79], v[124:127], v[210:213], v[76:79]
	v_mfma_i32_16x16x64_i8 v[72:75], v[136:139], v[210:213], v[72:75]
	v_mfma_i32_16x16x64_i8 v[116:119], v[132:135], v[190:193], v[116:119]
	v_mfma_i32_16x16x64_i8 v[104:107], v[140:143], v[190:193], v[104:107]
	v_mfma_i32_16x16x64_i8 v[112:115], v[132:135], v[198:201], v[112:115]
	v_mfma_i32_16x16x64_i8 v[108:111], v[140:143], v[198:201], v[108:111]
	v_mfma_i32_16x16x64_i8 v[92:95], v[132:135], v[206:209], v[92:95]
	v_mfma_i32_16x16x64_i8 v[88:91], v[140:143], v[206:209], v[88:91]
	v_mfma_i32_16x16x64_i8 v[76:79], v[132:135], v[214:217], v[76:79]
	v_mfma_i32_16x16x64_i8 v[72:75], v[140:143], v[214:217], v[72:75]
	v_mfma_i32_16x16x64_i8 v[128:131], v[162:165], v[186:189], v[128:131]
	v_mfma_i32_16x16x64_i8 v[120:123], v[170:173], v[186:189], v[120:123]
	v_mfma_i32_16x16x64_i8 v[100:103], v[162:165], v[194:197], v[100:103]
	v_mfma_i32_16x16x64_i8 v[96:99], v[170:173], v[194:197], v[96:99]
	v_mfma_i32_16x16x64_i8 v[84:87], v[162:165], v[202:205], v[84:87]
	v_mfma_i32_16x16x64_i8 v[80:83], v[170:173], v[202:205], v[80:83]
	v_mfma_i32_16x16x64_i8 v[68:71], v[162:165], v[210:213], v[68:71]
	v_mfma_i32_16x16x64_i8 v[64:67], v[170:173], v[210:213], v[64:67]
	v_mfma_i32_16x16x64_i8 v[128:131], v[166:169], v[190:193], v[128:131]
	v_mfma_i32_16x16x64_i8 v[120:123], v[174:177], v[190:193], v[120:123]
	v_mfma_i32_16x16x64_i8 v[100:103], v[166:169], v[198:201], v[100:103]
	v_mfma_i32_16x16x64_i8 v[96:99], v[174:177], v[198:201], v[96:99]
	v_mfma_i32_16x16x64_i8 v[84:87], v[166:169], v[206:209], v[84:87]
	v_mfma_i32_16x16x64_i8 v[80:83], v[174:177], v[206:209], v[80:83]
	v_mfma_i32_16x16x64_i8 v[68:71], v[166:169], v[214:217], v[68:71]
	v_mfma_i32_16x16x64_i8 v[64:67], v[174:177], v[214:217], v[64:67]
	s_barrier
	ds_read_b128 v[186:189], v183 offset:49152
	ds_read_b128 v[190:193], v183 offset:50176
	ds_read_b128 v[194:197], v183 offset:51200
	ds_read_b128 v[198:201], v183 offset:52224
	ds_read_b128 v[202:205], v183 offset:53248
	ds_read_b128 v[206:209], v183 offset:54272
	ds_read_b128 v[210:213], v183 offset:55296
	ds_read_b128 v[214:217], v183 offset:56320
	s_add_i32 s34, s54, s38
	v_lshl_add_u64 v[178:179], v[178:179], 0, s[10:11]
	s_mov_b32 m0, s34
	s_nop 0
	global_load_lds_dwordx4 v[178:179], off
	s_add_i32 m0, s34, 0x2000
	s_add_u32 s30, s30, 0x200080
	v_lshl_add_u64 v[178:179], v[218:219], 0, s[10:11]
	s_addc_u32 s31, s31, 0
	s_add_i32 s34, s55, s38
	global_load_lds_dwordx4 v[178:179], off
	v_lshl_add_u64 v[178:179], s[30:31], 0, v[146:147]
	s_mov_b32 m0, s34
	s_nop 0
	global_load_lds_dwordx4 v[178:179], off
	v_lshl_add_u64 v[178:179], s[30:31], 0, v[150:151]
	s_add_i32 m0, s34, 0x2000
	s_nop 0
	global_load_lds_dwordx4 v[178:179], off
	v_lshl_add_u64 v[178:179], v[220:221], 0, s[10:11]
	s_mov_b32 m0, s43
	s_nop 0
	global_load_lds_dwordx4 v[178:179], off
	v_lshl_add_u64 v[178:179], v[222:223], 0, s[10:11]
	s_mov_b32 m0, s44
	s_nop 0
	global_load_lds_dwordx4 v[178:179], off
	s_waitcnt vmcnt(8) lgkmcnt(0)
	s_barrier
	v_mfma_i32_16x16x64_i8 v[60:63], v[124:127], v[186:189], v[60:63]
	v_mfma_i32_16x16x64_i8 v[56:59], v[136:139], v[186:189], v[56:59]
	v_mfma_i32_16x16x64_i8 v[44:47], v[124:127], v[194:197], v[44:47]
	v_mfma_i32_16x16x64_i8 v[40:43], v[136:139], v[194:197], v[40:43]
	v_mfma_i32_16x16x64_i8 v[28:31], v[124:127], v[202:205], v[28:31]
	v_mfma_i32_16x16x64_i8 v[24:27], v[136:139], v[202:205], v[24:27]
	v_mfma_i32_16x16x64_i8 v[12:15], v[124:127], v[210:213], v[12:15]
	v_mfma_i32_16x16x64_i8 v[8:11], v[136:139], v[210:213], v[8:11]
	v_mfma_i32_16x16x64_i8 v[60:63], v[132:135], v[190:193], v[60:63]
	v_mfma_i32_16x16x64_i8 v[56:59], v[140:143], v[190:193], v[56:59]
	v_mfma_i32_16x16x64_i8 v[44:47], v[132:135], v[198:201], v[44:47]
	v_mfma_i32_16x16x64_i8 v[40:43], v[140:143], v[198:201], v[40:43]
	v_mfma_i32_16x16x64_i8 v[28:31], v[132:135], v[206:209], v[28:31]
	v_mfma_i32_16x16x64_i8 v[24:27], v[140:143], v[206:209], v[24:27]
	v_mfma_i32_16x16x64_i8 v[12:15], v[132:135], v[214:217], v[12:15]
	v_mfma_i32_16x16x64_i8 v[8:11], v[140:143], v[214:217], v[8:11]
	v_mfma_i32_16x16x64_i8 v[52:55], v[162:165], v[186:189], v[52:55]
	v_mfma_i32_16x16x64_i8 v[48:51], v[170:173], v[186:189], v[48:51]
	v_mfma_i32_16x16x64_i8 v[36:39], v[162:165], v[194:197], v[36:39]
	v_mfma_i32_16x16x64_i8 v[32:35], v[170:173], v[194:197], v[32:35]
	v_mfma_i32_16x16x64_i8 v[20:23], v[162:165], v[202:205], v[20:23]
	v_mfma_i32_16x16x64_i8 v[16:19], v[170:173], v[202:205], v[16:19]
	v_mfma_i32_16x16x64_i8 v[4:7], v[162:165], v[210:213], v[4:7]
	v_mfma_i32_16x16x64_i8 v[0:3], v[170:173], v[210:213], v[0:3]
	v_mfma_i32_16x16x64_i8 v[52:55], v[166:169], v[190:193], v[52:55]
	v_mfma_i32_16x16x64_i8 v[48:51], v[174:177], v[190:193], v[48:51]
	v_mfma_i32_16x16x64_i8 v[36:39], v[166:169], v[198:201], v[36:39]
	v_mfma_i32_16x16x64_i8 v[32:35], v[174:177], v[198:201], v[32:35]
	v_mfma_i32_16x16x64_i8 v[20:23], v[166:169], v[206:209], v[20:23]
	v_mfma_i32_16x16x64_i8 v[16:19], v[174:177], v[206:209], v[16:19]
	v_mfma_i32_16x16x64_i8 v[4:7], v[166:169], v[214:217], v[4:7]
	v_mfma_i32_16x16x64_i8 v[0:3], v[174:177], v[214:217], v[0:3]
	s_barrier
	s_add_i32 s53, s53, 2
	s_add_u32 s51, s51, 0x100
	s_addc_u32 s52, s52, 0
	s_add_u32 s28, s28, 0x100
	s_addc_u32 s29, s29, 0
	s_cmpk_gt_u32 s53, 0x7d
	s_cbranch_scc0 .LBB0_1841
	s_setprio 0
	s_and_b64 vcc, exec, s[12:13]
	s_cbranch_vccz .LBB0_1844
	s_barrier
